# v19 plus LayerNorm wave reductions via DPP row_ror/quad_perm and v_permlane16/32_swap instead of ds_bpermute (strategy: DPP for intra-wave movement)
# speedup vs baseline: 1.0071x; 1.0028x over previous
; DI float4 ld_nt4(const float* p) { const f32x4 v = __builtin_nontemporal_load((const f32x4*)p); return make_float4(v[0], v[1], v[2], v[3]); }
; DI float4 h4lo(const u32x4 v) { return make_float4(hlo(v[0]), hhi(v[0]), hlo(v[1]), hhi(v[1])); }
; DI float4 h4hi(const u32x4 v) { return make_float4(hlo(v[2]), hhi(v[2]), hlo(v[3]), hhi(v[3])); }
; DI float4 b4lo(const uint4 v) { return make_float4(bflo(v.x), bfhi(v.x), bflo(v.y), bfhi(v.y)); }
; DI float4 b4hi(const uint4 v) { return make_float4(bflo(v.z), bfhi(v.z), bflo(v.w), bfhi(v.w)); }
; template <bool IN16>
; DI LnRow ln_load(const float* hin, const unsigned short* hin16, const bf16_t* yu, const LnVec& gate, int c0) {
;   LnRow r;
;   const uint4 ya = *(const uint4*)(yu + c0), yb = *(const uint4*)(yu + 512 + c0);
;   float4 h0, h1, h2, h3;
;   if (IN16) {
;     const u32x4 ha = __builtin_nontemporal_load((const u32x4*)(hin16 + c0)), hb = __builtin_nontemporal_load((const u32x4*)(hin16 + 512 + c0));
;     h0 = h4lo(ha); h1 = h4hi(ha); h2 = h4lo(hb); h3 = h4hi(hb);
;   } else {
;     h0 = ld_nt4(hin + c0); h1 = ld_nt4(hin + c0 + 4); h2 = ld_nt4(hin + 512 + c0); h3 = ld_nt4(hin + 512 + c0 + 4);
;   }
;   r.z0 = zmix(h0, gate.a, b4lo(ya)); r.z1 = zmix(h1, gate.b, b4hi(ya)); r.z2 = zmix(h2, gate.c, b4lo(yb)); r.z3 = zmix(h3, gate.d, b4hi(yb));
;   return r;
; }
; template <bool IN16, bool OUT16>
; DI void ln_body(const Params& p, int layer) {
;     ...
;     const bool isctx = row >= TL;
;     const float* hin = isctx ? (p.ctx + (size_t)(row - TL) * 1024) : (p.x + (size_t)row * 1024);
;     const unsigned short* hin16 = in16 ? (p.h16 + (size_t)row * 1024) : nullptr;
;     float* hout = p.out + (size_t)(isctx ? 0 : row) * 1024;
;     unsigned short* hout16 = out16 ? (p.h16 + (size_t)row * 1024) : nullptr;
;     bf16_t* yu = p.u + (size_t)row * 1024;
;     const unsigned short* hb = hin16 ? hin16 + 1024 : nullptr; const unsigned short* hc_ = hin16 ? hin16 + 2048 : nullptr; const unsigned short* hd = hin16 ? hin16 + 3072 : nullptr;
;     const LnRow ra = ln_load<IN16>(hin, hin16, yu, gate, c0), rb = ln_load<IN16>(hin + 1024, hb, yu + 1024, gate, c0), rc = ln_load<IN16>(hin + 2048, hc_, yu + 2048, gate, c0), rd = ln_load<IN16>(hin + 3072, hd, yu + 3072, gate, c0);
.LBB0_127:
	s_ashr_i32 s7, s6, 31
	s_lshl_b64 s[12:13], s[6:7], 10
	s_cmp_lt_i32 s6, 0x10000
	s_cselect_b32 s13, s13, 0
	s_cselect_b32 s12, s12, 0
	s_lshl_b64 s[14:15], s[6:7], 11
	s_add_u32 s16, s40, s14
	s_addc_u32 s17, s41, s15
	v_lshlrev_b32_e32 v0, 1, v74
	global_load_dwordx4 v[42:45], v0, s[16:17] nt
	global_load_dwordx4 v[48:51], v0, s[16:17] offset:1024 nt
	s_lshl_b64 s[12:13], s[12:13], 2
	v_readlane_b32 s4, v255, 30
	v_readlane_b32 s5, v255, 31
	s_add_u32 s12, s4, s12
	s_addc_u32 s13, s5, s13
	s_add_u32 s14, s36, s14
	s_addc_u32 s15, s37, s15
	global_load_dwordx4 v[52:55], v0, s[14:15]
	global_load_dwordx4 v[38:41], v0, s[14:15] offset:1024
	global_load_dwordx4 v[56:59], v0, s[16:17] offset:2048 nt
	global_load_dwordx4 v[70:73], v0, s[16:17] offset:3072 nt
	global_load_dwordx4 v[86:89], v0, s[14:15] offset:2048
	v_lshl_add_u64 v[34:35], s[16:17], 0, v[0:1]
	v_add_co_u32_e32 v108, vcc, s91, v34
	v_lshl_add_u64 v[98:99], s[14:15], 0, v[0:1]
	s_nop 0
	v_addc_co_u32_e32 v109, vcc, 0, v35, vcc
	global_load_dwordx4 v[34:37], v[108:109], off nt
	global_load_dwordx4 v[90:93], v[108:109], off offset:1024 nt
	global_load_dwordx4 v[94:97], v0, s[14:15] offset:3072
	s_waitcnt vmcnt(12)
	v_mov_b32_e32 v46, v22
	v_mov_b32_e32 v47, v24
	v_add_co_u32_e32 v110, vcc, s91, v98
	v_mov_b32_e32 v62, v23
	s_nop 0
	v_addc_co_u32_e32 v111, vcc, 0, v99, vcc
	global_load_dwordx4 v[98:101], v[110:111], off
	s_waitcnt vmcnt(12)
	v_mov_b32_e32 v68, v27
	s_waitcnt vmcnt(11)
	v_mov_b32_e32 v106, v30
	v_mov_b32_e32 v64, v25
	v_mov_b32_e32 v67, v143
	v_mov_b32_e32 v102, v29
	v_mov_b32_e32 v105, v143
	v_mov_b32_e32 v60, v26
	v_mov_b32_e32 v61, v28
	global_load_dwordx4 v[180:183], v[110:111], off offset:2048
	v_mov_b32_e32 v150, v27
	v_mov_b32_e32 v148, v29
	s_mov_b32 s14, 0x3727c5ac
	global_load_dwordx4 v[156:159], v[108:109], off offset:3072 nt
	s_waitcnt vmcnt(12)
	v_cvt_f32_f16_e32 v113, v45
	v_cvt_f32_f16_e32 v112, v44
	v_cvt_f32_f16_sdwa v63, v44 dst_sel:DWORD dst_unused:UNUSED_PAD src0_sel:WORD_1
	s_waitcnt vmcnt(11)
	v_cvt_f32_f16_sdwa v69, v48 dst_sel:DWORD dst_unused:UNUSED_PAD src0_sel:WORD_1
	v_cvt_f32_f16_sdwa v103, v49 dst_sel:DWORD dst_unused:UNUSED_PAD src0_sel:WORD_1
	v_cvt_f32_f16_e32 v49, v49
	v_cvt_f32_f16_e32 v48, v48
	v_cvt_f32_f16_e32 v107, v50
	v_cvt_f32_f16_e32 v119, v51
	s_waitcnt vmcnt(10)
	v_and_b32_e32 v142, 0xffff0000, v54
	v_lshlrev_b32_e32 v115, 16, v55
	v_lshlrev_b32_e32 v114, 16, v54
	v_and_b32_e32 v66, 0xffff0000, v55
	v_pk_mul_f32 v[54:55], v[112:113], s[74:75] op_sel_hi:[1,0]
	s_waitcnt vmcnt(9)
	v_lshlrev_b32_e32 v117, 16, v39
	v_and_b32_e32 v104, 0xffff0000, v39
	v_and_b32_e32 v39, 0xffff0000, v40
	v_cvt_f32_f16_sdwa v65, v45 dst_sel:DWORD dst_unused:UNUSED_PAD src0_sel:WORD_1
	v_mul_f32_e32 v0, 0x3fd744fd, v63
	v_pk_mul_f32 v[120:121], v[48:49], s[74:75] op_sel_hi:[1,0]
	v_lshlrev_b32_e32 v49, 16, v41
	v_and_b32_e32 v41, 0xffff0000, v41
	v_pk_fma_f32 v[152:153], v[46:47], v[114:115], v[54:55]
	v_mul_f32_e32 v54, v31, v39
	s_waitcnt vmcnt(8)
	v_cvt_f32_f16_sdwa v39, v58 dst_sel:DWORD dst_unused:UNUSED_PAD src0_sel:WORD_1
	v_pk_fma_f32 v[136:137], v[62:63], v[142:143], v[0:1] op_sel_hi:[1,1,0]
	v_mul_f32_e32 v176, v33, v41
	v_cvt_f32_f16_sdwa v41, v59 dst_sel:DWORD dst_unused:UNUSED_PAD src0_sel:WORD_1
	v_cvt_f32_f16_e32 v63, v59
	v_cvt_f32_f16_e32 v62, v58
	v_cvt_f32_f16_sdwa v123, v51 dst_sel:DWORD dst_unused:UNUSED_PAD src0_sel:WORD_1
	v_mul_f32_e32 v118, 0x3fd744fd, v69
	v_and_b32_e32 v142, 0xffff0000, v38
	v_mul_f32_e32 v124, 0x3fd744fd, v107
	v_pk_fma_f32 v[126:127], v[68:69], v[142:143], v[118:119] op_sel_hi:[1,1,0]
	v_lshlrev_b32_e32 v142, 16, v40
	v_mul_f32_e32 v112, 0x3fd744fd, v65
	v_lshlrev_b32_e32 v116, 16, v38
	v_pk_fma_f32 v[124:125], v[106:107], v[142:143], v[124:125] op_sel_hi:[1,1,0]
	s_waitcnt vmcnt(6)
	v_and_b32_e32 v142, 0xffff0000, v88
	v_mov_b32_e32 v38, v23
	v_mul_f32_e32 v0, 0x3fd744fd, v39
	v_lshlrev_b32_e32 v44, 16, v53
	v_and_b32_e32 v45, 0xffff0000, v53
	v_mul_f32_e32 v122, 0x3fd744fd, v103
	v_pk_fma_f32 v[154:155], v[64:65], v[66:67], v[112:113] op_sel_hi:[1,1,0]
	v_mul_f32_e32 v178, v32, v49
	v_cvt_f32_f16_e32 v107, v72
	v_cvt_f32_f16_sdwa v49, v72 dst_sel:DWORD dst_unused:UNUSED_PAD src0_sel:WORD_1
	v_cvt_f32_f16_e32 v53, v73
	v_cvt_f32_f16_sdwa v55, v73 dst_sel:DWORD dst_unused:UNUSED_PAD src0_sel:WORD_1
	global_load_dwordx4 v[112:115], v[110:111], off offset:1024
	v_lshlrev_b32_e32 v69, 16, v89
	v_lshlrev_b32_e32 v68, 16, v88
	v_and_b32_e32 v72, 0xffff0000, v89
	v_pk_fma_f32 v[58:59], v[38:39], v[142:143], v[0:1] op_sel_hi:[1,1,0]
	v_pk_mul_f32 v[38:39], v[62:63], s[74:75] op_sel_hi:[1,0]
	v_mov_b32_e32 v40, v25
	v_mov_b32_e32 v73, v143
	v_mul_f32_e32 v0, 0x3fd744fd, v41
	v_pk_fma_f32 v[66:67], v[102:103], v[104:105], v[122:123] op_sel_hi:[1,1,0]
	v_cvt_f32_f16_sdwa v103, v70 dst_sel:DWORD dst_unused:UNUSED_PAD src0_sel:WORD_1
	v_cvt_f32_f16_sdwa v105, v71 dst_sel:DWORD dst_unused:UNUSED_PAD src0_sel:WORD_1
	v_pk_fma_f32 v[62:63], v[46:47], v[68:69], v[38:39]
	v_pk_fma_f32 v[68:69], v[40:41], v[72:73], v[0:1] op_sel_hi:[1,1,0]
	v_cvt_f32_f16_e32 v71, v71
	v_cvt_f32_f16_e32 v70, v70
	global_load_dwordx4 v[38:41], v[108:109], off offset:2048 nt
	s_waitcnt vmcnt(5)
; DI float wave_sum(float v) {
; #pragma unroll
;   for (int o = 32; o > 0; o >>= 1) v += __shfl_xor(v, o);
;   return v;
; template <bool OUT16>
; DI void ln_finish(const LnRow& r, float* hout, unsigned short* hout16, bf16_t* yu, const LnVec& g, const LnVec& b, const LnVec& sc, const LnVec& sh, int c0, bool wr_u) {
;   const float sum = (r.z0.x + r.z0.y + r.z0.z + r.z0.w) + (r.z1.x + r.z1.y + r.z1.z + r.z1.w) + (r.z2.x + r.z2.y + r.z2.z + r.z2.w) + (r.z3.x + r.z3.y + r.z3.z + r.z3.w);
;   const float mean = wave_sum(sum) * (1.f / 1024.f);
;   const float sq = sq4(r.z0, mean) + sq4(r.z1, mean) + sq4(r.z2, mean) + sq4(r.z3, mean);
;   const float rstd = rsqrtf(wave_sum(sq) * (1.f / 1024.f) + 1e-5f);
	v_lshlrev_b32_e32 v73, 16, v95
	v_lshlrev_b32_e32 v72, 16, v94
	v_pk_mul_f32 v[70:71], v[70:71], s[74:75] op_sel_hi:[1,0]
	v_and_b32_e32 v142, 0xffff0000, v94
	v_pk_fma_f32 v[134:135], v[60:61], v[72:73], v[70:71]
	v_lshlrev_b32_e32 v70, 16, v97
	v_and_b32_e32 v71, 0xffff0000, v97
	v_mul_f32_e32 v172, v32, v70
	v_mul_f32_e32 v168, v33, v71
	global_load_dwordx4 v[70:73], v[110:111], off offset:3072
	v_mov_b32_e32 v102, v27
	v_mul_f32_e32 v0, 0x3fd744fd, v103
	v_lshlrev_b32_e32 v130, 16, v86
	v_and_b32_e32 v131, 0xffff0000, v86
	v_lshlrev_b32_e32 v128, 16, v87
	v_and_b32_e32 v129, 0xffff0000, v87
	v_and_b32_e32 v86, 0xffff0000, v95
	v_pk_fma_f32 v[132:133], v[102:103], v[142:143], v[0:1] op_sel_hi:[1,1,0]
	v_mov_b32_e32 v104, v29
	v_mov_b32_e32 v87, v143
	v_mul_f32_e32 v0, 0x3fd744fd, v105
	v_pk_fma_f32 v[138:139], v[104:105], v[86:87], v[0:1] op_sel_hi:[1,1,0]
	v_cvt_f32_f16_sdwa v87, v36 dst_sel:DWORD dst_unused:UNUSED_PAD src0_sel:WORD_1
	v_lshlrev_b32_e32 v142, 16, v96
	v_mul_f32_e32 v0, 0x3fd744fd, v107
	v_cvt_f32_f16_sdwa v89, v37 dst_sel:DWORD dst_unused:UNUSED_PAD src0_sel:WORD_1
	v_pk_fma_f32 v[140:141], v[106:107], v[142:143], v[0:1] op_sel_hi:[1,1,0]
	v_cvt_f32_f16_sdwa v95, v90 dst_sel:DWORD dst_unused:UNUSED_PAD src0_sel:WORD_1
	v_cvt_f32_f16_e32 v37, v37
	v_cvt_f32_f16_e32 v36, v36
	s_waitcnt vmcnt(5)
	v_and_b32_e32 v142, 0xffff0000, v100
	v_mov_b32_e32 v86, v23
	v_mul_f32_e32 v0, 0x3fd744fd, v87
	v_cvt_f32_f16_sdwa v97, v91 dst_sel:DWORD dst_unused:UNUSED_PAD src0_sel:WORD_1
	v_pk_fma_f32 v[102:103], v[86:87], v[142:143], v[0:1] op_sel_hi:[1,1,0]
	v_cvt_f32_f16_e32 v87, v91
	v_cvt_f32_f16_e32 v86, v90
	v_lshlrev_b32_e32 v110, 16, v98
	v_and_b32_e32 v111, 0xffff0000, v98
	v_lshlrev_b32_e32 v108, 16, v99
	v_and_b32_e32 v109, 0xffff0000, v99
	v_and_b32_e32 v98, 0xffff0000, v101
	v_mov_b32_e32 v88, v25
	v_mov_b32_e32 v99, v143
	v_mul_f32_e32 v0, 0x3fd744fd, v89
	v_pk_fma_f32 v[64:65], v[60:61], v[116:117], v[120:121]
	v_mul_f32_e32 v162, 0x3fd744fd, v49
	v_mul_f32_e32 v170, 0x3fd744fd, v53
	v_mul_f32_e32 v166, 0x3fd744fd, v55
	v_cvt_f32_f16_e32 v117, v92
	v_cvt_f32_f16_sdwa v49, v92 dst_sel:DWORD dst_unused:UNUSED_PAD src0_sel:WORD_1
	v_cvt_f32_f16_e32 v53, v93
	v_cvt_f32_f16_sdwa v55, v93 dst_sel:DWORD dst_unused:UNUSED_PAD src0_sel:WORD_1
	v_lshlrev_b32_e32 v93, 16, v101
	v_lshlrev_b32_e32 v92, 16, v100
	v_pk_mul_f32 v[36:37], v[36:37], s[74:75] op_sel_hi:[1,0]
	v_pk_fma_f32 v[106:107], v[88:89], v[98:99], v[0:1] op_sel_hi:[1,1,0]
	v_mov_b32_e32 v94, v27
	v_mul_f32_e32 v0, 0x3fd744fd, v95
	v_and_b32_e32 v59, 0xffff0000, v96
	v_pk_fma_f32 v[104:105], v[46:47], v[92:93], v[36:37]
	v_pk_mul_f32 v[86:87], v[86:87], s[74:75] op_sel_hi:[1,0]
	v_mov_b32_e32 v96, v29
	s_waitcnt vmcnt(2)
	v_and_b32_e32 v142, 0xffff0000, v112
	v_lshlrev_b32_e32 v89, 16, v113
	v_lshlrev_b32_e32 v88, 16, v112
	v_and_b32_e32 v90, 0xffff0000, v113
	v_pk_fma_f32 v[36:37], v[94:95], v[142:143], v[0:1] op_sel_hi:[1,1,0]
	v_mov_b32_e32 v91, v143
	v_mul_f32_e32 v0, 0x3fd744fd, v97
	v_pk_fma_f32 v[86:87], v[60:61], v[88:89], v[86:87]
	v_pk_fma_f32 v[88:89], v[96:97], v[90:91], v[0:1] op_sel_hi:[1,1,0]
	v_lshlrev_b32_e32 v142, 16, v114
	v_mov_b32_e32 v116, v30
	v_mul_f32_e32 v0, 0x3fd744fd, v117
	v_pk_fma_f32 v[90:91], v[116:117], v[142:143], v[0:1] op_sel_hi:[1,1,0]
	v_and_b32_e32 v142, 0xffff0000, v182
	v_mov_b32_e32 v92, v23
	v_cvt_f32_f16_e32 v137, v158
	s_waitcnt vmcnt(1)
	v_cvt_f32_f16_sdwa v93, v40 dst_sel:DWORD dst_unused:UNUSED_PAD src0_sel:WORD_1
	v_cvt_f32_f16_sdwa v97, v41 dst_sel:DWORD dst_unused:UNUSED_PAD src0_sel:WORD_1
	v_cvt_f32_f16_sdwa v91, v158 dst_sel:DWORD dst_unused:UNUSED_PAD src0_sel:WORD_1
	v_cvt_f32_f16_e32 v103, v159
	v_mul_f32_e32 v0, 0x3fd744fd, v93
	v_cvt_f32_f16_sdwa v113, v159 dst_sel:DWORD dst_unused:UNUSED_PAD src0_sel:WORD_1
	v_and_b32_e32 v158, 0xffff0000, v183
	v_pk_fma_f32 v[92:93], v[92:93], v[142:143], v[0:1] op_sel_hi:[1,1,0]
	v_mov_b32_e32 v96, v25
	v_mov_b32_e32 v159, v143
	v_mul_f32_e32 v0, 0x3fd744fd, v97
	v_cvt_f32_f16_sdwa v151, v156 dst_sel:DWORD dst_unused:UNUSED_PAD src0_sel:WORD_1
	v_pk_fma_f32 v[96:97], v[96:97], v[158:159], v[0:1] op_sel_hi:[1,1,0]
	v_cvt_f32_f16_e32 v158, v156
	s_waitcnt vmcnt(0)
	v_and_b32_e32 v142, 0xffff0000, v70
	v_lshlrev_b32_e32 v161, 16, v71
	v_lshlrev_b32_e32 v160, 16, v70
	v_and_b32_e32 v156, 0xffff0000, v71
	v_cvt_f32_f16_e32 v70, v42
	v_cvt_f32_f16_sdwa v71, v42 dst_sel:DWORD dst_unused:UNUSED_PAD src0_sel:WORD_1
	v_cvt_f32_f16_e32 v42, v43
	v_cvt_f32_f16_sdwa v43, v43 dst_sel:DWORD dst_unused:UNUSED_PAD src0_sel:WORD_1
	v_cvt_f32_f16_e32 v41, v41
	v_cvt_f32_f16_e32 v40, v40
	v_cvt_f32_f16_sdwa v75, v50 dst_sel:DWORD dst_unused:UNUSED_PAD src0_sel:WORD_1
	v_lshlrev_b32_e32 v50, 16, v52
	v_and_b32_e32 v51, 0xffff0000, v52
	v_pk_mul_f32 v[70:71], v[70:71], s[74:75] op_sel_hi:[1,0]
	v_pk_mul_f32 v[42:43], v[42:43], s[74:75] op_sel_hi:[1,0]
	v_pk_fma_f32 v[70:71], v[18:19], v[50:51], v[70:71]
	v_lshlrev_b32_e32 v100, 16, v180
	v_and_b32_e32 v101, 0xffff0000, v180
	v_lshlrev_b32_e32 v98, 16, v181
	v_and_b32_e32 v99, 0xffff0000, v181
	v_lshlrev_b32_e32 v95, 16, v183
	v_lshlrev_b32_e32 v94, 16, v182
	v_pk_mul_f32 v[40:41], v[40:41], s[74:75] op_sel_hi:[1,0]
	v_add_f32_e32 v0, v152, v136
	v_pk_add_f32 v[50:51], v[70:71], v[70:71] op_sel_hi:[0,1]
	v_pk_fma_f32 v[180:181], v[20:21], v[44:45], v[42:43]
	v_mul_f32_e32 v48, 0x3fd744fd, v75
	v_mul_f32_e32 v112, 0x3fd744fd, v49
	v_mul_f32_e32 v116, 0x3fd744fd, v55
	v_pk_fma_f32 v[94:95], v[46:47], v[94:95], v[40:41]
	v_pk_add_f32 v[40:41], v[152:153], v[0:1] op_sel_hi:[1,0]
	v_add_f32_e32 v0, v64, v126
	v_mov_b32_e32 v49, v180
	v_mov_b32_e32 v55, v51
	v_mul_f32_e32 v174, 0x3fd744fd, v119
	v_and_b32_e32 v37, 0xffff0000, v114
	v_pk_add_f32 v[46:47], v[64:65], v[0:1] op_sel_hi:[1,0]
	v_and_b32_e32 v0, 64, v214
	v_mov_b32_e32 v179, v41
	v_mov_b32_e32 v175, v154
	v_pk_add_f32 v[190:191], v[48:49], v[54:55]
	v_mov_b32_e32 v125, v181
	v_mul_f32_e32 v52, 0x3fd744fd, v123
	v_mul_f32_e32 v114, v31, v37
	v_mul_f32_e32 v120, 0x3fd744fd, v53
	v_add_u32_e32 v0, 64, v0
	v_xor_b32_e32 v37, 32, v214
	v_pk_add_f32 v[182:183], v[178:179], v[174:175]
	v_mov_b32_e32 v177, v47
	v_mov_b32_e32 v53, v66
	v_pk_add_f32 v[40:41], v[124:125], v[190:191]
	v_cmp_lt_i32_e32 vcc, v37, v0
	v_pk_add_f32 v[188:189], v[176:177], v[52:53]
	v_pk_add_f32 v[40:41], v[40:41], v[182:183]
	v_cndmask_b32_e32 v37, v214, v37, vcc
	v_pk_add_f32 v[40:41], v[40:41], v[188:189]
	v_lshlrev_b32_e32 v37, 2, v37
	v_add_f32_e32 v40, v40, v41
	v_mov_b32_e32 v41, v40
	s_nop 1
	v_permlane32_swap_b32_e32 v41, v40
	v_xor_b32_e32 v42, 16, v214
	v_cmp_lt_i32_e32 vcc, v42, v0
	v_and_b32_e32 v75, 0xffff0000, v115
	v_mul_f32_e32 v164, v31, v59
	v_cndmask_b32_e32 v42, v214, v42, vcc
	v_lshlrev_b32_e32 v186, 2, v42
	s_waitcnt lgkmcnt(0)
; DI float wave_sum(float v) {
; #pragma unroll
;   for (int o = 32; o > 0; o >>= 1) v += __shfl_xor(v, o);
;   return v;
; template <bool OUT16>
; DI void ln_finish(const LnRow& r, float* hout, unsigned short* hout16, bf16_t* yu, const LnVec& g, const LnVec& b, const LnVec& sc, const LnVec& sh, int c0, bool wr_u) {
;   const float sum = (r.z0.x + r.z0.y + r.z0.z + r.z0.w) + (r.z1.x + r.z1.y + r.z1.z + r.z1.w) + (r.z2.x + r.z2.y + r.z2.z + r.z2.w) + (r.z3.x + r.z3.y + r.z3.z + r.z3.w);
;   const float mean = wave_sum(sum) * (1.f / 1024.f);
;   const float sq = sq4(r.z0, mean) + sq4(r.z1, mean) + sq4(r.z2, mean) + sq4(r.z3, mean);
;   const float rstd = rsqrtf(wave_sum(sq) * (1.f / 1024.f) + 1e-5f);
	v_add_f32_e32 v40, v40, v41
	v_mov_b32_e32 v41, v40
	s_nop 1
	v_permlane16_swap_b32_e32 v41, v40
	v_xor_b32_e32 v42, 8, v214
	v_cmp_lt_i32_e32 vcc, v42, v0
	v_lshlrev_b32_e32 v59, 16, v115
	v_mul_f32_e32 v118, v33, v75
	v_cndmask_b32_e32 v42, v214, v42, vcc
	v_lshlrev_b32_e32 v185, 2, v42
	s_waitcnt lgkmcnt(0)
	v_add_f32_e32 v40, v40, v41
	s_nop 1
	v_mov_b32_dpp v41, v40 row_ror:8 row_mask:0xf bank_mask:0xf
	v_xor_b32_e32 v42, 4, v214
	v_cmp_lt_i32_e32 vcc, v42, v0
	v_mul_f32_e32 v122, v32, v59
	v_cvt_f32_f16_e32 v194, v56
	v_cndmask_b32_e32 v42, v214, v42, vcc
	v_lshlrev_b32_e32 v184, 2, v42
	s_waitcnt lgkmcnt(0)
	v_add_f32_e32 v40, v40, v41
	s_nop 1
	v_mov_b32_dpp v41, v40 row_ror:4 row_mask:0xf bank_mask:0xf
	v_xor_b32_e32 v42, 2, v214
	v_cmp_lt_i32_e32 vcc, v42, v0
	v_cvt_f32_f16_sdwa v195, v56 dst_sel:DWORD dst_unused:UNUSED_PAD src0_sel:WORD_1
	v_cvt_f32_f16_e32 v56, v57
	v_cndmask_b32_e32 v42, v214, v42, vcc
	v_lshlrev_b32_e32 v93, 2, v42
	s_waitcnt lgkmcnt(0)
	v_add_f32_e32 v40, v40, v41
	s_nop 1
	v_mov_b32_dpp v41, v40 quad_perm:[2,3,0,1] row_mask:0xf bank_mask:0xf
	v_xor_b32_e32 v42, 1, v214
	v_cmp_lt_i32_e32 vcc, v42, v0
	v_cvt_f32_f16_sdwa v57, v57 dst_sel:DWORD dst_unused:UNUSED_PAD src0_sel:WORD_1
	v_pk_mul_f32 v[194:195], v[194:195], s[74:75] op_sel_hi:[1,0]
	v_cndmask_b32_e32 v0, v214, v42, vcc
	v_lshlrev_b32_e32 v75, 2, v0
	s_waitcnt lgkmcnt(0)
	v_add_f32_e32 v0, v40, v41
	s_nop 1
	v_mov_b32_dpp v59, v0 quad_perm:[1,0,3,2] row_mask:0xf bank_mask:0xf
	v_pk_fma_f32 v[130:131], v[18:19], v[130:131], v[194:195]
	v_pk_mul_f32 v[56:57], v[56:57], s[74:75] op_sel_hi:[1,0]
	v_pk_add_f32 v[194:195], v[130:131], v[130:131] op_sel_hi:[0,1]
	v_pk_fma_f32 v[56:57], v[20:21], v[128:129], v[56:57]
	s_waitcnt lgkmcnt(0)
	v_add_f32_e32 v0, v0, v59
	v_mul_f32_e32 v0, 0x3a800000, v0
	v_pk_add_f32 v[178:179], v[70:71], v[0:1] op_sel_hi:[1,0] neg_lo:[0,1] neg_hi:[0,1]
	v_mov_b32_e32 v71, v136
	v_add_f32_e32 v136, v62, v58
	v_pk_add_f32 v[192:193], v[62:63], v[136:137] op_sel_hi:[1,0]
	v_add_f32_e32 v136, v134, v132
	v_mov_b32_e32 v163, v56
	v_mov_b32_e32 v165, v195
	v_pk_add_f32 v[196:197], v[134:135], v[136:137] op_sel_hi:[1,0]
	v_mov_b32_e32 v173, v193
	v_mov_b32_e32 v171, v68
	v_pk_add_f32 v[192:193], v[162:163], v[164:165]
	v_mov_b32_e32 v141, v57
	v_pk_add_f32 v[170:171], v[172:173], v[170:171]
	v_mov_b32_e32 v169, v197
	v_mov_b32_e32 v167, v138
	v_pk_add_f32 v[128:129], v[140:141], v[192:193]
	v_pk_add_f32 v[172:173], v[168:169], v[166:167]
	v_pk_add_f32 v[128:129], v[128:129], v[170:171]
	v_mov_b32_e32 v70, v152
	v_pk_add_f32 v[128:129], v[128:129], v[172:173]
	v_pk_add_f32 v[174:175], v[70:71], v[0:1] op_sel_hi:[1,0] neg_lo:[0,1] neg_hi:[0,1]
	v_add_f32_e32 v59, v128, v129
	v_mov_b32_e32 v115, v59
	s_nop 1
	v_permlane32_swap_b32_e32 v115, v59
	v_mov_b32_e32 v128, v64
	v_pk_mov_b32 v[64:65], v[64:65], v[66:67] op_sel:[1,0]
	v_pk_mov_b32 v[70:71], v[152:153], v[154:155] op_sel:[1,0]
	v_pk_add_f32 v[162:163], v[64:65], v[0:1] op_sel_hi:[1,0] neg_lo:[0,1] neg_hi:[0,1]
	s_waitcnt lgkmcnt(0)
	v_add_f32_e32 v59, v59, v115
	v_mov_b32_e32 v115, v59
	s_nop 1
	v_permlane16_swap_b32_e32 v115, v59
	v_mov_b32_e32 v152, v179
	v_mov_b32_e32 v153, v175
	v_pk_add_f32 v[180:181], v[180:181], v[0:1] op_sel_hi:[1,0] neg_lo:[0,1] neg_hi:[0,1]
	v_pk_add_f32 v[176:177], v[70:71], v[0:1] op_sel_hi:[1,0] neg_lo:[0,1] neg_hi:[0,1]
	s_waitcnt lgkmcnt(0)
	v_add_f32_e32 v59, v59, v115
	s_nop 1
	v_mov_b32_dpp v64, v59 row_ror:8 row_mask:0xf bank_mask:0xf
	v_mov_b32_e32 v70, v178
	v_mov_b32_e32 v71, v174
	v_pk_mul_f32 v[152:153], v[152:153], v[152:153]
	v_mov_b32_e32 v154, v181
	v_pk_fma_f32 v[70:71], v[70:71], v[70:71], v[152:153]
	v_mov_b32_e32 v152, v180
	v_mov_b32_e32 v153, v176
	v_mov_b32_e32 v155, v177
	v_pk_fma_f32 v[70:71], v[152:153], v[152:153], v[70:71]
	v_mov_b32_e32 v129, v126
	v_mov_b32_e32 v125, v190
	v_mov_b32_e32 v183, v188
	v_pk_fma_f32 v[70:71], v[154:155], v[154:155], v[70:71]
	v_pk_add_f32 v[164:165], v[128:129], v[0:1] op_sel_hi:[1,0] neg_lo:[0,1] neg_hi:[0,1]
	v_pk_add_f32 v[152:153], v[124:125], v[0:1] op_sel_hi:[1,0] neg_lo:[0,1] neg_hi:[0,1]
	v_pk_add_f32 v[154:155], v[182:183], v[0:1] op_sel_hi:[1,0] neg_lo:[0,1] neg_hi:[0,1]
	s_waitcnt lgkmcnt(0)
	v_add_f32_e32 v0, v59, v64
	global_load_dwordx4 v[40:43], v[76:77], off offset:16
	global_load_dwordx4 v[48:51], v[76:77], off
	global_load_dwordx4 v[44:47], v[78:79], off offset:16
	global_load_dwordx4 v[52:55], v[78:79], off
	s_nop 1
	v_mov_b32_dpp v59, v0 row_ror:4 row_mask:0xf bank_mask:0xf
	v_mov_b32_e32 v66, v153
	v_mov_b32_e32 v67, v165
	v_mov_b32_e32 v64, v152
	v_mov_b32_e32 v65, v164
	s_waitcnt lgkmcnt(0)
	v_add_f32_e32 v0, v0, v59
	s_nop 1
	v_mov_b32_dpp v59, v0 quad_perm:[2,3,0,1] row_mask:0xf bank_mask:0xf
	v_pk_mul_f32 v[66:67], v[66:67], v[66:67]
	v_mov_b32_e32 v124, v155
	v_pk_fma_f32 v[64:65], v[64:65], v[64:65], v[66:67]
	v_mov_b32_e32 v66, v154
	s_waitcnt lgkmcnt(0)
	v_add_f32_e32 v0, v0, v59
	s_nop 1
	v_mov_b32_dpp v59, v0 quad_perm:[1,0,3,2] row_mask:0xf bank_mask:0xf
	v_mov_b32_e32 v67, v162
	v_mov_b32_e32 v125, v163
	v_pk_fma_f32 v[64:65], v[66:67], v[66:67], v[64:65]
	v_mov_b32_e32 v141, v192
	s_waitcnt lgkmcnt(0)
; DI float wave_sum(float v) {
; #pragma unroll
;   for (int o = 32; o > 0; o >>= 1) v += __shfl_xor(v, o);
;   return v;
; template <bool OUT16>
; DI void ln_finish(const LnRow& r, float* hout, unsigned short* hout16, bf16_t* yu, const LnVec& g, const LnVec& b, const LnVec& sc, const LnVec& sh, int c0, bool wr_u) {
;   const float sum = (r.z0.x + r.z0.y + r.z0.z + r.z0.w) + (r.z1.x + r.z1.y + r.z1.z + r.z1.w) + (r.z2.x + r.z2.y + r.z2.z + r.z2.w) + (r.z3.x + r.z3.y + r.z3.z + r.z3.w);
;   const float mean = wave_sum(sum) * (1.f / 1024.f);
;   const float sq = sq4(r.z0, mean) + sq4(r.z1, mean) + sq4(r.z2, mean) + sq4(r.z3, mean);
;   const float rstd = rsqrtf(wave_sum(sq) * (1.f / 1024.f) + 1e-5f);
;   const float4 o0 = ln_norm(r.z0, mean, rstd, g.a, b.a), o1 = ln_norm(r.z1, mean, rstd, g.b, b.b), o2 = ln_norm(r.z2, mean, rstd, g.c, b.c), o3 = ln_norm(r.z3, mean, rstd, g.d, b.d);
	v_add_f32_e32 v0, v0, v59
	v_mul_f32_e32 v0, 0x3a800000, v0
	v_pk_add_f32 v[166:167], v[56:57], v[0:1] op_sel_hi:[1,0] neg_lo:[0,1] neg_hi:[0,1]
	v_mov_b32_e32 v56, v62
	v_mov_b32_e32 v57, v58
	v_pk_fma_f32 v[64:65], v[124:125], v[124:125], v[64:65]
	v_pk_add_f32 v[168:169], v[130:131], v[0:1] op_sel_hi:[1,0] neg_lo:[0,1] neg_hi:[0,1]
	v_pk_add_f32 v[124:125], v[56:57], v[0:1] op_sel_hi:[1,0] neg_lo:[0,1] neg_hi:[0,1]
	v_pk_mov_b32 v[56:57], v[62:63], v[68:69] op_sel:[1,0]
	v_mov_b32_e32 v58, v169
	v_mov_b32_e32 v59, v125
	v_pk_add_f32 v[128:129], v[56:57], v[0:1] op_sel_hi:[1,0] neg_lo:[0,1] neg_hi:[0,1]
	v_mov_b32_e32 v56, v168
	v_mov_b32_e32 v57, v124
	v_pk_mul_f32 v[58:59], v[58:59], v[58:59]
	v_mov_b32_e32 v62, v167
	v_pk_fma_f32 v[56:57], v[56:57], v[56:57], v[58:59]
	v_mov_b32_e32 v58, v166
	v_mov_b32_e32 v59, v128
	v_pk_fma_f32 v[56:57], v[58:59], v[58:59], v[56:57]
	v_mov_b32_e32 v58, v134
	v_mov_b32_e32 v59, v132
	v_mov_b32_e32 v63, v129
	v_pk_add_f32 v[132:133], v[58:59], v[0:1] op_sel_hi:[1,0] neg_lo:[0,1] neg_hi:[0,1]
	v_pk_add_f32 v[126:127], v[140:141], v[0:1] op_sel_hi:[1,0] neg_lo:[0,1] neg_hi:[0,1]
	v_pk_fma_f32 v[56:57], v[62:63], v[62:63], v[56:57]
	v_pk_mov_b32 v[58:59], v[134:135], v[138:139] op_sel:[1,0]
	v_mov_b32_e32 v171, v172
	v_mov_b32_e32 v62, v127
	v_mov_b32_e32 v63, v133
	v_pk_add_f32 v[134:135], v[58:59], v[0:1] op_sel_hi:[1,0] neg_lo:[0,1] neg_hi:[0,1]
	v_pk_add_f32 v[130:131], v[170:171], v[0:1] op_sel_hi:[1,0] neg_lo:[0,1] neg_hi:[0,1]
	v_mov_b32_e32 v58, v126
	v_mov_b32_e32 v59, v132
	v_pk_mul_f32 v[62:63], v[62:63], v[62:63]
	v_mov_b32_e32 v66, v131
	v_pk_fma_f32 v[58:59], v[58:59], v[58:59], v[62:63]
	v_mov_b32_e32 v62, v130
	v_mov_b32_e32 v63, v134
	v_mov_b32_e32 v67, v135
	v_pk_fma_f32 v[58:59], v[62:63], v[62:63], v[58:59]
	v_mov_b32_e32 v62, v56
	v_pk_fma_f32 v[58:59], v[66:67], v[66:67], v[58:59]
	v_mov_b32_e32 v63, v70
	v_mov_b32_e32 v70, v57
	v_pk_add_f32 v[56:57], v[62:63], v[70:71]
	v_mov_b32_e32 v62, v59
	v_mov_b32_e32 v63, v65
	v_pk_add_f32 v[56:57], v[62:63], v[56:57]
	v_mov_b32_e32 v59, v64
	v_pk_add_f32 v[56:57], v[58:59], v[56:57]
	v_mov_b32_e32 v59, v57
	s_nop 1
	v_permlane32_swap_b32_e32 v59, v57
	v_mov_b32_e32 v58, v56
	s_nop 1
	v_permlane32_swap_b32_e32 v58, v56
	v_cvt_f32_f16_e32 v159, v157
	v_mul_f32_e32 v0, 0x3fd744fd, v151
	v_pk_fma_f32 v[138:139], v[150:151], v[142:143], v[0:1] op_sel_hi:[1,1,0]
	v_cvt_f32_f16_sdwa v149, v157 dst_sel:DWORD dst_unused:UNUSED_PAD src0_sel:WORD_1
	s_waitcnt lgkmcnt(0)
	v_pk_add_f32 v[150:151], v[56:57], v[58:59]
	v_pk_mul_f32 v[62:63], v[158:159], s[74:75] op_sel_hi:[1,0]
	v_mov_b32_e32 v159, v151
	s_nop 1
	v_permlane16_swap_b32_e32 v159, v151
	v_mov_b32_e32 v158, v150
	s_nop 1
	v_permlane16_swap_b32_e32 v158, v150
	v_pk_fma_f32 v[140:141], v[60:61], v[160:161], v[62:63]
	global_load_dwordx4 v[56:59], v[76:77], off offset:2064
	global_load_dwordx4 v[64:67], v[76:77], off offset:2048
	global_load_dwordx4 v[60:63], v[78:79], off offset:2064
	global_load_dwordx4 v[68:71], v[78:79], off offset:2048
	v_mov_b32_e32 v157, v143
	v_mul_f32_e32 v0, 0x3fd744fd, v149
	s_waitcnt lgkmcnt(0)
	v_pk_add_f32 v[150:151], v[150:151], v[158:159]
	s_nop 1
	v_mov_b32_dpp v159, v151 row_ror:8 row_mask:0xf bank_mask:0xf
	s_nop 1
	v_mov_b32_dpp v158, v150 row_ror:8 row_mask:0xf bank_mask:0xf
	v_pk_fma_f32 v[148:149], v[148:149], v[156:157], v[0:1] op_sel_hi:[1,1,0]
	v_lshlrev_b32_e32 v142, 16, v72
	v_and_b32_e32 v115, 0xffff0000, v72
	v_lshlrev_b32_e32 v117, 16, v73
	s_waitcnt lgkmcnt(0)
	v_pk_add_f32 v[150:151], v[150:151], v[158:159]
	s_nop 1
	v_mov_b32_dpp v157, v151 row_ror:4 row_mask:0xf bank_mask:0xf
	s_nop 1
	v_mov_b32_dpp v156, v150 row_ror:4 row_mask:0xf bank_mask:0xf
	v_and_b32_e32 v119, 0xffff0000, v73
	v_mov_b32_e32 v136, v30
	v_mul_f32_e32 v0, 0x3fd744fd, v137
	v_mul_f32_e32 v170, 0x3fd744fd, v103
	s_waitcnt lgkmcnt(0)
	v_pk_add_f32 v[72:73], v[150:151], v[156:157]
	s_nop 1
	v_mov_b32_dpp v159, v73 quad_perm:[2,3,0,1] row_mask:0xf bank_mask:0xf
	s_nop 1
	v_mov_b32_dpp v158, v72 quad_perm:[2,3,0,1] row_mask:0xf bank_mask:0xf
	v_pk_fma_f32 v[150:151], v[136:137], v[142:143], v[0:1] op_sel_hi:[1,1,0]
	v_mul_f32_e32 v156, 0x3fd744fd, v91
	v_mul_f32_e32 v172, v32, v117
	v_mul_f32_e32 v160, 0x3fd744fd, v113
	s_waitcnt lgkmcnt(0)
	v_pk_add_f32 v[72:73], v[72:73], v[158:159]
	s_nop 1
	v_mov_b32_dpp v137, v73 quad_perm:[1,0,3,2] row_mask:0xf bank_mask:0xf
	s_nop 1
	v_mov_b32_dpp v136, v72 quad_perm:[1,0,3,2] row_mask:0xf bank_mask:0xf
	v_mul_f32_e32 v158, v31, v115
	v_mul_f32_e32 v182, v33, v119
	v_mov_b32_e32 v117, v88
	v_mov_b32_e32 v121, v106
	s_waitcnt lgkmcnt(0)
	v_pk_add_f32 v[72:73], v[72:73], v[136:137]
	v_mov_b64_e32 v[136:137], s[14:15]
	s_mov_b32 s14, 0x3a800000
	v_pk_fma_f32 v[188:189], v[72:73], s[14:15], v[136:137] op_sel_hi:[1,0,0]
	v_mov_b32_e32 v171, v96
	v_mul_f32_e32 v0, 0x4b800000, v189
	v_cmp_gt_f32_e32 vcc, s96, v189
	v_mov_b32_e32 v161, v148
	s_nop 0
	v_cndmask_b32_e32 v0, v189, v0, vcc
	v_rsq_f32_e32 v91, v0
	v_lshlrev_b32_e32 v0, 2, v74
	v_lshl_add_u64 v[72:73], s[12:13], 0, v[0:1]
	v_mul_f32_e32 v103, 0x45800000, v91
	v_cndmask_b32_e32 v142, v91, v103, vcc
	v_pk_mul_f32 v[178:179], v[178:179], v[142:143] op_sel_hi:[1,0]
	v_pk_mul_f32 v[180:181], v[180:181], v[142:143] op_sel_hi:[1,0]
	s_waitcnt vmcnt(4)
; DI unsigned pkh2(float lo, float hi) { f32x2 v = {lo, hi}; return __builtin_bit_cast(unsigned, __builtin_convertvector(v, h16x2)); }
; template <bool OUT16>
; DI void ln_finish(const LnRow& r, float* hout, unsigned short* hout16, bf16_t* yu, const LnVec& g, const LnVec& b, const LnVec& sc, const LnVec& sh, int c0, bool wr_u) {
;   const float sum = (r.z0.x + r.z0.y + r.z0.z + r.z0.w) + (r.z1.x + r.z1.y + r.z1.z + r.z1.w) + (r.z2.x + r.z2.y + r.z2.z + r.z2.w) + (r.z3.x + r.z3.y + r.z3.z + r.z3.w);
;   const float mean = wave_sum(sum) * (1.f / 1024.f);
;   const float sq = sq4(r.z0, mean) + sq4(r.z1, mean) + sq4(r.z2, mean) + sq4(r.z3, mean);
;   const float rstd = rsqrtf(wave_sum(sq) * (1.f / 1024.f) + 1e-5f);
;   const float4 o0 = ln_norm(r.z0, mean, rstd, g.a, b.a), o1 = ln_norm(r.z1, mean, rstd, g.b, b.b), o2 = ln_norm(r.z2, mean, rstd, g.c, b.c), o3 = ln_norm(r.z3, mean, rstd, g.d, b.d);
;   if (OUT16) {
;     u32x4 wa, wb;
;     wa[0] = pkh2(o0.x, o0.y); wa[1] = pkh2(o0.z, o0.w); wa[2] = pkh2(o1.x, o1.y); wa[3] = pkh2(o1.z, o1.w);
;     wb[0] = pkh2(o2.x, o2.y); wb[1] = pkh2(o2.z, o2.w); wb[2] = pkh2(o3.x, o3.y); wb[3] = pkh2(o3.z, o3.w);
;     __builtin_nontemporal_store(wa, (u32x4*)(hout16 + c0));
;     __builtin_nontemporal_store(wb, (u32x4*)(hout16 + 512 + c0));
;   } else {
;     f32x4 v;
;     v[0] = o0.x; v[1] = o0.y; v[2] = o0.z; v[3] = o0.w; __builtin_nontemporal_store(v, (f32x4*)(hout + c0));
;     v[0] = o1.x; v[1] = o1.y; v[2] = o1.z; v[3] = o1.w; __builtin_nontemporal_store(v, (f32x4*)(hout + c0 + 4));
;     v[0] = o2.x; v[1] = o2.y; v[2] = o2.z; v[3] = o2.w; __builtin_nontemporal_store(v, (f32x4*)(hout + 512 + c0));
;     v[0] = o3.x; v[1] = o3.y; v[2] = o3.z; v[3] = o3.w; __builtin_nontemporal_store(v, (f32x4*)(hout + 512 + c0 + 4));
	v_pk_fma_f32 v[178:179], v[48:49], v[178:179], v[52:53]
	v_pk_fma_f32 v[180:181], v[50:51], v[180:181], v[54:55]
	global_store_dwordx4 v0, v[178:181], s[12:13] nt
	v_pk_mul_f32 v[174:175], v[174:175], v[142:143] op_sel_hi:[1,0]
	v_pk_mul_f32 v[176:177], v[176:177], v[142:143] op_sel_hi:[1,0]
	v_cvt_f32_f16_e32 v180, v34
	v_cvt_f32_f16_sdwa v181, v34 dst_sel:DWORD dst_unused:UNUSED_PAD src0_sel:WORD_1
	v_cvt_f32_f16_e32 v34, v35
	v_cvt_f32_f16_sdwa v35, v35 dst_sel:DWORD dst_unused:UNUSED_PAD src0_sel:WORD_1
	v_add_f32_e32 v178, v104, v102
	v_pk_add_f32 v[178:179], v[104:105], v[178:179] op_sel_hi:[1,0]
	v_pk_mul_f32 v[180:181], v[180:181], s[74:75] op_sel_hi:[1,0]
	v_add_f32_e32 v178, v86, v36
	v_pk_fma_f32 v[180:181], v[18:19], v[110:111], v[180:181]
	v_pk_mul_f32 v[34:35], v[34:35], s[74:75] op_sel_hi:[1,0]
	v_pk_add_f32 v[190:191], v[86:87], v[178:179] op_sel_hi:[1,0]
	v_pk_add_f32 v[110:111], v[180:181], v[180:181] op_sel_hi:[0,1]
	v_pk_fma_f32 v[34:35], v[20:21], v[108:109], v[34:35]
	v_mov_b32_e32 v119, v191
	v_mov_b32_e32 v113, v34
	v_mov_b32_e32 v115, v111
	v_mov_b32_e32 v123, v179
	v_pk_add_f32 v[116:117], v[118:119], v[116:117]
	v_pk_add_f32 v[118:119], v[112:113], v[114:115]
	v_mov_b32_e32 v91, v35
	v_pk_add_f32 v[120:121], v[122:123], v[120:121]
	v_pk_add_f32 v[108:109], v[90:91], v[118:119]
	v_pk_fma_f32 v[110:111], v[42:43], v[176:177], v[46:47]
	v_pk_add_f32 v[108:109], v[108:109], v[120:121]
	v_mul_f32_e32 v112, 0x4b800000, v188
	v_pk_add_f32 v[108:109], v[108:109], v[116:117]
	v_cmp_gt_f32_e32 vcc, s96, v188
	v_add_f32_e32 v91, v108, v109
	v_mov_b32_e32 v103, v91
	s_nop 1
	v_permlane32_swap_b32_e32 v103, v91
	v_pk_fma_f32 v[108:109], v[40:41], v[174:175], v[44:45]
	global_store_dwordx4 v0, v[108:111], s[12:13] offset:16 nt
	v_cndmask_b32_e32 v112, v188, v112, vcc
	v_rsq_f32_e32 v112, v112
	s_waitcnt lgkmcnt(0)
	v_add_f32_e32 v91, v91, v103
	v_mov_b32_e32 v103, v91
	s_nop 1
	v_permlane16_swap_b32_e32 v103, v91
	v_pk_mul_f32 v[110:111], v[162:163], v[142:143] op_sel_hi:[1,0]
	v_cvt_f32_f16_e32 v162, v38
	v_cvt_f32_f16_sdwa v163, v38 dst_sel:DWORD dst_unused:UNUSED_PAD src0_sel:WORD_1
	v_cvt_f32_f16_e32 v38, v39
	s_waitcnt lgkmcnt(0)
	v_add_f32_e32 v91, v91, v103
	s_nop 1
	v_mov_b32_dpp v103, v91 row_ror:8 row_mask:0xf bank_mask:0xf
	v_cvt_f32_f16_sdwa v39, v39 dst_sel:DWORD dst_unused:UNUSED_PAD src0_sel:WORD_1
	v_pk_mul_f32 v[108:109], v[164:165], v[142:143] op_sel_hi:[1,0]
	s_waitcnt vmcnt(2)
	v_pk_fma_f32 v[110:111], v[66:67], v[110:111], v[70:71]
	v_pk_fma_f32 v[108:109], v[64:65], v[108:109], v[68:69]
	s_waitcnt lgkmcnt(0)
	v_add_f32_e32 v91, v91, v103
	s_nop 1
	v_mov_b32_dpp v103, v91 row_ror:4 row_mask:0xf bank_mask:0xf
	v_pk_mul_f32 v[162:163], v[162:163], s[74:75] op_sel_hi:[1,0]
	global_store_dwordx4 v0, v[108:111], s[12:13] offset:2048 nt
	v_pk_fma_f32 v[100:101], v[18:19], v[100:101], v[162:163]
	v_pk_mul_f32 v[38:39], v[38:39], s[74:75] op_sel_hi:[1,0]
	s_waitcnt lgkmcnt(0)
	v_add_f32_e32 v91, v91, v103
	s_nop 1
	v_mov_b32_dpp v103, v91 quad_perm:[2,3,0,1] row_mask:0xf bank_mask:0xf
	v_pk_mul_f32 v[110:111], v[154:155], v[142:143] op_sel_hi:[1,0]
	v_add_f32_e32 v154, v94, v92
	v_pk_add_f32 v[154:155], v[94:95], v[154:155] op_sel_hi:[1,0]
	v_pk_add_f32 v[162:163], v[100:101], v[100:101] op_sel_hi:[0,1]
	s_waitcnt lgkmcnt(0)
	v_add_f32_e32 v91, v91, v103
	s_nop 1
	v_mov_b32_dpp v103, v91 quad_perm:[1,0,3,2] row_mask:0xf bank_mask:0xf
	v_pk_fma_f32 v[38:39], v[20:21], v[98:99], v[38:39]
	v_add_f32_e32 v154, v140, v138
	v_mov_b32_e32 v157, v38
	v_mov_b32_e32 v159, v163
	v_pk_add_f32 v[164:165], v[140:141], v[154:155] op_sel_hi:[1,0]
	v_mov_b32_e32 v173, v155
	v_pk_add_f32 v[156:157], v[156:157], v[158:159]
	v_mov_b32_e32 v151, v39
	v_pk_add_f32 v[98:99], v[172:173], v[170:171]
	v_mov_b32_e32 v183, v165
	v_pk_add_f32 v[158:159], v[150:151], v[156:157]
	v_pk_add_f32 v[154:155], v[182:183], v[160:161]
	v_pk_add_f32 v[158:159], v[158:159], v[98:99]
	s_waitcnt lgkmcnt(0)
	v_add_f32_e32 v91, v91, v103
	v_pk_add_f32 v[158:159], v[158:159], v[154:155]
	v_pk_mul_f32 v[108:109], v[152:153], v[142:143] op_sel_hi:[1,0]
	v_mul_f32_e32 v142, 0x3a800000, v91
	v_add_f32_e32 v91, v158, v159
	v_mov_b32_e32 v99, v91
	s_nop 1
	v_permlane32_swap_b32_e32 v99, v91
	v_pk_fma_f32 v[110:111], v[58:59], v[110:111], v[62:63]
	v_pk_fma_f32 v[108:109], v[56:57], v[108:109], v[60:61]
	global_store_dwordx4 v0, v[108:111], s[12:13] offset:2064 nt
	v_mul_f32_e32 v0, 0x45800000, v112
	v_cndmask_b32_e32 v0, v112, v0, vcc
	v_pk_mul_f32 v[110:111], v[166:167], v[0:1] op_sel_hi:[1,0]
	s_waitcnt lgkmcnt(0)
	v_add_f32_e32 v91, v91, v99
	v_pk_mul_f32 v[108:109], v[168:169], v[0:1] op_sel_hi:[1,0]
	v_pk_fma_f32 v[114:115], v[50:51], v[110:111], v[54:55]
	v_pk_add_f32 v[110:111], v[34:35], v[142:143] op_sel_hi:[1,0] neg_lo:[0,1] neg_hi:[0,1]
	v_mov_b32_e32 v34, v104
	v_mov_b32_e32 v35, v102
	v_mov_b32_e32 v99, v91
	s_nop 1
	v_permlane16_swap_b32_e32 v99, v91
	v_pk_fma_f32 v[112:113], v[48:49], v[108:109], v[52:53]
	v_pk_add_f32 v[108:109], v[180:181], v[142:143] op_sel_hi:[1,0] neg_lo:[0,1] neg_hi:[0,1]
	v_pk_add_f32 v[34:35], v[34:35], v[142:143] op_sel_hi:[1,0] neg_lo:[0,1] neg_hi:[0,1]
	v_pk_mov_b32 v[102:103], v[104:105], v[106:107] op_sel:[1,0]
	v_mov_b32_e32 v106, v109
	v_mov_b32_e32 v107, v35
	v_pk_add_f32 v[102:103], v[102:103], v[142:143] op_sel_hi:[1,0] neg_lo:[0,1] neg_hi:[0,1]
	v_mov_b32_e32 v104, v108
	v_mov_b32_e32 v105, v34
	v_pk_mul_f32 v[106:107], v[106:107], v[106:107]
	v_mov_b32_e32 v121, v116
	v_pk_fma_f32 v[104:105], v[104:105], v[104:105], v[106:107]
	v_mov_b32_e32 v106, v110
	v_mov_b32_e32 v107, v102
	v_pk_fma_f32 v[104:105], v[106:107], v[106:107], v[104:105]
	v_mov_b32_e32 v107, v36
	s_waitcnt lgkmcnt(0)
; DI float wave_sum(float v) {
; #pragma unroll
;   for (int o = 32; o > 0; o >>= 1) v += __shfl_xor(v, o);
;   return v;
; template <bool OUT16>
; DI void ln_finish(const LnRow& r, float* hout, unsigned short* hout16, bf16_t* yu, const LnVec& g, const LnVec& b, const LnVec& sc, const LnVec& sh, int c0, bool wr_u) {
;   const float sum = (r.z0.x + r.z0.y + r.z0.z + r.z0.w) + (r.z1.x + r.z1.y + r.z1.z + r.z1.w) + (r.z2.x + r.z2.y + r.z2.z + r.z2.w) + (r.z3.x + r.z3.y + r.z3.z + r.z3.w);
;   const float mean = wave_sum(sum) * (1.f / 1024.f);
;   const float sq = sq4(r.z0, mean) + sq4(r.z1, mean) + sq4(r.z2, mean) + sq4(r.z3, mean);
;   const float rstd = rsqrtf(wave_sum(sq) * (1.f / 1024.f) + 1e-5f);
;   const float4 o0 = ln_norm(r.z0, mean, rstd, g.a, b.a), o1 = ln_norm(r.z1, mean, rstd, g.b, b.b), o2 = ln_norm(r.z2, mean, rstd, g.c, b.c), o3 = ln_norm(r.z3, mean, rstd, g.d, b.d);
	v_add_f32_e32 v36, v91, v99
	s_nop 1
	v_mov_b32_dpp v99, v36 row_ror:8 row_mask:0xf bank_mask:0xf
	v_mov_b32_e32 v106, v86
	v_mov_b32_e32 v91, v118
	v_pk_add_f32 v[106:107], v[106:107], v[142:143] op_sel_hi:[1,0] neg_lo:[0,1] neg_hi:[0,1]
	v_pk_mov_b32 v[86:87], v[86:87], v[88:89] op_sel:[1,0]
	s_waitcnt lgkmcnt(0)
	v_add_f32_e32 v36, v36, v99
	s_nop 1
	v_mov_b32_dpp v99, v36 row_ror:4 row_mask:0xf bank_mask:0xf
	v_pk_add_f32 v[88:89], v[90:91], v[142:143] op_sel_hi:[1,0] neg_lo:[0,1] neg_hi:[0,1]
	v_mov_b32_e32 v119, v107
	v_mov_b32_e32 v118, v89
	v_pk_add_f32 v[86:87], v[86:87], v[142:143] op_sel_hi:[1,0] neg_lo:[0,1] neg_hi:[0,1]
	s_waitcnt lgkmcnt(0)
	v_add_f32_e32 v36, v36, v99
	s_nop 1
	v_mov_b32_dpp v99, v36 quad_perm:[2,3,0,1] row_mask:0xf bank_mask:0xf
	v_pk_add_f32 v[90:91], v[120:121], v[142:143] op_sel_hi:[1,0] neg_lo:[0,1] neg_hi:[0,1]
	v_mov_b32_e32 v116, v88
	v_mov_b32_e32 v117, v106
	v_pk_mul_f32 v[118:119], v[118:119], v[118:119]
	s_waitcnt lgkmcnt(0)
	v_add_f32_e32 v36, v36, v99
	s_nop 1
	v_mov_b32_dpp v99, v36 quad_perm:[1,0,3,2] row_mask:0xf bank_mask:0xf
	v_pk_fma_f32 v[116:117], v[116:117], v[116:117], v[118:119]
	v_mov_b32_e32 v118, v90
	v_mov_b32_e32 v119, v86
	v_mov_b32_e32 v120, v91
	s_waitcnt lgkmcnt(0)
	v_add_f32_e32 v36, v36, v99
	v_mul_f32_e32 v36, 0x3a800000, v36
	v_mov_b32_e32 v121, v87
	v_pk_fma_f32 v[116:117], v[118:119], v[118:119], v[116:117]
	v_pk_add_f32 v[118:119], v[38:39], v[36:37] op_sel_hi:[1,0] neg_lo:[0,1] neg_hi:[0,1]
	v_mov_b32_e32 v38, v94
	v_mov_b32_e32 v39, v92
	v_pk_fma_f32 v[116:117], v[120:121], v[120:121], v[116:117]
	v_pk_add_f32 v[100:101], v[100:101], v[36:37] op_sel_hi:[1,0] neg_lo:[0,1] neg_hi:[0,1]
	v_pk_add_f32 v[120:121], v[38:39], v[36:37] op_sel_hi:[1,0] neg_lo:[0,1] neg_hi:[0,1]
	v_pk_mov_b32 v[38:39], v[94:95], v[96:97] op_sel:[1,0]
	v_mov_b32_e32 v96, v101
	v_mov_b32_e32 v97, v121
	v_pk_add_f32 v[94:95], v[38:39], v[36:37] op_sel_hi:[1,0] neg_lo:[0,1] neg_hi:[0,1]
	v_mov_b32_e32 v38, v100
	v_mov_b32_e32 v39, v120
	v_pk_mul_f32 v[96:97], v[96:97], v[96:97]
	v_mov_b32_e32 v151, v156
	v_pk_fma_f32 v[38:39], v[38:39], v[38:39], v[96:97]
	v_mov_b32_e32 v96, v118
	v_mov_b32_e32 v97, v94
	v_pk_fma_f32 v[38:39], v[96:97], v[96:97], v[38:39]
	v_mov_b32_e32 v96, v140
	v_mov_b32_e32 v97, v138
	v_pk_add_f32 v[96:97], v[96:97], v[36:37] op_sel_hi:[1,0] neg_lo:[0,1] neg_hi:[0,1]
	v_pk_mov_b32 v[138:139], v[140:141], v[148:149] op_sel:[1,0]
	v_pk_add_f32 v[140:141], v[150:151], v[36:37] op_sel_hi:[1,0] neg_lo:[0,1] neg_hi:[0,1]
	v_mov_b32_e32 v99, v154
	v_mov_b32_e32 v150, v141
	v_mov_b32_e32 v151, v97
	v_mov_b32_e32 v152, v111
	v_mov_b32_e32 v153, v103
	v_pk_add_f32 v[138:139], v[138:139], v[36:37] op_sel_hi:[1,0] neg_lo:[0,1] neg_hi:[0,1]
	v_pk_add_f32 v[98:99], v[98:99], v[36:37] op_sel_hi:[1,0] neg_lo:[0,1] neg_hi:[0,1]
	v_mov_b32_e32 v148, v140
	v_mov_b32_e32 v149, v96
	v_pk_mul_f32 v[150:151], v[150:151], v[150:151]
	v_pk_fma_f32 v[104:105], v[152:153], v[152:153], v[104:105]
	v_mov_b32_e32 v152, v119
	v_mov_b32_e32 v153, v95
	v_pk_fma_f32 v[148:149], v[148:149], v[148:149], v[150:151]
	v_mov_b32_e32 v150, v98
	v_mov_b32_e32 v151, v138
	v_pk_fma_f32 v[38:39], v[152:153], v[152:153], v[38:39]
	v_mov_b32_e32 v152, v99
	v_mov_b32_e32 v153, v139
	v_pk_fma_f32 v[148:149], v[150:151], v[150:151], v[148:149]
	v_mov_b32_e32 v150, v38
	v_pk_fma_f32 v[148:149], v[152:153], v[152:153], v[148:149]
	v_mov_b32_e32 v151, v104
	v_mov_b32_e32 v104, v39
	v_pk_add_f32 v[38:39], v[150:151], v[104:105]
	v_mov_b32_e32 v104, v149
	v_mov_b32_e32 v105, v117
	v_pk_add_f32 v[38:39], v[104:105], v[38:39]
	v_mov_b32_e32 v149, v116
	v_pk_add_f32 v[38:39], v[148:149], v[38:39]
	v_mov_b32_e32 v105, v39
	s_nop 1
	v_permlane32_swap_b32_e32 v105, v39
	v_mov_b32_e32 v104, v38
	s_nop 1
	v_permlane32_swap_b32_e32 v104, v38
	v_add_co_u32_e32 v116, vcc, s91, v72
	v_lshl_add_u64 v[122:123], v[72:73], 0, s[88:89]
	s_nop 0
	v_addc_co_u32_e32 v117, vcc, 0, v73, vcc
	s_waitcnt lgkmcnt(0)
	v_pk_add_f32 v[36:37], v[38:39], v[104:105]
	v_mov_b32_e32 v39, v37
	s_nop 1
	v_permlane16_swap_b32_e32 v39, v37
	v_mov_b32_e32 v38, v36
	s_nop 1
	v_permlane16_swap_b32_e32 v38, v36
	v_add_co_u32_e32 v104, vcc, s90, v72
	s_mov_b64 s[12:13], 0x1800
	s_nop 0
	v_addc_co_u32_e32 v105, vcc, 0, v73, vcc
	s_waitcnt lgkmcnt(0)
	v_pk_add_f32 v[36:37], v[36:37], v[38:39]
	s_nop 1
	v_mov_b32_dpp v149, v37 row_ror:8 row_mask:0xf bank_mask:0xf
	s_nop 1
	v_mov_b32_dpp v148, v36 row_ror:8 row_mask:0xf bank_mask:0xf
	global_store_dwordx4 v[104:105], v[112:115], off offset:-4096 nt
	v_pk_mul_f32 v[38:39], v[128:129], v[0:1] op_sel_hi:[1,0]
	s_nop 0
	v_pk_mul_f32 v[112:113], v[124:125], v[0:1] op_sel_hi:[1,0]
	s_waitcnt lgkmcnt(0)
; DI unsigned pkh2(float lo, float hi) { f32x2 v = {lo, hi}; return __builtin_bit_cast(unsigned, __builtin_convertvector(v, h16x2)); }
; template <bool OUT16>
; DI void ln_finish(const LnRow& r, float* hout, unsigned short* hout16, bf16_t* yu, const LnVec& g, const LnVec& b, const LnVec& sc, const LnVec& sh, int c0, bool wr_u) {
;     ...
;   const float sq = sq4(r.z0, mean) + sq4(r.z1, mean) + sq4(r.z2, mean) + sq4(r.z3, mean);
;   const float rstd = rsqrtf(wave_sum(sq) * (1.f / 1024.f) + 1e-5f);
;   const float4 o0 = ln_norm(r.z0, mean, rstd, g.a, b.a), o1 = ln_norm(r.z1, mean, rstd, g.b, b.b), o2 = ln_norm(r.z2, mean, rstd, g.c, b.c), o3 = ln_norm(r.z3, mean, rstd, g.d, b.d);
;   if (OUT16) {
;     u32x4 wa, wb;
;     wa[0] = pkh2(o0.x, o0.y); wa[1] = pkh2(o0.z, o0.w); wa[2] = pkh2(o1.x, o1.y); wa[3] = pkh2(o1.z, o1.w);
;     wb[0] = pkh2(o2.x, o2.y); wb[1] = pkh2(o2.z, o2.w); wb[2] = pkh2(o3.x, o3.y); wb[3] = pkh2(o3.z, o3.w);
;     __builtin_nontemporal_store(wa, (u32x4*)(hout16 + c0));
;     __builtin_nontemporal_store(wb, (u32x4*)(hout16 + 512 + c0));
;   } else {
;     f32x4 v;
;     v[0] = o0.x; v[1] = o0.y; v[2] = o0.z; v[3] = o0.w; __builtin_nontemporal_store(v, (f32x4*)(hout + c0));
;     v[0] = o1.x; v[1] = o1.y; v[2] = o1.z; v[3] = o1.w; __builtin_nontemporal_store(v, (f32x4*)(hout + c0 + 4));
;     v[0] = o2.x; v[1] = o2.y; v[2] = o2.z; v[3] = o2.w; __builtin_nontemporal_store(v, (f32x4*)(hout + 512 + c0));
;     v[0] = o3.x; v[1] = o3.y; v[2] = o3.z; v[3] = o3.w; __builtin_nontemporal_store(v, (f32x4*)(hout + 512 + c0 + 4));
	v_pk_add_f32 v[114:115], v[36:37], v[148:149]
	s_nop 1
	v_mov_b32_dpp v125, v115 row_ror:4 row_mask:0xf bank_mask:0xf
	s_nop 1
	v_mov_b32_dpp v124, v114 row_ror:4 row_mask:0xf bank_mask:0xf
	v_pk_fma_f32 v[36:37], v[40:41], v[112:113], v[44:45]
	v_pk_fma_f32 v[38:39], v[42:43], v[38:39], v[46:47]
	global_store_dwordx4 v[122:123], v[36:39], off offset:16 nt
	s_waitcnt lgkmcnt(0)
	v_pk_add_f32 v[112:113], v[114:115], v[124:125]
	s_nop 1
	v_mov_b32_dpp v115, v113 quad_perm:[2,3,0,1] row_mask:0xf bank_mask:0xf
	s_nop 1
	v_mov_b32_dpp v114, v112 quad_perm:[2,3,0,1] row_mask:0xf bank_mask:0xf
	v_pk_mul_f32 v[36:37], v[132:133], v[0:1] op_sel_hi:[1,0]
	v_pk_mul_f32 v[38:39], v[134:135], v[0:1] op_sel_hi:[1,0]
	v_pk_fma_f32 v[36:37], v[64:65], v[36:37], v[68:69]
	v_pk_fma_f32 v[38:39], v[66:67], v[38:39], v[70:71]
	s_waitcnt lgkmcnt(0)
	v_pk_add_f32 v[112:113], v[112:113], v[114:115]
	s_nop 1
	v_mov_b32_dpp v115, v113 quad_perm:[1,0,3,2] row_mask:0xf bank_mask:0xf
	s_nop 1
	v_mov_b32_dpp v114, v112 quad_perm:[1,0,3,2] row_mask:0xf bank_mask:0xf
	global_store_dwordx4 v[116:117], v[36:39], off offset:2048 nt
	v_lshl_add_u64 v[92:93], v[72:73], 0, s[12:13]
	s_mov_b64 s[12:13], 0x2000
	v_pk_mul_f32 v[36:37], v[126:127], v[0:1] op_sel_hi:[1,0]
	s_waitcnt lgkmcnt(0)
	v_pk_add_f32 v[112:113], v[112:113], v[114:115]
	v_pk_mul_f32 v[38:39], v[130:131], v[0:1] op_sel_hi:[1,0]
	v_pk_fma_f32 v[112:113], v[112:113], s[14:15], v[136:137] op_sel_hi:[1,0,0]
	v_pk_fma_f32 v[38:39], v[58:59], v[38:39], v[62:63]
	v_mul_f32_e32 v0, 0x4b800000, v113
	v_cmp_gt_f32_e32 vcc, s96, v113
	v_pk_fma_f32 v[36:37], v[56:57], v[36:37], v[60:61]
	global_store_dwordx4 v[92:93], v[36:39], off offset:16 nt
	v_cndmask_b32_e32 v0, v113, v0, vcc
	v_rsq_f32_e32 v0, v0
	v_lshl_add_u64 v[92:93], v[72:73], 0, s[12:13]
	s_mov_b64 s[12:13], 0x2800
	v_lshl_add_u64 v[114:115], v[72:73], 0, s[12:13]
	v_mul_f32_e32 v36, 0x45800000, v0
	v_cndmask_b32_e32 v0, v0, v36, vcc
	v_pk_mul_f32 v[36:37], v[108:109], v[0:1] op_sel_hi:[1,0]
	v_pk_mul_f32 v[38:39], v[110:111], v[0:1] op_sel_hi:[1,0]
	v_pk_fma_f32 v[36:37], v[48:49], v[36:37], v[52:53]
	v_pk_fma_f32 v[38:39], v[50:51], v[38:39], v[54:55]
	global_store_dwordx4 v[104:105], v[36:39], off nt
	v_pk_mul_f32 v[34:35], v[34:35], v[0:1] op_sel_hi:[1,0]
	v_cmp_gt_f32_e32 vcc, s96, v112
	v_pk_mul_f32 v[36:37], v[102:103], v[0:1] op_sel_hi:[1,0]
	v_pk_fma_f32 v[34:35], v[40:41], v[34:35], v[44:45]
	v_pk_fma_f32 v[36:37], v[42:43], v[36:37], v[46:47]
	global_store_dwordx4 v[92:93], v[34:37], off offset:16 nt
	s_mov_b64 s[12:13], 0x3000
	v_lshl_add_u64 v[38:39], v[72:73], 0, s[12:13]
	v_pk_mul_f32 v[34:35], v[106:107], v[0:1] op_sel_hi:[1,0]
	v_pk_mul_f32 v[36:37], v[86:87], v[0:1] op_sel_hi:[1,0]
	v_pk_fma_f32 v[34:35], v[64:65], v[34:35], v[68:69]
	v_pk_fma_f32 v[36:37], v[66:67], v[36:37], v[70:71]
	global_store_dwordx4 v[104:105], v[34:37], off offset:2048 nt
	s_mov_b64 s[12:13], 0x3800
	s_nop 0
	v_pk_mul_f32 v[34:35], v[88:89], v[0:1] op_sel_hi:[1,0]
	v_pk_mul_f32 v[36:37], v[90:91], v[0:1] op_sel_hi:[1,0]
	v_mul_f32_e32 v0, 0x4b800000, v112
	v_cndmask_b32_e32 v0, v112, v0, vcc
	v_rsq_f32_e32 v0, v0
	v_pk_fma_f32 v[36:37], v[58:59], v[36:37], v[62:63]
	v_pk_fma_f32 v[34:35], v[56:57], v[34:35], v[60:61]
	global_store_dwordx4 v[114:115], v[34:37], off offset:16 nt
	s_nop 1
	v_mul_f32_e32 v34, 0x45800000, v0
	v_cndmask_b32_e32 v0, v0, v34, vcc
	v_pk_mul_f32 v[34:35], v[100:101], v[0:1] op_sel_hi:[1,0]
	v_pk_mul_f32 v[36:37], v[118:119], v[0:1] op_sel_hi:[1,0]
	v_pk_fma_f32 v[34:35], v[48:49], v[34:35], v[52:53]
	v_add_co_u32_e32 v48, vcc, s3, v72
	v_pk_fma_f32 v[36:37], v[50:51], v[36:37], v[54:55]
	s_nop 0
	v_addc_co_u32_e32 v49, vcc, 0, v73, vcc
	global_store_dwordx4 v[48:49], v[34:37], off nt
	s_nop 1
	v_pk_mul_f32 v[34:35], v[120:121], v[0:1] op_sel_hi:[1,0]
	v_pk_mul_f32 v[36:37], v[94:95], v[0:1] op_sel_hi:[1,0]
	v_pk_fma_f32 v[34:35], v[40:41], v[34:35], v[44:45]
	v_pk_fma_f32 v[36:37], v[42:43], v[36:37], v[46:47]
	global_store_dwordx4 v[38:39], v[34:37], off offset:16 nt
	v_lshl_add_u64 v[38:39], v[72:73], 0, s[12:13]
	s_mov_b64 s[12:13], 0
	v_pk_mul_f32 v[34:35], v[96:97], v[0:1] op_sel_hi:[1,0]
	v_pk_mul_f32 v[36:37], v[138:139], v[0:1] op_sel_hi:[1,0]
	v_pk_fma_f32 v[34:35], v[64:65], v[34:35], v[68:69]
	v_pk_fma_f32 v[36:37], v[66:67], v[36:37], v[70:71]
	global_store_dwordx4 v[48:49], v[34:37], off offset:2048 nt
	s_nop 1
	v_pk_mul_f32 v[34:35], v[140:141], v[0:1] op_sel_hi:[1,0]
	v_pk_mul_f32 v[36:37], v[98:99], v[0:1] op_sel_hi:[1,0]
	v_pk_fma_f32 v[34:35], v[56:57], v[34:35], v[60:61]
	v_pk_fma_f32 v[36:37], v[58:59], v[36:37], v[62:63]
	global_store_dwordx4 v[38:39], v[34:37], off offset:16 nt

; template <bool OUT16>
; DI void ln_finish(const LnRow& r, float* hout, unsigned short* hout16, bf16_t* yu, const LnVec& g, const LnVec& b, const LnVec& sc, const LnVec& sh, int c0, bool wr_u) {
;   const float sum = (r.z0.x + r.z0.y + r.z0.z + r.z0.w) + (r.z1.x + r.z1.y + r.z1.z + r.z1.w) + (r.z2.x + r.z2.y + r.z2.z + r.z2.w) + (r.z3.x + r.z3.y + r.z3.z + r.z3.w);
;   const float mean = wave_sum(sum) * (1.f / 1024.f);
;   const float sq = sq4(r.z0, mean) + sq4(r.z1, mean) + sq4(r.z2, mean) + sq4(r.z3, mean);
;   const float rstd = rsqrtf(wave_sum(sq) * (1.f / 1024.f) + 1e-5f);
; template <bool IN16, bool OUT16>
; DI void ln_body(const Params& p, int layer) {
;     ...
;       for (int j = 0; j < nr; ++j) {
;         const int rj = row + j;
;         const bool isctx = rj >= TL;
;         const int b = isctx ? 32 : (rj >> 11);
;         if (b != bcur) {
;           bcur = b;
;           const float* md = p.mod + ((size_t)layer * 33 + b) * 3072;
;           md2 = p.mod + ((size_t)(wr_u ? layer + 1 : layer) * 33 + b) * 3072;
;           gate = ln_ldvec(md + 2048, c0);
;         }
;         const float* hin = isctx ? (p.ctx + (size_t)(rj - TL) * 1024) : (p.x + (size_t)rj * 1024);
;         const unsigned short* hin16 = in16 ? (p.h16 + (size_t)rj * 1024) : nullptr;
;         float* hout = p.out + (size_t)(isctx ? 0 : rj) * 1024;
;         unsigned short* hout16 = out16 ? (p.h16 + (size_t)rj * 1024) : nullptr;
;         bf16_t* yu = p.u + (size_t)rj * 1024;
;         const LnRow ra = ln_load<IN16>(hin, hin16, yu, gate, c0);
;         const LnVec g = ln_ldvec(lgp, c0), bb = ln_ldvec(lbp, c0), sc = ln_ldvec(md2 + 1024, c0), sh = ln_ldvec(md2, c0);
;         ln_finish<OUT16>(ra, hout, hout16, yu, g, bb, sc, sh, c0, wr_u);
.LBB0_131:
	v_lshl_add_u64 v[18:19], v[84:85], 0, s[12:13]
	v_lshl_add_u64 v[22:23], v[82:83], 0, s[12:13]
	global_load_dwordx4 v[24:27], v[18:19], off
	s_nop 0
	global_load_dwordx4 v[18:21], v[18:19], off offset:1024
	s_waitcnt vmcnt(3)
	v_mov_b32_e32 v32, v7
	global_load_dwordx4 v[34:37], v[22:23], off offset:-1024 nt
	global_load_dwordx4 v[28:31], v[22:23], off nt
	v_mov_b32_e32 v42, v9
	v_mov_b32_e32 v44, v11
	v_mov_b32_e32 v46, v13
	s_waitcnt vmcnt(4)
	v_mov_b32_e32 v48, v14
	s_cmp_lt_i32 s19, 0x10000
	s_cselect_b32 s17, s15, 0
	s_cselect_b32 s16, s14, 0
	s_add_u32 s12, s12, 0x800
	s_addc_u32 s13, s13, 0
	s_add_i32 s19, s19, 1
	s_add_u32 s14, s14, 0x400
	s_addc_u32 s15, s15, 0
	s_cmp_eq_u32 s7, s12
	s_waitcnt vmcnt(3)
	v_and_b32_e32 v142, 0xffff0000, v26
	v_lshlrev_b32_e32 v22, 16, v24
	v_and_b32_e32 v23, 0xffff0000, v24
	s_waitcnt vmcnt(1)
	v_cvt_f32_f16_sdwa v33, v36 dst_sel:DWORD dst_unused:UNUSED_PAD src0_sel:WORD_1
	v_cvt_f32_f16_sdwa v43, v37 dst_sel:DWORD dst_unused:UNUSED_PAD src0_sel:WORD_1
	s_waitcnt vmcnt(0)
	v_cvt_f32_f16_sdwa v45, v28 dst_sel:DWORD dst_unused:UNUSED_PAD src0_sel:WORD_1
	v_cvt_f32_f16_sdwa v47, v29 dst_sel:DWORD dst_unused:UNUSED_PAD src0_sel:WORD_1
	v_mul_f32_e32 v0, 0x3fd744fd, v33
	v_cvt_f32_f16_e32 v49, v30
	v_cvt_f32_f16_sdwa v58, v30 dst_sel:DWORD dst_unused:UNUSED_PAD src0_sel:WORD_1
	v_cvt_f32_f16_e32 v59, v31
	v_cvt_f32_f16_sdwa v61, v31 dst_sel:DWORD dst_unused:UNUSED_PAD src0_sel:WORD_1
	v_lshlrev_b32_e32 v40, 16, v25
	v_and_b32_e32 v41, 0xffff0000, v25
	v_cvt_f32_f16_e32 v25, v37
	v_cvt_f32_f16_e32 v24, v36
	v_lshlrev_b32_e32 v31, 16, v27
	v_lshlrev_b32_e32 v30, 16, v26
	v_and_b32_e32 v26, 0xffff0000, v27
	v_pk_fma_f32 v[36:37], v[32:33], v[142:143], v[0:1] op_sel_hi:[1,1,0]
	v_mov_b32_e32 v27, v143
	v_mul_f32_e32 v0, 0x3fd744fd, v43
	v_pk_fma_f32 v[42:43], v[42:43], v[26:27], v[0:1] op_sel_hi:[1,1,0]
	v_and_b32_e32 v142, 0xffff0000, v18
	v_mul_f32_e32 v0, 0x3fd744fd, v45
	v_lshlrev_b32_e32 v27, 16, v19
	v_lshlrev_b32_e32 v26, 16, v18
	v_and_b32_e32 v18, 0xffff0000, v19
	v_pk_fma_f32 v[52:53], v[44:45], v[142:143], v[0:1] op_sel_hi:[1,1,0]
	v_mov_b32_e32 v19, v143
	v_mul_f32_e32 v0, 0x3fd744fd, v47
	v_pk_fma_f32 v[56:57], v[46:47], v[18:19], v[0:1] op_sel_hi:[1,1,0]
	v_and_b32_e32 v18, 0xffff0000, v20
	v_lshlrev_b32_e32 v19, 16, v21
	v_pk_mul_f32 v[24:25], v[24:25], s[74:75] op_sel_hi:[1,0]
	v_mov_b32_e32 v32, v6
	v_mov_b32_e32 v33, v8
	v_mul_f32_e32 v46, v15, v18
	v_mul_f32_e32 v62, v16, v19
	v_cvt_f32_f16_e32 v18, v34
	v_cvt_f32_f16_sdwa v19, v34 dst_sel:DWORD dst_unused:UNUSED_PAD src0_sel:WORD_1
	v_pk_fma_f32 v[38:39], v[32:33], v[30:31], v[24:25]
	v_cvt_f32_f16_e32 v25, v29
	v_cvt_f32_f16_e32 v24, v28
	v_cvt_f32_f16_e32 v34, v35
	v_cvt_f32_f16_sdwa v35, v35 dst_sel:DWORD dst_unused:UNUSED_PAD src0_sel:WORD_1
	v_pk_mul_f32 v[18:19], v[18:19], s[74:75] op_sel_hi:[1,0]
	v_pk_mul_f32 v[24:25], v[24:25], s[74:75] op_sel_hi:[1,0]
	v_mov_b32_e32 v28, v10
	v_mov_b32_e32 v29, v12
	v_lshlrev_b32_e32 v142, 16, v20
	v_mul_f32_e32 v0, 0x3fd744fd, v49
	v_pk_fma_f32 v[68:69], v[2:3], v[22:23], v[18:19]
	v_pk_mul_f32 v[34:35], v[34:35], s[74:75] op_sel_hi:[1,0]
	v_pk_fma_f32 v[54:55], v[28:29], v[26:27], v[24:25]
	v_pk_fma_f32 v[50:51], v[48:49], v[142:143], v[0:1] op_sel_hi:[1,1,0]
	v_add_f32_e32 v0, v38, v36
	v_pk_add_f32 v[70:71], v[68:69], v[68:69] op_sel_hi:[0,1]
	v_pk_fma_f32 v[34:35], v[4:5], v[40:41], v[34:35]
	v_mul_f32_e32 v44, 0x3fd744fd, v58
	v_pk_add_f32 v[66:67], v[38:39], v[0:1] op_sel_hi:[1,0]
	v_add_f32_e32 v0, v54, v52
	v_mov_b32_e32 v45, v34
	v_mov_b32_e32 v47, v71
	v_and_b32_e32 v20, 0xffff0000, v21
	v_mul_f32_e32 v60, 0x3fd744fd, v59
	v_mul_f32_e32 v48, 0x3fd744fd, v61
	v_pk_add_f32 v[64:65], v[54:55], v[0:1] op_sel_hi:[1,0]
	v_mov_b32_e32 v63, v67
	v_mov_b32_e32 v61, v42
	v_pk_add_f32 v[70:71], v[44:45], v[46:47]
	v_mov_b32_e32 v51, v35
	v_mul_f32_e32 v58, v17, v20
	v_pk_add_f32 v[62:63], v[62:63], v[60:61]
	v_mov_b32_e32 v59, v65
	v_mov_b32_e32 v49, v56
	v_pk_add_f32 v[40:41], v[50:51], v[70:71]
	v_pk_add_f32 v[64:65], v[58:59], v[48:49]
	v_pk_add_f32 v[40:41], v[40:41], v[62:63]
	global_load_dwordx4 v[18:21], v[76:77], off offset:16
	global_load_dwordx4 v[26:29], v[76:77], off
	global_load_dwordx4 v[22:25], v[78:79], off offset:16
	global_load_dwordx4 v[30:33], v[78:79], off
	v_pk_add_f32 v[40:41], v[40:41], v[64:65]
	v_mov_b32_e32 v92, v54
	v_add_f32_e32 v0, v40, v41
	v_mov_b32_e32 v37, v0
	s_nop 1
	v_permlane32_swap_b32_e32 v37, v0
	v_mov_b32_e32 v93, v52
	v_mov_b32_e32 v51, v70
	v_pk_mov_b32 v[54:55], v[54:55], v[56:57] op_sel:[1,0]
	v_mov_b32_e32 v63, v64
	s_waitcnt lgkmcnt(0)
	v_add_f32_e32 v0, v0, v37
	v_mov_b32_e32 v37, v0
	s_nop 1
	v_permlane16_swap_b32_e32 v37, v0
	s_waitcnt lgkmcnt(0)
; DI unsigned pkh2(float lo, float hi) { f32x2 v = {lo, hi}; return __builtin_bit_cast(unsigned, __builtin_convertvector(v, h16x2)); }
; template <bool OUT16>
; DI void ln_finish(const LnRow& r, float* hout, unsigned short* hout16, bf16_t* yu, const LnVec& g, const LnVec& b, const LnVec& sc, const LnVec& sh, int c0, bool wr_u) {
;   const float sum = (r.z0.x + r.z0.y + r.z0.z + r.z0.w) + (r.z1.x + r.z1.y + r.z1.z + r.z1.w) + (r.z2.x + r.z2.y + r.z2.z + r.z2.w) + (r.z3.x + r.z3.y + r.z3.z + r.z3.w);
;   const float mean = wave_sum(sum) * (1.f / 1024.f);
;   const float sq = sq4(r.z0, mean) + sq4(r.z1, mean) + sq4(r.z2, mean) + sq4(r.z3, mean);
;   const float rstd = rsqrtf(wave_sum(sq) * (1.f / 1024.f) + 1e-5f);
;   const float4 o0 = ln_norm(r.z0, mean, rstd, g.a, b.a), o1 = ln_norm(r.z1, mean, rstd, g.b, b.b), o2 = ln_norm(r.z2, mean, rstd, g.c, b.c), o3 = ln_norm(r.z3, mean, rstd, g.d, b.d);
;   if (OUT16) {
;     u32x4 wa, wb;
;     wa[0] = pkh2(o0.x, o0.y); wa[1] = pkh2(o0.z, o0.w); wa[2] = pkh2(o1.x, o1.y); wa[3] = pkh2(o1.z, o1.w);
;     wb[0] = pkh2(o2.x, o2.y); wb[1] = pkh2(o2.z, o2.w); wb[2] = pkh2(o3.x, o3.y); wb[3] = pkh2(o3.z, o3.w);
;     __builtin_nontemporal_store(wa, (u32x4*)(hout16 + c0));
;     __builtin_nontemporal_store(wb, (u32x4*)(hout16 + 512 + c0));
;   } else {
;     f32x4 v;
;     v[0] = o0.x; v[1] = o0.y; v[2] = o0.z; v[3] = o0.w; __builtin_nontemporal_store(v, (f32x4*)(hout + c0));
;     v[0] = o1.x; v[1] = o1.y; v[2] = o1.z; v[3] = o1.w; __builtin_nontemporal_store(v, (f32x4*)(hout + c0 + 4));
;     v[0] = o2.x; v[1] = o2.y; v[2] = o2.z; v[3] = o2.w; __builtin_nontemporal_store(v, (f32x4*)(hout + 512 + c0));
;     v[0] = o3.x; v[1] = o3.y; v[2] = o3.z; v[3] = o3.w; __builtin_nontemporal_store(v, (f32x4*)(hout + 512 + c0 + 4));
	v_add_f32_e32 v0, v0, v37
	s_nop 1
	v_mov_b32_dpp v37, v0 row_ror:8 row_mask:0xf bank_mask:0xf
	s_waitcnt lgkmcnt(0)
	v_add_f32_e32 v0, v0, v37
	s_nop 1
	v_mov_b32_dpp v37, v0 row_ror:4 row_mask:0xf bank_mask:0xf
	s_waitcnt lgkmcnt(0)
	v_add_f32_e32 v0, v0, v37
	s_nop 1
	v_mov_b32_dpp v37, v0 quad_perm:[2,3,0,1] row_mask:0xf bank_mask:0xf
	s_waitcnt lgkmcnt(0)
	v_add_f32_e32 v0, v0, v37
	s_nop 1
	v_mov_b32_dpp v37, v0 quad_perm:[1,0,3,2] row_mask:0xf bank_mask:0xf
	s_waitcnt lgkmcnt(0)
	v_add_f32_e32 v0, v0, v37
	v_mul_f32_e32 v0, 0x3a800000, v0
	v_pk_add_f32 v[66:67], v[68:69], v[0:1] op_sel_hi:[1,0] neg_lo:[0,1] neg_hi:[0,1]
	v_pk_add_f32 v[68:69], v[34:35], v[0:1] op_sel_hi:[1,0] neg_lo:[0,1] neg_hi:[0,1]
	v_mov_b32_e32 v34, v38
	v_mov_b32_e32 v35, v36
	v_pk_add_f32 v[58:59], v[34:35], v[0:1] op_sel_hi:[1,0] neg_lo:[0,1] neg_hi:[0,1]
	v_pk_mov_b32 v[34:35], v[38:39], v[42:43] op_sel:[1,0]
	v_mov_b32_e32 v36, v67
	v_mov_b32_e32 v37, v59
	v_pk_add_f32 v[60:61], v[34:35], v[0:1] op_sel_hi:[1,0] neg_lo:[0,1] neg_hi:[0,1]
	v_mov_b32_e32 v34, v66
	v_mov_b32_e32 v35, v58
	v_pk_mul_f32 v[36:37], v[36:37], v[36:37]
	v_mov_b32_e32 v38, v69
	v_pk_fma_f32 v[34:35], v[34:35], v[34:35], v[36:37]
	v_mov_b32_e32 v36, v68
	v_mov_b32_e32 v37, v60
	v_mov_b32_e32 v39, v61
	v_pk_fma_f32 v[34:35], v[36:37], v[36:37], v[34:35]
	v_pk_add_f32 v[52:53], v[92:93], v[0:1] op_sel_hi:[1,0] neg_lo:[0,1] neg_hi:[0,1]
	v_pk_fma_f32 v[72:73], v[38:39], v[38:39], v[34:35]
	global_load_dwordx4 v[34:37], v[76:77], off offset:2064
	global_load_dwordx4 v[38:41], v[76:77], off offset:2048
	global_load_dwordx4 v[42:45], v[78:79], off offset:2064
	global_load_dwordx4 v[46:49], v[78:79], off offset:2048
	v_pk_add_f32 v[50:51], v[50:51], v[0:1] op_sel_hi:[1,0] neg_lo:[0,1] neg_hi:[0,1]
	v_mov_b32_e32 v65, v53
	v_mov_b32_e32 v64, v51
	v_pk_add_f32 v[54:55], v[54:55], v[0:1] op_sel_hi:[1,0] neg_lo:[0,1] neg_hi:[0,1]
	v_pk_add_f32 v[56:57], v[62:63], v[0:1] op_sel_hi:[1,0] neg_lo:[0,1] neg_hi:[0,1]
	v_mov_b32_e32 v62, v50
	v_mov_b32_e32 v63, v52
	v_pk_mul_f32 v[64:65], v[64:65], v[64:65]
	v_mov_b32_e32 v70, v57
	v_pk_fma_f32 v[62:63], v[62:63], v[62:63], v[64:65]
	v_mov_b32_e32 v64, v56
	v_mov_b32_e32 v65, v54
	v_mov_b32_e32 v71, v55
	v_pk_fma_f32 v[62:63], v[64:65], v[64:65], v[62:63]
	v_add_f32_e32 v0, v72, v73
	v_pk_fma_f32 v[62:63], v[70:71], v[70:71], v[62:63]
	s_nop 0
	v_add_f32_e32 v0, v63, v0
	v_add_f32_e32 v0, v62, v0
	v_mov_b32_e32 v62, v0
	s_nop 1
	v_permlane32_swap_b32_e32 v62, v0
	s_waitcnt lgkmcnt(0)
	v_add_f32_e32 v0, v0, v62
	v_mov_b32_e32 v62, v0
	s_nop 1
	v_permlane16_swap_b32_e32 v62, v0
	s_waitcnt lgkmcnt(0)
	v_add_f32_e32 v0, v0, v62
	s_nop 1
	v_mov_b32_dpp v62, v0 row_ror:8 row_mask:0xf bank_mask:0xf
	s_waitcnt lgkmcnt(0)
	v_add_f32_e32 v0, v0, v62
	s_nop 1
	v_mov_b32_dpp v62, v0 row_ror:4 row_mask:0xf bank_mask:0xf
	s_waitcnt lgkmcnt(0)
	v_add_f32_e32 v0, v0, v62
	s_nop 1
	v_mov_b32_dpp v62, v0 quad_perm:[2,3,0,1] row_mask:0xf bank_mask:0xf
	s_waitcnt lgkmcnt(0)
	v_add_f32_e32 v0, v0, v62
	s_nop 1
	v_mov_b32_dpp v62, v0 quad_perm:[1,0,3,2] row_mask:0xf bank_mask:0xf
	s_waitcnt lgkmcnt(0)
	v_add_f32_e32 v0, v0, v62
	v_fmamk_f32 v0, v0, 0x3a800000, v209
	v_cmp_gt_f32_e32 vcc, s96, v0
	v_mul_f32_e32 v62, 0x4b800000, v0
	s_nop 0
	v_cndmask_b32_e32 v0, v0, v62, vcc
	v_rsq_f32_e32 v0, v0
	s_nop 0
	v_mul_f32_e32 v62, 0x45800000, v0
	v_cndmask_b32_e32 v0, v0, v62, vcc
	v_pk_mul_f32 v[62:63], v[66:67], v[0:1] op_sel_hi:[1,0]
	v_pk_mul_f32 v[64:65], v[68:69], v[0:1] op_sel_hi:[1,0]
	s_waitcnt vmcnt(4)
	v_pk_fma_f32 v[26:27], v[26:27], v[62:63], v[30:31]
	v_pk_fma_f32 v[28:29], v[28:29], v[64:65], v[32:33]
	v_lshl_add_u64 v[30:31], s[16:17], 2, v[80:81]
	global_store_dwordx4 v[30:31], v[26:29], off nt
	s_nop 1
	v_pk_mul_f32 v[26:27], v[58:59], v[0:1] op_sel_hi:[1,0]
	v_pk_mul_f32 v[28:29], v[60:61], v[0:1] op_sel_hi:[1,0]
	v_pk_fma_f32 v[18:19], v[18:19], v[26:27], v[22:23]
	v_pk_fma_f32 v[20:21], v[20:21], v[28:29], v[24:25]
	global_store_dwordx4 v[30:31], v[18:21], off offset:16 nt
	s_nop 1
	v_pk_mul_f32 v[18:19], v[52:53], v[0:1] op_sel_hi:[1,0]
	v_pk_mul_f32 v[20:21], v[54:55], v[0:1] op_sel_hi:[1,0]
	s_waitcnt vmcnt(2)
	v_pk_fma_f32 v[18:19], v[38:39], v[18:19], v[46:47]
	v_pk_fma_f32 v[20:21], v[40:41], v[20:21], v[48:49]
	global_store_dwordx4 v[30:31], v[18:21], off offset:2048 nt
	s_nop 1
	v_pk_mul_f32 v[18:19], v[50:51], v[0:1] op_sel_hi:[1,0]
	v_pk_mul_f32 v[20:21], v[56:57], v[0:1] op_sel_hi:[1,0]
	v_pk_fma_f32 v[18:19], v[34:35], v[18:19], v[42:43]
	v_pk_fma_f32 v[20:21], v[36:37], v[20:21], v[44:45]
	global_store_dwordx4 v[30:31], v[18:21], off offset:2064 nt
	s_cbranch_scc1 .LBB0_122

; DI float4 ld_nt4(const float* p) { const f32x4 v = __builtin_nontemporal_load((const f32x4*)p); return make_float4(v[0], v[1], v[2], v[3]); }
; DI float4 h4lo(const u32x4 v) { return make_float4(hlo(v[0]), hhi(v[0]), hlo(v[1]), hhi(v[1])); }
; DI float4 h4hi(const u32x4 v) { return make_float4(hlo(v[2]), hhi(v[2]), hlo(v[3]), hhi(v[3])); }
; DI float4 b4lo(const uint4 v) { return make_float4(bflo(v.x), bfhi(v.x), bflo(v.y), bfhi(v.y)); }
; DI float4 b4hi(const uint4 v) { return make_float4(bflo(v.z), bfhi(v.z), bflo(v.w), bfhi(v.w)); }
; template <bool IN16>
; DI LnRow ln_load(const float* hin, const unsigned short* hin16, const bf16_t* yu, const LnVec& gate, int c0) {
;   LnRow r;
;   const uint4 ya = *(const uint4*)(yu + c0), yb = *(const uint4*)(yu + 512 + c0);
;   float4 h0, h1, h2, h3;
;   if (IN16) {
;     const u32x4 ha = __builtin_nontemporal_load((const u32x4*)(hin16 + c0)), hb = __builtin_nontemporal_load((const u32x4*)(hin16 + 512 + c0));
;     h0 = h4lo(ha); h1 = h4hi(ha); h2 = h4lo(hb); h3 = h4hi(hb);
;   } else {
;     h0 = ld_nt4(hin + c0); h1 = ld_nt4(hin + c0 + 4); h2 = ld_nt4(hin + 512 + c0); h3 = ld_nt4(hin + 512 + c0 + 4);
;   }
;   r.z0 = zmix(h0, gate.a, b4lo(ya)); r.z1 = zmix(h1, gate.b, b4hi(ya)); r.z2 = zmix(h2, gate.c, b4lo(yb)); r.z3 = zmix(h3, gate.d, b4hi(yb));
;   return r;
; }
; template <bool IN16, bool OUT16>
; DI void ln_body(const Params& p, int layer) {
;     ...
;     const bool isctx = row >= TL;
;     const float* hin = isctx ? (p.ctx + (size_t)(row - TL) * 1024) : (p.x + (size_t)row * 1024);
;     const unsigned short* hin16 = in16 ? (p.h16 + (size_t)row * 1024) : nullptr;
;     float* hout = p.out + (size_t)(isctx ? 0 : row) * 1024;
;     unsigned short* hout16 = out16 ? (p.h16 + (size_t)row * 1024) : nullptr;
;     bf16_t* yu = p.u + (size_t)row * 1024;
;     const unsigned short* hb = hin16 ? hin16 + 1024 : nullptr; const unsigned short* hc_ = hin16 ? hin16 + 2048 : nullptr; const unsigned short* hd = hin16 ? hin16 + 3072 : nullptr;
;     const LnRow ra = ln_load<IN16>(hin, hin16, yu, gate, c0), rb = ln_load<IN16>(hin + 1024, hb, yu + 1024, gate, c0), rc = ln_load<IN16>(hin + 2048, hc_, yu + 2048, gate, c0), rd = ln_load<IN16>(hin + 3072, hd, yu + 3072, gate, c0);
;     const LnVec g = ln_ldvec(lgp, c0), bb = ln_ldvec(lbp, c0), sc = ln_ldvec(md2 + 1024, c0), sh = ln_ldvec(md2, c0);
.LBB0_168:
	s_ashr_i32 s7, s6, 31
	s_lshl_b64 s[12:13], s[6:7], 11
	s_add_u32 s88, s40, s12
	s_addc_u32 s89, s41, s13
	s_add_u32 s14, s36, s12
	s_addc_u32 s15, s37, s13
	v_lshlrev_b32_e32 v0, 1, v106
	global_load_dwordx4 v[46:49], v0, s[14:15]
	global_load_dwordx4 v[54:57], v0, s[14:15] offset:1024
	global_load_dwordx4 v[58:61], v0, s[14:15] offset:2048
	global_load_dwordx4 v[62:65], v0, s[14:15] offset:3072
	v_lshl_add_u64 v[34:35], s[14:15], 0, v[0:1]
	v_add_co_u32_e32 v116, vcc, s91, v34
	s_add_u32 s7, s88, 0x800
	s_nop 0
	v_addc_co_u32_e32 v117, vcc, 0, v35, vcc
	global_load_dwordx4 v[122:125], v[116:117], off
	global_load_dwordx4 v[130:133], v[116:117], off offset:1024
	global_load_dwordx4 v[34:37], v0, s[88:89] nt
	global_load_dwordx4 v[38:41], v0, s[88:89] offset:1024 nt
	v_readlane_b32 s22, v254, 3
	s_addc_u32 s16, s89, 0
	v_readlane_b32 s23, v254, 4
	s_and_b64 s[12:13], s[22:23], exec
	s_cselect_b32 s19, 0, s16
	s_cselect_b32 s18, 0, s7
	global_load_dwordx4 v[94:97], v[116:117], off offset:2048
	global_load_dwordx4 v[82:85], v[116:117], off offset:3072
	global_load_dwordx4 v[74:77], v0, s[18:19] nt
	global_load_dwordx4 v[78:81], v0, s[18:19] offset:1024 nt
	v_lshlrev_b32_e32 v92, 2, v106
	v_mov_b32_e32 v93, v1
	v_lshl_add_u64 v[140:141], s[10:11], 0, v[92:93]
	s_add_u32 s7, s88, 0x1000
	s_addc_u32 s16, s89, 0
	s_and_b64 s[12:13], s[22:23], exec
	s_cselect_b32 s17, 0, s16
	s_cselect_b32 s16, 0, s7
	s_add_u32 s7, s88, 0x1800
	s_addc_u32 s20, s89, 0
	s_and_b64 s[12:13], s[22:23], exec
	s_cselect_b32 s13, 0, s20
	s_mov_b64 s[20:21], 0x1000
	v_lshl_add_u64 v[136:137], v[140:141], 0, s[20:21]
	s_mov_b64 s[20:21], 0x1800
	v_lshl_add_u64 v[138:139], v[140:141], 0, s[20:21]
	global_load_dwordx4 v[66:69], v0, s[16:17] nt
	global_load_dwordx4 v[70:73], v0, s[16:17] offset:1024 nt
	s_cselect_b32 s12, 0, s7
	s_mov_b32 s20, 0x3727c5ac
	s_waitcnt vmcnt(13)
	v_lshlrev_b32_e32 v42, 16, v46
	s_waitcnt vmcnt(12)
	v_lshlrev_b32_e32 v50, 16, v54
	s_waitcnt vmcnt(11)
	v_lshlrev_b32_e32 v86, 16, v58
	v_and_b32_e32 v87, 0xffff0000, v58
	v_and_b32_e32 v58, 64, v214
	s_waitcnt vmcnt(10)
	v_lshlrev_b32_e32 v100, 16, v62
	v_and_b32_e32 v101, 0xffff0000, v62
	v_add_u32_e32 v62, 64, v58
	v_xor_b32_e32 v58, 32, v214
	v_cmp_lt_i32_e32 vcc, v58, v62
	v_lshlrev_b32_e32 v88, 16, v59
	v_and_b32_e32 v89, 0xffff0000, v59
	v_cndmask_b32_e32 v58, v214, v58, vcc
	v_lshlrev_b32_e32 v107, 2, v58
	v_xor_b32_e32 v58, 16, v214
	v_cmp_lt_i32_e32 vcc, v58, v62
	v_lshlrev_b32_e32 v102, 16, v63
	v_and_b32_e32 v103, 0xffff0000, v63
	v_cndmask_b32_e32 v63, v214, v58, vcc
	s_waitcnt vmcnt(6)
	v_cvt_f32_f16_e32 v58, v41
	v_cvt_f32_f16_sdwa v59, v41 dst_sel:DWORD dst_unused:UNUSED_PAD src0_sel:WORD_1
	v_and_b32_e32 v51, 0xffff0000, v54
	v_lshlrev_b32_e32 v52, 16, v55
	v_and_b32_e32 v53, 0xffff0000, v55
	v_lshlrev_b32_e32 v54, 16, v56
	v_and_b32_e32 v55, 0xffff0000, v56
	v_lshlrev_b32_e32 v56, 16, v57
	v_and_b32_e32 v57, 0xffff0000, v57
	v_lshlrev_b32_e32 v90, 16, v60
	v_and_b32_e32 v91, 0xffff0000, v60
	v_lshlrev_b32_e32 v98, 16, v61
	v_and_b32_e32 v99, 0xffff0000, v61
	v_cvt_f32_f16_e32 v60, v40
	v_cvt_f32_f16_sdwa v61, v40 dst_sel:DWORD dst_unused:UNUSED_PAD src0_sel:WORD_1
	v_pk_mul_f32 v[40:41], v[58:59], s[74:75] op_sel_hi:[1,0]
	v_cvt_f32_f16_e32 v58, v38
	v_pk_fma_f32 v[148:149], v[32:33], v[56:57], v[40:41]
	v_cvt_f32_f16_e32 v56, v39
	v_cvt_f32_f16_sdwa v57, v39 dst_sel:DWORD dst_unused:UNUSED_PAD src0_sel:WORD_1
	v_cvt_f32_f16_sdwa v59, v38 dst_sel:DWORD dst_unused:UNUSED_PAD src0_sel:WORD_1
	v_pk_mul_f32 v[40:41], v[60:61], s[74:75] op_sel_hi:[1,0]
	v_and_b32_e32 v43, 0xffff0000, v46
	v_pk_mul_f32 v[38:39], v[56:57], s[74:75] op_sel_hi:[1,0]
	v_pk_fma_f32 v[150:151], v[30:31], v[54:55], v[40:41]
	v_pk_fma_f32 v[152:153], v[28:29], v[52:53], v[38:39]
	v_pk_mul_f32 v[38:39], v[58:59], s[74:75] op_sel_hi:[1,0]
	v_mov_b32_e32 v40, v151
	v_pk_fma_f32 v[154:155], v[26:27], v[50:51], v[38:39]
	v_cvt_f32_f16_e32 v50, v37
	v_cvt_f32_f16_sdwa v51, v37 dst_sel:DWORD dst_unused:UNUSED_PAD src0_sel:WORD_1
	v_mov_b32_e32 v38, v150
	v_mov_b32_e32 v39, v154
	v_mov_b32_e32 v41, v155
	v_pk_add_f32 v[38:39], v[38:39], v[40:41]
	v_mov_b32_e32 v40, v148
	v_mov_b32_e32 v41, v152
	v_pk_add_f32 v[38:39], v[40:41], v[38:39]
	v_mov_b32_e32 v40, v149
	v_mov_b32_e32 v41, v153
	v_lshlrev_b32_e32 v44, 16, v47
	v_and_b32_e32 v45, 0xffff0000, v47
	v_lshlrev_b32_e32 v46, 16, v48
	v_and_b32_e32 v47, 0xffff0000, v48
	v_lshlrev_b32_e32 v48, 16, v49
	v_and_b32_e32 v49, 0xffff0000, v49
	v_cvt_f32_f16_e32 v52, v36
	v_cvt_f32_f16_sdwa v53, v36 dst_sel:DWORD dst_unused:UNUSED_PAD src0_sel:WORD_1
	v_pk_add_f32 v[36:37], v[40:41], v[38:39]
	v_pk_mul_f32 v[38:39], v[50:51], s[74:75] op_sel_hi:[1,0]
	v_cvt_f32_f16_e32 v40, v35
	v_cvt_f32_f16_sdwa v41, v35 dst_sel:DWORD dst_unused:UNUSED_PAD src0_sel:WORD_1
	v_pk_fma_f32 v[156:157], v[24:25], v[48:49], v[38:39]
	v_cvt_f32_f16_e32 v48, v34
	v_cvt_f32_f16_sdwa v49, v34 dst_sel:DWORD dst_unused:UNUSED_PAD src0_sel:WORD_1
	v_pk_mul_f32 v[34:35], v[40:41], s[74:75] op_sel_hi:[1,0]
	v_pk_mul_f32 v[38:39], v[52:53], s[74:75] op_sel_hi:[1,0]
	v_pk_fma_f32 v[160:161], v[20:21], v[44:45], v[34:35]
	v_pk_mul_f32 v[34:35], v[48:49], s[74:75] op_sel_hi:[1,0]
	v_pk_fma_f32 v[158:159], v[22:23], v[46:47], v[38:39]
	v_pk_fma_f32 v[162:163], v[18:19], v[42:43], v[34:35]
	v_mov_b32_e32 v35, v158
	v_mov_b32_e32 v34, v162
	v_mov_b32_e32 v38, v163
	v_mov_b32_e32 v39, v159
	v_pk_add_f32 v[34:35], v[34:35], v[38:39]
	v_mov_b32_e32 v38, v160
	v_mov_b32_e32 v39, v156
	v_pk_add_f32 v[34:35], v[38:39], v[34:35]
	v_mov_b32_e32 v38, v161
	v_mov_b32_e32 v39, v157
	v_pk_add_f32 v[34:35], v[38:39], v[34:35]
	v_lshlrev_b32_e32 v142, 2, v63
	v_add_f32_e32 v34, v34, v35
	v_add_f32_e32 v34, v34, v37
	v_add_f32_e32 v34, v36, v34
	v_mov_b32_e32 v35, v34
	s_nop 1
	v_permlane32_swap_b32_e32 v35, v34
	v_xor_b32_e32 v36, 8, v214
	v_cmp_lt_i32_e32 vcc, v36, v62
	v_lshlrev_b32_e32 v134, 16, v65
	v_and_b32_e32 v135, 0xffff0000, v65
	s_waitcnt lgkmcnt(0)
; DI float wave_sum(float v) {
; #pragma unroll
;   for (int o = 32; o > 0; o >>= 1) v += __shfl_xor(v, o);
;   return v;
; template <bool OUT16>
; DI void ln_finish(const LnRow& r, float* hout, unsigned short* hout16, bf16_t* yu, const LnVec& g, const LnVec& b, const LnVec& sc, const LnVec& sh, int c0, bool wr_u) {
;   const float sum = (r.z0.x + r.z0.y + r.z0.z + r.z0.w) + (r.z1.x + r.z1.y + r.z1.z + r.z1.w) + (r.z2.x + r.z2.y + r.z2.z + r.z2.w) + (r.z3.x + r.z3.y + r.z3.z + r.z3.w);
;   const float mean = wave_sum(sum) * (1.f / 1024.f);
;   const float sq = sq4(r.z0, mean) + sq4(r.z1, mean) + sq4(r.z2, mean) + sq4(r.z3, mean);
;   const float rstd = rsqrtf(wave_sum(sq) * (1.f / 1024.f) + 1e-5f);
	v_add_f32_e32 v34, v34, v35
	v_mov_b32_e32 v35, v34
	s_nop 1
	v_permlane16_swap_b32_e32 v35, v34
	v_cndmask_b32_e32 v36, v214, v36, vcc
	v_lshlrev_b32_e32 v193, 2, v36
	v_xor_b32_e32 v36, 4, v214
	v_cmp_lt_i32_e32 vcc, v36, v62
	s_waitcnt lgkmcnt(0)
	v_add_f32_e32 v34, v34, v35
	s_nop 1
	v_mov_b32_dpp v35, v34 row_ror:8 row_mask:0xf bank_mask:0xf
	v_cndmask_b32_e32 v36, v214, v36, vcc
	v_lshlrev_b32_e32 v192, 2, v36
	v_xor_b32_e32 v36, 2, v214
	v_cmp_lt_i32_e32 vcc, v36, v62
	s_waitcnt lgkmcnt(0)
	v_add_f32_e32 v34, v34, v35
	s_nop 1
	v_mov_b32_dpp v35, v34 row_ror:4 row_mask:0xf bank_mask:0xf
	v_cndmask_b32_e32 v36, v214, v36, vcc
	v_lshlrev_b32_e32 v191, 2, v36
	v_xor_b32_e32 v36, 1, v214
	v_cmp_lt_i32_e32 vcc, v36, v62
	s_waitcnt lgkmcnt(0)
	v_add_f32_e32 v50, v34, v35
	s_nop 1
	v_mov_b32_dpp v51, v50 quad_perm:[2,3,0,1] row_mask:0xf bank_mask:0xf
	v_cndmask_b32_e32 v36, v214, v36, vcc
	v_lshlrev_b32_e32 v190, 2, v36
	v_lshlrev_b32_e32 v104, 16, v64
	v_and_b32_e32 v105, 0xffff0000, v64
	s_waitcnt lgkmcnt(0)
	v_add_f32_e32 v93, v50, v51
	s_nop 1
	v_mov_b32_dpp v164, v93 quad_perm:[1,0,3,2] row_mask:0xf bank_mask:0xf
	v_add_co_u32_e32 v140, vcc, s91, v140
	global_load_dwordx4 v[34:37], v[108:109], off offset:2064
	global_load_dwordx4 v[42:45], v[108:109], off offset:2048
	global_load_dwordx4 v[38:41], v[110:111], off offset:2064
	global_load_dwordx4 v[46:49], v[110:111], off offset:2048
	v_addc_co_u32_e32 v141, vcc, 0, v141, vcc
	s_waitcnt lgkmcnt(0)
	v_add_f32_e32 v93, v93, v164
	v_mul_f32_e32 v164, 0x3a800000, v93
	v_pk_add_f32 v[188:189], v[162:163], v[164:165] op_sel_hi:[1,0] neg_lo:[0,1] neg_hi:[0,1]
	v_pk_add_f32 v[184:185], v[158:159], v[164:165] op_sel_hi:[1,0] neg_lo:[0,1] neg_hi:[0,1]
	v_mov_b32_e32 v158, v189
	v_mov_b32_e32 v159, v185
	v_pk_add_f32 v[186:187], v[160:161], v[164:165] op_sel_hi:[1,0] neg_lo:[0,1] neg_hi:[0,1]
	v_pk_add_f32 v[182:183], v[156:157], v[164:165] op_sel_hi:[1,0] neg_lo:[0,1] neg_hi:[0,1]
	v_mov_b32_e32 v156, v188
	v_mov_b32_e32 v157, v184
	v_pk_mul_f32 v[158:159], v[158:159], v[158:159]
	s_waitcnt vmcnt(6)
	v_cvt_f32_f16_e32 v160, v81
	v_cvt_f32_f16_sdwa v161, v81 dst_sel:DWORD dst_unused:UNUSED_PAD src0_sel:WORD_1
	v_pk_fma_f32 v[156:157], v[156:157], v[156:157], v[158:159]
	v_mov_b32_e32 v158, v186
	v_mov_b32_e32 v159, v182
	v_pk_fma_f32 v[156:157], v[158:159], v[158:159], v[156:157]
	v_mov_b32_e32 v158, v187
	v_mov_b32_e32 v159, v183
	v_pk_fma_f32 v[156:157], v[158:159], v[158:159], v[156:157]
	v_cvt_f32_f16_e32 v158, v79
	v_cvt_f32_f16_sdwa v159, v79 dst_sel:DWORD dst_unused:UNUSED_PAD src0_sel:WORD_1
	v_cvt_f32_f16_e32 v162, v80
	v_cvt_f32_f16_sdwa v163, v80 dst_sel:DWORD dst_unused:UNUSED_PAD src0_sel:WORD_1
	v_pk_mul_f32 v[80:81], v[160:161], s[74:75] op_sel_hi:[1,0]
	v_cvt_f32_f16_e32 v160, v78
	v_cvt_f32_f16_sdwa v161, v78 dst_sel:DWORD dst_unused:UNUSED_PAD src0_sel:WORD_1
	v_pk_mul_f32 v[78:79], v[158:159], s[74:75] op_sel_hi:[1,0]
	v_pk_fma_f32 v[134:135], v[32:33], v[134:135], v[80:81]
	v_pk_mul_f32 v[80:81], v[162:163], s[74:75] op_sel_hi:[1,0]
	v_pk_fma_f32 v[102:103], v[28:29], v[102:103], v[78:79]
	v_pk_mul_f32 v[78:79], v[160:161], s[74:75] op_sel_hi:[1,0]
	v_pk_fma_f32 v[104:105], v[30:31], v[104:105], v[80:81]
	v_pk_fma_f32 v[100:101], v[26:27], v[100:101], v[78:79]
	v_mov_b32_e32 v78, v104
	v_mov_b32_e32 v79, v100
	v_mov_b32_e32 v80, v105
	v_mov_b32_e32 v81, v101
	v_cvt_f32_f16_e32 v158, v77
	v_cvt_f32_f16_sdwa v159, v77 dst_sel:DWORD dst_unused:UNUSED_PAD src0_sel:WORD_1
	v_pk_add_f32 v[78:79], v[78:79], v[80:81]
	v_mov_b32_e32 v80, v134
	v_mov_b32_e32 v81, v102
	v_pk_add_f32 v[78:79], v[80:81], v[78:79]
	v_mov_b32_e32 v80, v135
	v_mov_b32_e32 v81, v103
	v_cvt_f32_f16_e32 v160, v76
	v_cvt_f32_f16_sdwa v161, v76 dst_sel:DWORD dst_unused:UNUSED_PAD src0_sel:WORD_1
	v_pk_add_f32 v[76:77], v[80:81], v[78:79]
	v_cvt_f32_f16_e32 v80, v75
	v_cvt_f32_f16_sdwa v81, v75 dst_sel:DWORD dst_unused:UNUSED_PAD src0_sel:WORD_1
	v_pk_mul_f32 v[78:79], v[158:159], s[74:75] op_sel_hi:[1,0]
	v_cvt_f32_f16_e32 v158, v74
	v_cvt_f32_f16_sdwa v159, v74 dst_sel:DWORD dst_unused:UNUSED_PAD src0_sel:WORD_1
	v_pk_mul_f32 v[74:75], v[80:81], s[74:75] op_sel_hi:[1,0]
	v_pk_fma_f32 v[98:99], v[24:25], v[98:99], v[78:79]
	v_pk_mul_f32 v[78:79], v[160:161], s[74:75] op_sel_hi:[1,0]
	v_pk_fma_f32 v[88:89], v[20:21], v[88:89], v[74:75]
	v_pk_mul_f32 v[74:75], v[158:159], s[74:75] op_sel_hi:[1,0]
	v_pk_fma_f32 v[90:91], v[22:23], v[90:91], v[78:79]
	v_pk_fma_f32 v[86:87], v[18:19], v[86:87], v[74:75]
	v_mov_b32_e32 v75, v90
	v_mov_b32_e32 v74, v86
	v_mov_b32_e32 v78, v87
	v_mov_b32_e32 v79, v91
	v_pk_add_f32 v[74:75], v[74:75], v[78:79]
	v_mov_b32_e32 v78, v88
	v_mov_b32_e32 v79, v98
	v_pk_add_f32 v[74:75], v[78:79], v[74:75]
	v_mov_b32_e32 v78, v89
	v_mov_b32_e32 v79, v99
	v_pk_add_f32 v[74:75], v[78:79], v[74:75]
	v_pk_add_f32 v[220:221], v[150:151], v[164:165] op_sel_hi:[1,0] neg_lo:[0,1] neg_hi:[0,1]
	v_add_f32_e32 v74, v74, v75
	v_add_f32_e32 v74, v74, v77
	v_add_f32_e32 v74, v76, v74
	v_mov_b32_e32 v75, v74
	s_nop 1
	v_permlane32_swap_b32_e32 v75, v74
	v_pk_add_f32 v[206:207], v[154:155], v[164:165] op_sel_hi:[1,0] neg_lo:[0,1] neg_hi:[0,1]
	v_mov_b32_e32 v76, v221
	v_mov_b32_e32 v77, v207
	v_pk_add_f32 v[212:213], v[152:153], v[164:165] op_sel_hi:[1,0] neg_lo:[0,1] neg_hi:[0,1]
	s_waitcnt lgkmcnt(0)
	v_add_f32_e32 v78, v74, v75
	v_mov_b32_e32 v79, v78
	s_nop 1
	v_permlane16_swap_b32_e32 v79, v78
	v_pk_add_f32 v[230:231], v[148:149], v[164:165] op_sel_hi:[1,0] neg_lo:[0,1] neg_hi:[0,1]
	v_mov_b32_e32 v74, v220
	v_mov_b32_e32 v75, v206
	v_pk_mul_f32 v[76:77], v[76:77], v[76:77]
	s_waitcnt lgkmcnt(0)
; template <bool OUT16>
; DI void ln_finish(const LnRow& r, float* hout, unsigned short* hout16, bf16_t* yu, const LnVec& g, const LnVec& b, const LnVec& sc, const LnVec& sh, int c0, bool wr_u) {
;   const float sum = (r.z0.x + r.z0.y + r.z0.z + r.z0.w) + (r.z1.x + r.z1.y + r.z1.z + r.z1.w) + (r.z2.x + r.z2.y + r.z2.z + r.z2.w) + (r.z3.x + r.z3.y + r.z3.z + r.z3.w);
;   const float mean = wave_sum(sum) * (1.f / 1024.f);
;   const float sq = sq4(r.z0, mean) + sq4(r.z1, mean) + sq4(r.z2, mean) + sq4(r.z3, mean);
;   const float rstd = rsqrtf(wave_sum(sq) * (1.f / 1024.f) + 1e-5f);
;   const float4 o0 = ln_norm(r.z0, mean, rstd, g.a, b.a), o1 = ln_norm(r.z1, mean, rstd, g.b, b.b), o2 = ln_norm(r.z2, mean, rstd, g.c, b.c), o3 = ln_norm(r.z3, mean, rstd, g.d, b.d);
	v_add_f32_e32 v78, v78, v79
	s_nop 1
	v_mov_b32_dpp v79, v78 row_ror:8 row_mask:0xf bank_mask:0xf
	v_pk_fma_f32 v[74:75], v[74:75], v[74:75], v[76:77]
	v_mov_b32_e32 v76, v230
	v_mov_b32_e32 v77, v212
	v_pk_fma_f32 v[74:75], v[76:77], v[76:77], v[74:75]
	s_waitcnt lgkmcnt(0)
	v_add_f32_e32 v78, v78, v79
	s_nop 1
	v_mov_b32_dpp v79, v78 row_ror:4 row_mask:0xf bank_mask:0xf
	v_mov_b32_e32 v76, v231
	v_mov_b32_e32 v77, v213
	global_load_dwordx4 v[50:53], v[108:109], off offset:16
	global_load_dwordx4 v[58:61], v[108:109], off
	global_load_dwordx4 v[54:57], v[110:111], off offset:16
	global_load_dwordx4 v[62:65], v[110:111], off
	v_pk_fma_f32 v[148:149], v[76:77], v[76:77], v[74:75]
	s_waitcnt lgkmcnt(0)
	v_add_f32_e32 v93, v78, v79
	s_nop 1
	v_mov_b32_dpp v150, v93 quad_perm:[2,3,0,1] row_mask:0xf bank_mask:0xf
	global_load_dwordx4 v[74:77], v92, s[10:11] offset:16
	global_load_dwordx4 v[78:81], v92, s[10:11]
	global_load_dwordx4 v[194:197], v[140:141], off
	global_load_dwordx4 v[198:201], v[140:141], off offset:2048
	global_load_dwordx4 v[202:205], v[136:137], off offset:16
	global_load_dwordx4 v[226:229], v[138:139], off offset:16
	v_and_b32_e32 v151, 0xffff0000, v94
	v_lshlrev_b32_e32 v152, 16, v95
	s_waitcnt lgkmcnt(0)
	v_add_f32_e32 v93, v93, v150
	s_nop 1
	v_mov_b32_dpp v150, v93 quad_perm:[1,0,3,2] row_mask:0xf bank_mask:0xf
	v_and_b32_e32 v153, 0xffff0000, v95
	v_lshlrev_b32_e32 v154, 16, v96
	v_and_b32_e32 v155, 0xffff0000, v96
	v_lshlrev_b32_e32 v158, 16, v82
	s_waitcnt lgkmcnt(0)
	v_add_f32_e32 v93, v93, v150
	v_mul_f32_e32 v136, 0x3a800000, v93
	v_pk_add_f32 v[170:171], v[86:87], v[136:137] op_sel_hi:[1,0] neg_lo:[0,1] neg_hi:[0,1]
	v_pk_add_f32 v[166:167], v[90:91], v[136:137] op_sel_hi:[1,0] neg_lo:[0,1] neg_hi:[0,1]
	v_pk_add_f32 v[168:169], v[88:89], v[136:137] op_sel_hi:[1,0] neg_lo:[0,1] neg_hi:[0,1]
	v_mov_b32_e32 v88, v171
	v_mov_b32_e32 v89, v167
	v_pk_add_f32 v[164:165], v[98:99], v[136:137] op_sel_hi:[1,0] neg_lo:[0,1] neg_hi:[0,1]
	v_mov_b32_e32 v86, v170
	v_mov_b32_e32 v87, v166
	v_pk_mul_f32 v[88:89], v[88:89], v[88:89]
	v_pk_add_f32 v[178:179], v[100:101], v[136:137] op_sel_hi:[1,0] neg_lo:[0,1] neg_hi:[0,1]
	v_pk_fma_f32 v[86:87], v[86:87], v[86:87], v[88:89]
	v_mov_b32_e32 v88, v168
	v_mov_b32_e32 v89, v164
	v_pk_add_f32 v[174:175], v[104:105], v[136:137] op_sel_hi:[1,0] neg_lo:[0,1] neg_hi:[0,1]
	v_pk_fma_f32 v[86:87], v[88:89], v[88:89], v[86:87]
	v_mov_b32_e32 v88, v169
	v_mov_b32_e32 v89, v165
	v_mov_b32_e32 v90, v175
	v_mov_b32_e32 v91, v179
	v_pk_fma_f32 v[86:87], v[88:89], v[88:89], v[86:87]
	v_pk_add_f32 v[176:177], v[102:103], v[136:137] op_sel_hi:[1,0] neg_lo:[0,1] neg_hi:[0,1]
	v_pk_add_f32 v[172:173], v[134:135], v[136:137] op_sel_hi:[1,0] neg_lo:[0,1] neg_hi:[0,1]
	v_mov_b32_e32 v88, v174
	v_mov_b32_e32 v89, v178
	v_pk_mul_f32 v[90:91], v[90:91], v[90:91]
	global_load_dwordx4 v[98:101], v0, s[12:13] nt
	global_load_dwordx4 v[102:105], v0, s[12:13] offset:1024 nt
	v_pk_fma_f32 v[88:89], v[88:89], v[88:89], v[90:91]
	v_mov_b32_e32 v90, v172
	v_mov_b32_e32 v91, v176
	v_pk_fma_f32 v[88:89], v[90:91], v[90:91], v[88:89]
	v_mov_b32_e32 v90, v173
	v_mov_b32_e32 v91, v177
	v_pk_fma_f32 v[88:89], v[90:91], v[90:91], v[88:89]
	v_mov_b32_e32 v90, v86
	v_mov_b32_e32 v91, v156
	v_mov_b32_e32 v156, v87
	v_pk_add_f32 v[86:87], v[90:91], v[156:157]
	v_mov_b32_e32 v90, v89
	v_mov_b32_e32 v91, v149
	v_pk_add_f32 v[86:87], v[90:91], v[86:87]
	v_mov_b32_e32 v89, v148
	v_pk_add_f32 v[134:135], v[88:89], v[86:87]
	global_load_dwordx4 v[86:89], v92, s[10:11] offset:2064
	s_nop 0
	global_load_dwordx4 v[90:93], v92, s[10:11] offset:2048
	v_mov_b32_e32 v137, v135
	s_nop 1
	v_permlane32_swap_b32_e32 v137, v135
	v_mov_b32_e32 v136, v134
	s_nop 1
	v_permlane32_swap_b32_e32 v136, v134
	v_lshlrev_b32_e32 v150, 16, v94
	v_lshlrev_b32_e32 v156, 16, v97
	v_and_b32_e32 v157, 0xffff0000, v97
	v_mov_b64_e32 v[148:149], s[20:21]
	s_waitcnt lgkmcnt(0)
	v_pk_add_f32 v[134:135], v[134:135], v[136:137]
	v_mov_b32_e32 v137, v135
	s_nop 1
	v_permlane16_swap_b32_e32 v137, v135
	v_mov_b32_e32 v136, v134
	s_nop 1
	v_permlane16_swap_b32_e32 v136, v134
	s_mov_b32 s20, 0x3a800000
	v_and_b32_e32 v159, 0xffff0000, v82
	v_lshlrev_b32_e32 v160, 16, v83
	v_and_b32_e32 v161, 0xffff0000, v83
	s_waitcnt lgkmcnt(0)
	v_pk_add_f32 v[94:95], v[134:135], v[136:137]
	s_nop 1
	v_mov_b32_dpp v135, v95 row_ror:8 row_mask:0xf bank_mask:0xf
	s_nop 1
	v_mov_b32_dpp v134, v94 row_ror:8 row_mask:0xf bank_mask:0xf
	v_lshlrev_b32_e32 v162, 16, v84
	v_and_b32_e32 v163, 0xffff0000, v84
	v_lshlrev_b32_e32 v180, 16, v85
	v_and_b32_e32 v181, 0xffff0000, v85
	s_waitcnt lgkmcnt(0)
	v_pk_add_f32 v[94:95], v[94:95], v[134:135]
	s_nop 1
	v_mov_b32_dpp v97, v95 row_ror:4 row_mask:0xf bank_mask:0xf
	s_nop 1
	v_mov_b32_dpp v96, v94 row_ror:4 row_mask:0xf bank_mask:0xf
	s_waitcnt vmcnt(7)
	v_pk_add_f32 v[82:83], v[194:195], 1.0 op_sel_hi:[1,0]
	v_pk_add_f32 v[134:135], v[196:197], 1.0 op_sel_hi:[1,0]
	s_waitcnt vmcnt(6)
	v_pk_add_f32 v[84:85], v[198:199], 1.0 op_sel_hi:[1,0]
	v_pk_add_f32 v[140:141], v[200:201], 1.0 op_sel_hi:[1,0]
	s_waitcnt lgkmcnt(0)
	v_pk_add_f32 v[94:95], v[94:95], v[96:97]
	s_nop 1
	v_mov_b32_dpp v97, v95 quad_perm:[2,3,0,1] row_mask:0xf bank_mask:0xf
	s_nop 1
	v_mov_b32_dpp v96, v94 quad_perm:[2,3,0,1] row_mask:0xf bank_mask:0xf
	v_lshlrev_b32_e32 v126, 16, v130
	v_and_b32_e32 v127, 0xffff0000, v130
	v_lshlrev_b32_e32 v128, 16, v131
	v_and_b32_e32 v129, 0xffff0000, v131
	s_waitcnt lgkmcnt(0)
	v_pk_add_f32 v[136:137], v[94:95], v[96:97]
	s_nop 1
	v_mov_b32_dpp v139, v137 quad_perm:[1,0,3,2] row_mask:0xf bank_mask:0xf
	s_nop 1
	v_mov_b32_dpp v138, v136 quad_perm:[1,0,3,2] row_mask:0xf bank_mask:0xf
	s_waitcnt vmcnt(5)
; DI unsigned pkh2(float lo, float hi) { f32x2 v = {lo, hi}; return __builtin_bit_cast(unsigned, __builtin_convertvector(v, h16x2)); }
; DI unsigned umod(float a, float b, float sca, float scb, float sha, float shb) { return pk2(a * (1.f + sca) + sha, b * (1.f + scb) + shb); }
; template <bool OUT16>
; DI void ln_finish(const LnRow& r, float* hout, unsigned short* hout16, bf16_t* yu, const LnVec& g, const LnVec& b, const LnVec& sc, const LnVec& sh, int c0, bool wr_u) {
;     ...
;   const float rstd = rsqrtf(wave_sum(sq) * (1.f / 1024.f) + 1e-5f);
;   const float4 o0 = ln_norm(r.z0, mean, rstd, g.a, b.a), o1 = ln_norm(r.z1, mean, rstd, g.b, b.b), o2 = ln_norm(r.z2, mean, rstd, g.c, b.c), o3 = ln_norm(r.z3, mean, rstd, g.d, b.d);
;   if (OUT16) {
;     u32x4 wa, wb;
;     wa[0] = pkh2(o0.x, o0.y); wa[1] = pkh2(o0.z, o0.w); wa[2] = pkh2(o1.x, o1.y); wa[3] = pkh2(o1.z, o1.w);
;     wb[0] = pkh2(o2.x, o2.y); wb[1] = pkh2(o2.z, o2.w); wb[2] = pkh2(o3.x, o3.y); wb[3] = pkh2(o3.z, o3.w);
;     __builtin_nontemporal_store(wa, (u32x4*)(hout16 + c0));
;     __builtin_nontemporal_store(wb, (u32x4*)(hout16 + 512 + c0));
;   } else {
;     f32x4 v;
;     v[0] = o0.x; v[1] = o0.y; v[2] = o0.z; v[3] = o0.w; __builtin_nontemporal_store(v, (f32x4*)(hout + c0));
;     v[0] = o1.x; v[1] = o1.y; v[2] = o1.z; v[3] = o1.w; __builtin_nontemporal_store(v, (f32x4*)(hout + c0 + 4));
;     v[0] = o2.x; v[1] = o2.y; v[2] = o2.z; v[3] = o2.w; __builtin_nontemporal_store(v, (f32x4*)(hout + 512 + c0));
;     v[0] = o3.x; v[1] = o3.y; v[2] = o3.z; v[3] = o3.w; __builtin_nontemporal_store(v, (f32x4*)(hout + 512 + c0 + 4));
;   }
;   if (wr_u) {
;     uint4 ua, ub;
;     ua.x = umod(o0.x, o0.y, sc.a.x, sc.a.y, sh.a.x, sh.a.y); ua.y = umod(o0.z, o0.w, sc.a.z, sc.a.w, sh.a.z, sh.a.w);
;     ua.z = umod(o1.x, o1.y, sc.b.x, sc.b.y, sh.b.x, sh.b.y); ua.w = umod(o1.z, o1.w, sc.b.z, sc.b.w, sh.b.z, sh.b.w);
;     ub.x = umod(o2.x, o2.y, sc.c.x, sc.c.y, sh.c.x, sh.c.y); ub.y = umod(o2.z, o2.w, sc.c.z, sc.c.w, sh.c.z, sh.c.w);
;     ub.z = umod(o3.x, o3.y, sc.d.x, sc.d.y, sh.d.x, sh.d.y); ub.w = umod(o3.z, o3.w, sc.d.z, sc.d.w, sh.d.z, sh.d.w);
;     *(uint4*)(yu + c0) = ua;
;     *(uint4*)(yu + 512 + c0) = ub;
;   }
	v_pk_add_f32 v[96:97], v[202:203], 1.0 op_sel_hi:[1,0]
	v_pk_add_f32 v[94:95], v[204:205], 1.0 op_sel_hi:[1,0]
	v_lshlrev_b32_e32 v130, 16, v132
	v_and_b32_e32 v131, 0xffff0000, v132
	s_waitcnt lgkmcnt(0)
	v_pk_add_f32 v[136:137], v[136:137], v[138:139]
	s_waitcnt vmcnt(4)
	v_pk_add_f32 v[138:139], v[226:227], 1.0 op_sel_hi:[1,0]
	v_pk_fma_f32 v[202:203], v[136:137], s[20:21], v[148:149] op_sel_hi:[1,0,0]
	v_lshlrev_b32_e32 v132, 16, v133
	v_mul_f32_e32 v136, 0x4b800000, v203
	v_cmp_gt_f32_e32 vcc, s96, v203
	v_and_b32_e32 v133, 0xffff0000, v133
	v_lshlrev_b32_e32 v118, 16, v122
	v_cndmask_b32_e32 v136, v203, v136, vcc
	v_rsq_f32_e32 v194, v136
	v_pk_add_f32 v[136:137], v[228:229], 1.0 op_sel_hi:[1,0]
	v_and_b32_e32 v119, 0xffff0000, v122
	v_lshlrev_b32_e32 v120, 16, v123
	v_mul_f32_e32 v195, 0x45800000, v194
	v_cndmask_b32_e32 v194, v194, v195, vcc
	v_pk_mul_f32 v[182:183], v[182:183], v[194:195] op_sel_hi:[1,0]
	v_pk_mul_f32 v[188:189], v[188:189], v[194:195] op_sel_hi:[1,0]
	v_pk_fma_f32 v[204:205], v[52:53], v[182:183], v[56:57]
	v_pk_mul_f32 v[182:183], v[206:207], v[194:195] op_sel_hi:[1,0]
	v_pk_mul_f32 v[186:187], v[186:187], v[194:195] op_sel_hi:[1,0]
	v_pk_fma_f32 v[206:207], v[42:43], v[182:183], v[46:47]
	v_pk_mul_f32 v[182:183], v[212:213], v[194:195] op_sel_hi:[1,0]
	v_pk_fma_f32 v[196:197], v[58:59], v[188:189], v[62:63]
	v_pk_fma_f32 v[212:213], v[44:45], v[182:183], v[48:49]
	v_pk_mul_f32 v[182:183], v[220:221], v[194:195] op_sel_hi:[1,0]
	v_pk_fma_f32 v[198:199], v[60:61], v[186:187], v[64:65]
	v_pk_mul_f32 v[184:185], v[184:185], v[194:195] op_sel_hi:[1,0]
	v_pk_fma_f32 v[220:221], v[34:35], v[182:183], v[38:39]
	v_pk_mul_f32 v[182:183], v[230:231], v[194:195] op_sel_hi:[1,0]
	v_pk_fma_f32 v[200:201], v[50:51], v[184:185], v[54:55]
	v_pk_fma_f32 v[226:227], v[36:37], v[182:183], v[40:41]
	v_cvt_pk_f16_f32 v182, v196, v197
	v_pk_fma_f32 v[194:195], v[82:83], v[196:197], v[78:79]
	v_pk_fma_f32 v[196:197], v[134:135], v[198:199], v[80:81]
	v_cvt_pk_f16_f32 v183, v198, v199
	v_cvt_pk_bf16_f32 v194, v194, v195
	v_cvt_pk_bf16_f32 v195, v196, v197
	v_pk_fma_f32 v[196:197], v[96:97], v[200:201], v[74:75]
	v_pk_fma_f32 v[198:199], v[94:95], v[204:205], v[76:77]
	v_cvt_pk_f16_f32 v184, v200, v201
	v_cvt_pk_f16_f32 v185, v204, v205
	v_cvt_pk_bf16_f32 v196, v196, v197
	v_cvt_pk_bf16_f32 v197, v198, v199
	s_waitcnt vmcnt(0)
	v_pk_fma_f32 v[198:199], v[84:85], v[206:207], v[90:91]
	v_pk_fma_f32 v[200:201], v[140:141], v[212:213], v[92:93]
	v_cvt_pk_f16_f32 v186, v206, v207
	v_cvt_pk_f16_f32 v187, v212, v213
	v_cvt_pk_f16_f32 v188, v220, v221
	v_cvt_pk_f16_f32 v189, v226, v227
	v_cvt_pk_bf16_f32 v198, v198, v199
	v_cvt_pk_bf16_f32 v199, v200, v201
	v_pk_fma_f32 v[200:201], v[138:139], v[220:221], v[86:87]
	global_store_dwordx4 v0, v[182:185], s[88:89] nt
	global_store_dwordx4 v0, v[186:189], s[88:89] offset:1024 nt
	v_cvt_pk_bf16_f32 v200, v200, v201
	v_pk_fma_f32 v[182:183], v[136:137], v[226:227], v[88:89]
	v_cvt_f32_f16_e32 v184, v72
	v_cvt_pk_bf16_f32 v201, v182, v183
	v_cvt_f32_f16_e32 v182, v73
	v_cvt_f32_f16_sdwa v183, v73 dst_sel:DWORD dst_unused:UNUSED_PAD src0_sel:WORD_1
	v_cvt_f32_f16_sdwa v185, v72 dst_sel:DWORD dst_unused:UNUSED_PAD src0_sel:WORD_1
	v_cvt_f32_f16_e32 v186, v70
	v_cvt_f32_f16_sdwa v187, v70 dst_sel:DWORD dst_unused:UNUSED_PAD src0_sel:WORD_1
	v_pk_mul_f32 v[72:73], v[182:183], s[74:75] op_sel_hi:[1,0]
	v_and_b32_e32 v121, 0xffff0000, v123
	v_pk_fma_f32 v[132:133], v[32:33], v[132:133], v[72:73]
	v_pk_mul_f32 v[72:73], v[184:185], s[74:75] op_sel_hi:[1,0]
	v_cvt_f32_f16_e32 v184, v71
	v_cvt_f32_f16_sdwa v185, v71 dst_sel:DWORD dst_unused:UNUSED_PAD src0_sel:WORD_1
	v_pk_fma_f32 v[182:183], v[30:31], v[130:131], v[72:73]
	v_lshlrev_b32_e32 v122, 16, v124
	v_mov_b32_e32 v72, v183
	v_pk_mul_f32 v[70:71], v[184:185], s[74:75] op_sel_hi:[1,0]
	v_and_b32_e32 v123, 0xffff0000, v124
	v_pk_fma_f32 v[184:185], v[28:29], v[128:129], v[70:71]
	v_pk_mul_f32 v[70:71], v[186:187], s[74:75] op_sel_hi:[1,0]
	v_lshlrev_b32_e32 v124, 16, v125
	v_pk_fma_f32 v[186:187], v[26:27], v[126:127], v[70:71]
	v_cvt_f32_f16_e32 v126, v69
	v_cvt_f32_f16_sdwa v127, v69 dst_sel:DWORD dst_unused:UNUSED_PAD src0_sel:WORD_1
	v_mov_b32_e32 v70, v182
	v_mov_b32_e32 v71, v186
	v_mov_b32_e32 v73, v187
	v_pk_add_f32 v[70:71], v[70:71], v[72:73]
	v_mov_b32_e32 v72, v132
	v_mov_b32_e32 v73, v184
	v_pk_add_f32 v[70:71], v[72:73], v[70:71]
	v_mov_b32_e32 v72, v133
	v_mov_b32_e32 v73, v185
	v_and_b32_e32 v125, 0xffff0000, v125
	v_cvt_f32_f16_e32 v128, v68
	v_cvt_f32_f16_sdwa v129, v68 dst_sel:DWORD dst_unused:UNUSED_PAD src0_sel:WORD_1
	v_pk_add_f32 v[68:69], v[72:73], v[70:71]
	v_pk_mul_f32 v[70:71], v[126:127], s[74:75] op_sel_hi:[1,0]
	v_cvt_f32_f16_e32 v126, v66
	v_pk_fma_f32 v[70:71], v[24:25], v[124:125], v[70:71]
	v_cvt_f32_f16_e32 v124, v67
	v_cvt_f32_f16_sdwa v125, v67 dst_sel:DWORD dst_unused:UNUSED_PAD src0_sel:WORD_1
	v_cvt_f32_f16_sdwa v127, v66 dst_sel:DWORD dst_unused:UNUSED_PAD src0_sel:WORD_1
	v_pk_mul_f32 v[72:73], v[128:129], s[74:75] op_sel_hi:[1,0]
	v_cmp_gt_f32_e32 vcc, s96, v202
	v_pk_mul_f32 v[66:67], v[124:125], s[74:75] op_sel_hi:[1,0]
	v_pk_fma_f32 v[72:73], v[22:23], v[122:123], v[72:73]
	v_pk_fma_f32 v[188:189], v[20:21], v[120:121], v[66:67]
	v_pk_mul_f32 v[66:67], v[126:127], s[74:75] op_sel_hi:[1,0]
	v_mov_b32_e32 v121, v73
	v_pk_fma_f32 v[118:119], v[18:19], v[118:119], v[66:67]
	v_mov_b32_e32 v67, v72
	v_mov_b32_e32 v66, v118
	v_mov_b32_e32 v120, v119
	v_pk_add_f32 v[66:67], v[66:67], v[120:121]
	v_mov_b32_e32 v120, v188
	v_mov_b32_e32 v121, v70
	v_pk_add_f32 v[66:67], v[120:121], v[66:67]
	v_mov_b32_e32 v120, v189
	v_mov_b32_e32 v121, v71
	v_pk_add_f32 v[66:67], v[120:121], v[66:67]
	global_store_dwordx4 v0, v[194:197], s[14:15]
	v_add_f32_e32 v66, v66, v67
	v_add_f32_e32 v66, v66, v69
	v_add_f32_e32 v66, v68, v66
	v_mov_b32_e32 v67, v66
	s_nop 1
	v_permlane32_swap_b32_e32 v67, v66
	v_mul_f32_e32 v68, 0x4b800000, v202
	v_cndmask_b32_e32 v68, v202, v68, vcc
	v_rsq_f32_e32 v68, v68
	global_store_dwordx4 v0, v[198:201], s[14:15] offset:1024
	s_waitcnt lgkmcnt(0)
; DI float wave_sum(float v) {
; #pragma unroll
;   for (int o = 32; o > 0; o >>= 1) v += __shfl_xor(v, o);
;   return v;
; template <bool OUT16>
; DI void ln_finish(const LnRow& r, float* hout, unsigned short* hout16, bf16_t* yu, const LnVec& g, const LnVec& b, const LnVec& sc, const LnVec& sh, int c0, bool wr_u) {
;   const float sum = (r.z0.x + r.z0.y + r.z0.z + r.z0.w) + (r.z1.x + r.z1.y + r.z1.z + r.z1.w) + (r.z2.x + r.z2.y + r.z2.z + r.z2.w) + (r.z3.x + r.z3.y + r.z3.z + r.z3.w);
;   const float mean = wave_sum(sum) * (1.f / 1024.f);
;   const float sq = sq4(r.z0, mean) + sq4(r.z1, mean) + sq4(r.z2, mean) + sq4(r.z3, mean);
;   const float rstd = rsqrtf(wave_sum(sq) * (1.f / 1024.f) + 1e-5f);
;   const float4 o0 = ln_norm(r.z0, mean, rstd, g.a, b.a), o1 = ln_norm(r.z1, mean, rstd, g.b, b.b), o2 = ln_norm(r.z2, mean, rstd, g.c, b.c), o3 = ln_norm(r.z3, mean, rstd, g.d, b.d);
;   if (OUT16) {
;     u32x4 wa, wb;
;     wa[0] = pkh2(o0.x, o0.y); wa[1] = pkh2(o0.z, o0.w); wa[2] = pkh2(o1.x, o1.y); wa[3] = pkh2(o1.z, o1.w);
;     wb[0] = pkh2(o2.x, o2.y); wb[1] = pkh2(o2.z, o2.w); wb[2] = pkh2(o3.x, o3.y); wb[3] = pkh2(o3.z, o3.w);
;     __builtin_nontemporal_store(wa, (u32x4*)(hout16 + c0));
;     __builtin_nontemporal_store(wb, (u32x4*)(hout16 + 512 + c0));
;   } else {
;     f32x4 v;
;     v[0] = o0.x; v[1] = o0.y; v[2] = o0.z; v[3] = o0.w; __builtin_nontemporal_store(v, (f32x4*)(hout + c0));
;     v[0] = o1.x; v[1] = o1.y; v[2] = o1.z; v[3] = o1.w; __builtin_nontemporal_store(v, (f32x4*)(hout + c0 + 4));
;     v[0] = o2.x; v[1] = o2.y; v[2] = o2.z; v[3] = o2.w; __builtin_nontemporal_store(v, (f32x4*)(hout + 512 + c0));
;     v[0] = o3.x; v[1] = o3.y; v[2] = o3.z; v[3] = o3.w; __builtin_nontemporal_store(v, (f32x4*)(hout + 512 + c0 + 4));
;   }
;   if (wr_u) {
;     uint4 ua, ub;
;     ua.x = umod(o0.x, o0.y, sc.a.x, sc.a.y, sh.a.x, sh.a.y); ua.y = umod(o0.z, o0.w, sc.a.z, sc.a.w, sh.a.z, sh.a.w);
;     ua.z = umod(o1.x, o1.y, sc.b.x, sc.b.y, sh.b.x, sh.b.y); ua.w = umod(o1.z, o1.w, sc.b.z, sc.b.w, sh.b.z, sh.b.w);
;     ub.x = umod(o2.x, o2.y, sc.c.x, sc.c.y, sh.c.x, sh.c.y); ub.y = umod(o2.z, o2.w, sc.c.z, sc.c.w, sh.c.z, sh.c.w);
;     ub.z = umod(o3.x, o3.y, sc.d.x, sc.d.y, sh.d.x, sh.d.y); ub.w = umod(o3.z, o3.w, sc.d.z, sc.d.w, sh.d.z, sh.d.w);
;     *(uint4*)(yu + c0) = ua;
;     *(uint4*)(yu + 512 + c0) = ub;
;   }
; }
	v_add_f32_e32 v67, v66, v67
	v_mov_b32_e32 v120, v67
	s_nop 1
	v_permlane16_swap_b32_e32 v120, v67
	v_mul_f32_e32 v66, 0x45800000, v68
	v_cndmask_b32_e32 v66, v68, v66, vcc
	v_pk_mul_f32 v[68:69], v[170:171], v[66:67] op_sel_hi:[1,0]
	s_mov_b64 s[88:89], 0x1000
	s_waitcnt lgkmcnt(0)
	v_add_f32_e32 v67, v67, v120
	s_nop 1
	v_mov_b32_dpp v120, v67 row_ror:8 row_mask:0xf bank_mask:0xf
	v_pk_fma_f32 v[170:171], v[58:59], v[68:69], v[62:63]
	v_pk_mul_f32 v[68:69], v[168:169], v[66:67] op_sel_hi:[1,0]
	s_nop 0
	v_pk_fma_f32 v[168:169], v[60:61], v[68:69], v[64:65]
	v_pk_mul_f32 v[68:69], v[166:167], v[66:67] op_sel_hi:[1,0]
	s_waitcnt lgkmcnt(0)
	v_add_f32_e32 v67, v67, v120
	s_nop 1
	v_mov_b32_dpp v120, v67 row_ror:4 row_mask:0xf bank_mask:0xf
	v_pk_fma_f32 v[130:131], v[50:51], v[68:69], v[54:55]
	v_pk_mul_f32 v[68:69], v[164:165], v[66:67] op_sel_hi:[1,0]
	s_nop 0
	v_pk_fma_f32 v[164:165], v[52:53], v[68:69], v[56:57]
	v_pk_mul_f32 v[68:69], v[178:179], v[66:67] op_sel_hi:[1,0]
	s_waitcnt lgkmcnt(0)
	v_add_f32_e32 v67, v67, v120
	v_pk_fma_f32 v[126:127], v[42:43], v[68:69], v[46:47]
	v_pk_mul_f32 v[68:69], v[176:177], v[66:67] op_sel_hi:[1,0]
	v_cvt_f32_f16_e32 v176, v104
	v_pk_fma_f32 v[128:129], v[44:45], v[68:69], v[48:49]
	v_pk_mul_f32 v[68:69], v[174:175], v[66:67] op_sel_hi:[1,0]
	v_cvt_f32_f16_e32 v174, v105
	v_cvt_f32_f16_sdwa v175, v105 dst_sel:DWORD dst_unused:UNUSED_PAD src0_sel:WORD_1
	v_cvt_f32_f16_sdwa v177, v104 dst_sel:DWORD dst_unused:UNUSED_PAD src0_sel:WORD_1
	v_cvt_f32_f16_e32 v178, v102
	v_cvt_f32_f16_sdwa v179, v102 dst_sel:DWORD dst_unused:UNUSED_PAD src0_sel:WORD_1
	v_pk_mul_f32 v[104:105], v[174:175], s[74:75] op_sel_hi:[1,0]
	v_pk_mul_f32 v[174:175], v[176:177], s[74:75] op_sel_hi:[1,0]
	v_cvt_f32_f16_e32 v176, v103
	v_cvt_f32_f16_sdwa v177, v103 dst_sel:DWORD dst_unused:UNUSED_PAD src0_sel:WORD_1
	v_pk_fma_f32 v[102:103], v[30:31], v[162:163], v[174:175]
	v_pk_fma_f32 v[104:105], v[32:33], v[180:181], v[104:105]
	v_mov_b32_e32 v174, v103
	v_pk_mul_f32 v[162:163], v[176:177], s[74:75] op_sel_hi:[1,0]
	v_cvt_f32_f16_e32 v176, v101
	v_pk_fma_f32 v[160:161], v[28:29], v[160:161], v[162:163]
	v_pk_mul_f32 v[162:163], v[178:179], s[74:75] op_sel_hi:[1,0]
	v_cvt_f32_f16_sdwa v177, v101 dst_sel:DWORD dst_unused:UNUSED_PAD src0_sel:WORD_1
	v_pk_fma_f32 v[158:159], v[26:27], v[158:159], v[162:163]
	v_mov_b32_e32 v162, v102
	v_mov_b32_e32 v163, v158
	v_mov_b32_e32 v175, v159
	v_pk_add_f32 v[162:163], v[162:163], v[174:175]
	v_mov_b32_e32 v174, v104
	v_mov_b32_e32 v175, v160
	s_nop 1
	v_mov_b32_dpp v120, v67 quad_perm:[2,3,0,1] row_mask:0xf bank_mask:0xf
	v_pk_add_f32 v[162:163], v[174:175], v[162:163]
	v_mov_b32_e32 v174, v105
	v_mov_b32_e32 v175, v161
	v_cvt_f32_f16_e32 v178, v100
	v_cvt_f32_f16_sdwa v179, v100 dst_sel:DWORD dst_unused:UNUSED_PAD src0_sel:WORD_1
	v_pk_add_f32 v[100:101], v[174:175], v[162:163]
	v_cvt_f32_f16_e32 v174, v99
	v_cvt_f32_f16_sdwa v175, v99 dst_sel:DWORD dst_unused:UNUSED_PAD src0_sel:WORD_1
	v_pk_mul_f32 v[162:163], v[176:177], s[74:75] op_sel_hi:[1,0]
	v_cvt_f32_f16_e32 v176, v98
	v_cvt_f32_f16_sdwa v177, v98 dst_sel:DWORD dst_unused:UNUSED_PAD src0_sel:WORD_1
	v_pk_fma_f32 v[156:157], v[24:25], v[156:157], v[162:163]
	v_pk_mul_f32 v[162:163], v[178:179], s[74:75] op_sel_hi:[1,0]
	s_waitcnt lgkmcnt(0)
	v_add_f32_e32 v120, v67, v120
	v_pk_fma_f32 v[98:99], v[22:23], v[154:155], v[162:163]
	v_pk_mul_f32 v[154:155], v[174:175], s[74:75] op_sel_hi:[1,0]
	s_nop 1
	v_mov_b32_dpp v121, v120 quad_perm:[1,0,3,2] row_mask:0xf bank_mask:0xf
	v_pk_fma_f32 v[152:153], v[20:21], v[152:153], v[154:155]
	v_pk_mul_f32 v[154:155], v[176:177], s[74:75] op_sel_hi:[1,0]
	v_mov_b32_e32 v163, v99
	v_pk_fma_f32 v[150:151], v[18:19], v[150:151], v[154:155]
	v_mov_b32_e32 v155, v98
	v_mov_b32_e32 v154, v150
	v_mov_b32_e32 v162, v151
	v_pk_add_f32 v[154:155], v[154:155], v[162:163]
	v_mov_b32_e32 v162, v152
	v_mov_b32_e32 v163, v156
	v_pk_mul_f32 v[66:67], v[172:173], v[66:67] op_sel_hi:[1,0]
	v_pk_add_f32 v[154:155], v[162:163], v[154:155]
	v_mov_b32_e32 v162, v153
	v_mov_b32_e32 v163, v157
	v_pk_fma_f32 v[124:125], v[36:37], v[66:67], v[40:41]
	s_waitcnt lgkmcnt(0)
	v_add_f32_e32 v67, v120, v121
	v_pk_add_f32 v[154:155], v[162:163], v[154:155]
	v_pk_fma_f32 v[122:123], v[34:35], v[68:69], v[38:39]
	v_mul_f32_e32 v68, 0x3a800000, v67
	v_add_f32_e32 v67, v154, v155
	v_add_f32_e32 v67, v67, v101
	v_add_f32_e32 v67, v100, v67
	v_pk_add_f32 v[120:121], v[118:119], v[68:69] op_sel_hi:[1,0] neg_lo:[0,1] neg_hi:[0,1]
	v_pk_add_f32 v[118:119], v[188:189], v[68:69] op_sel_hi:[1,0] neg_lo:[0,1] neg_hi:[0,1]
	v_pk_add_f32 v[72:73], v[72:73], v[68:69] op_sel_hi:[1,0] neg_lo:[0,1] neg_hi:[0,1]
	v_pk_add_f32 v[70:71], v[70:71], v[68:69] op_sel_hi:[1,0] neg_lo:[0,1] neg_hi:[0,1]
	v_mov_b32_e32 v69, v67
	s_nop 1
	v_permlane32_swap_b32_e32 v69, v67
	v_mov_b32_e32 v172, v121
	v_mov_b32_e32 v173, v73
	v_mov_b32_e32 v166, v120
	v_mov_b32_e32 v167, v72
	s_waitcnt lgkmcnt(0)
	v_add_f32_e32 v67, v67, v69
	v_mov_b32_e32 v69, v67
	s_nop 1
	v_permlane16_swap_b32_e32 v69, v67
	v_pk_mul_f32 v[100:101], v[172:173], v[172:173]
	v_mov_b32_e32 v154, v118
	v_pk_fma_f32 v[100:101], v[166:167], v[166:167], v[100:101]
	v_mov_b32_e32 v155, v70
	s_waitcnt lgkmcnt(0)
	v_add_f32_e32 v67, v67, v69
	s_nop 1
	v_mov_b32_dpp v69, v67 row_ror:8 row_mask:0xf bank_mask:0xf
	v_pk_fma_f32 v[100:101], v[154:155], v[154:155], v[100:101]
	v_mov_b32_e32 v154, v119
	v_mov_b32_e32 v155, v71
	v_pk_fma_f32 v[100:101], v[154:155], v[154:155], v[100:101]
	s_waitcnt lgkmcnt(0)
; DI unsigned pkh2(float lo, float hi) { f32x2 v = {lo, hi}; return __builtin_bit_cast(unsigned, __builtin_convertvector(v, h16x2)); }
; DI float wave_sum(float v) {
; #pragma unroll
;   for (int o = 32; o > 0; o >>= 1) v += __shfl_xor(v, o);
;   return v;
; template <bool OUT16>
; DI void ln_finish(const LnRow& r, float* hout, unsigned short* hout16, bf16_t* yu, const LnVec& g, const LnVec& b, const LnVec& sc, const LnVec& sh, int c0, bool wr_u) {
;     ...
;   const float mean = wave_sum(sum) * (1.f / 1024.f);
;   const float sq = sq4(r.z0, mean) + sq4(r.z1, mean) + sq4(r.z2, mean) + sq4(r.z3, mean);
;   const float rstd = rsqrtf(wave_sum(sq) * (1.f / 1024.f) + 1e-5f);
;   const float4 o0 = ln_norm(r.z0, mean, rstd, g.a, b.a), o1 = ln_norm(r.z1, mean, rstd, g.b, b.b), o2 = ln_norm(r.z2, mean, rstd, g.c, b.c), o3 = ln_norm(r.z3, mean, rstd, g.d, b.d);
;   if (OUT16) {
;     u32x4 wa, wb;
;     wa[0] = pkh2(o0.x, o0.y); wa[1] = pkh2(o0.z, o0.w); wa[2] = pkh2(o1.x, o1.y); wa[3] = pkh2(o1.z, o1.w);
;     wb[0] = pkh2(o2.x, o2.y); wb[1] = pkh2(o2.z, o2.w); wb[2] = pkh2(o3.x, o3.y); wb[3] = pkh2(o3.z, o3.w);
;     __builtin_nontemporal_store(wa, (u32x4*)(hout16 + c0));
;     __builtin_nontemporal_store(wb, (u32x4*)(hout16 + 512 + c0));
;   } else {
;     f32x4 v;
;     v[0] = o0.x; v[1] = o0.y; v[2] = o0.z; v[3] = o0.w; __builtin_nontemporal_store(v, (f32x4*)(hout + c0));
;     v[0] = o1.x; v[1] = o1.y; v[2] = o1.z; v[3] = o1.w; __builtin_nontemporal_store(v, (f32x4*)(hout + c0 + 4));
;     v[0] = o2.x; v[1] = o2.y; v[2] = o2.z; v[3] = o2.w; __builtin_nontemporal_store(v, (f32x4*)(hout + 512 + c0));
;     v[0] = o3.x; v[1] = o3.y; v[2] = o3.z; v[3] = o3.w; __builtin_nontemporal_store(v, (f32x4*)(hout + 512 + c0 + 4));
;   }
;   if (wr_u) {
;     uint4 ua, ub;
;     ua.x = umod(o0.x, o0.y, sc.a.x, sc.a.y, sh.a.x, sh.a.y); ua.y = umod(o0.z, o0.w, sc.a.z, sc.a.w, sh.a.z, sh.a.w);
;     ua.z = umod(o1.x, o1.y, sc.b.x, sc.b.y, sh.b.x, sh.b.y); ua.w = umod(o1.z, o1.w, sc.b.z, sc.b.w, sh.b.z, sh.b.w);
;     ub.x = umod(o2.x, o2.y, sc.c.x, sc.c.y, sh.c.x, sh.c.y); ub.y = umod(o2.z, o2.w, sc.c.z, sc.c.w, sh.c.z, sh.c.w);
;     ub.z = umod(o3.x, o3.y, sc.d.x, sc.d.y, sh.d.x, sh.d.y); ub.w = umod(o3.z, o3.w, sc.d.z, sc.d.w, sh.d.z, sh.d.w);
;     *(uint4*)(yu + c0) = ua;
;     *(uint4*)(yu + 512 + c0) = ub;
;   }
	v_add_f32_e32 v67, v67, v69
	s_nop 1
	v_mov_b32_dpp v174, v67 row_ror:4 row_mask:0xf bank_mask:0xf
	v_pk_add_f32 v[154:155], v[186:187], v[68:69] op_sel_hi:[1,0] neg_lo:[0,1] neg_hi:[0,1]
	v_pk_add_f32 v[166:167], v[182:183], v[68:69] op_sel_hi:[1,0] neg_lo:[0,1] neg_hi:[0,1]
	v_mov_b32_e32 v173, v155
	v_mov_b32_e32 v172, v167
	s_waitcnt lgkmcnt(0)
	v_add_f32_e32 v67, v67, v174
	s_nop 1
	v_mov_b32_dpp v174, v67 quad_perm:[2,3,0,1] row_mask:0xf bank_mask:0xf
	v_pk_add_f32 v[162:163], v[184:185], v[68:69] op_sel_hi:[1,0] neg_lo:[0,1] neg_hi:[0,1]
	v_pk_add_f32 v[132:133], v[132:133], v[68:69] op_sel_hi:[1,0] neg_lo:[0,1] neg_hi:[0,1]
	v_mov_b32_e32 v68, v166
	v_mov_b32_e32 v69, v154
	s_waitcnt lgkmcnt(0)
	v_add_f32_e32 v67, v67, v174
	s_nop 1
	v_mov_b32_dpp v174, v67 quad_perm:[1,0,3,2] row_mask:0xf bank_mask:0xf
	v_pk_mul_f32 v[172:173], v[172:173], v[172:173]
	v_cvt_pk_f16_f32 v66, v170, v171
	v_pk_fma_f32 v[68:69], v[68:69], v[68:69], v[172:173]
	v_mov_b32_e32 v172, v132
	v_mov_b32_e32 v173, v162
	v_pk_fma_f32 v[68:69], v[172:173], v[172:173], v[68:69]
	v_mov_b32_e32 v172, v133
	v_mov_b32_e32 v173, v163
	s_waitcnt lgkmcnt(0)
	v_add_f32_e32 v67, v67, v174
	v_pk_fma_f32 v[68:69], v[172:173], v[172:173], v[68:69]
	v_mul_f32_e32 v172, 0x3a800000, v67
	v_pk_add_f32 v[150:151], v[150:151], v[172:173] op_sel_hi:[1,0] neg_lo:[0,1] neg_hi:[0,1]
	v_pk_add_f32 v[174:175], v[98:99], v[172:173] op_sel_hi:[1,0] neg_lo:[0,1] neg_hi:[0,1]
	v_mov_b32_e32 v176, v151
	v_mov_b32_e32 v177, v175
	v_pk_add_f32 v[152:153], v[152:153], v[172:173] op_sel_hi:[1,0] neg_lo:[0,1] neg_hi:[0,1]
	v_pk_add_f32 v[156:157], v[156:157], v[172:173] op_sel_hi:[1,0] neg_lo:[0,1] neg_hi:[0,1]
	v_mov_b32_e32 v98, v150
	v_mov_b32_e32 v99, v174
	v_pk_mul_f32 v[176:177], v[176:177], v[176:177]
	v_pk_add_f32 v[158:159], v[158:159], v[172:173] op_sel_hi:[1,0] neg_lo:[0,1] neg_hi:[0,1]
	v_pk_fma_f32 v[98:99], v[98:99], v[98:99], v[176:177]
	v_mov_b32_e32 v176, v152
	v_mov_b32_e32 v177, v156
	v_pk_fma_f32 v[98:99], v[176:177], v[176:177], v[98:99]
	v_mov_b32_e32 v176, v153
	v_mov_b32_e32 v177, v157
	v_pk_add_f32 v[102:103], v[102:103], v[172:173] op_sel_hi:[1,0] neg_lo:[0,1] neg_hi:[0,1]
	v_pk_fma_f32 v[98:99], v[176:177], v[176:177], v[98:99]
	v_mov_b32_e32 v176, v103
	v_mov_b32_e32 v177, v159
	v_pk_add_f32 v[160:161], v[160:161], v[172:173] op_sel_hi:[1,0] neg_lo:[0,1] neg_hi:[0,1]
	v_pk_add_f32 v[104:105], v[104:105], v[172:173] op_sel_hi:[1,0] neg_lo:[0,1] neg_hi:[0,1]
	v_mov_b32_e32 v172, v102
	v_mov_b32_e32 v173, v158
	v_pk_mul_f32 v[176:177], v[176:177], v[176:177]
	v_cvt_pk_f16_f32 v67, v168, v169
	v_pk_fma_f32 v[172:173], v[172:173], v[172:173], v[176:177]
	v_mov_b32_e32 v176, v104
	v_mov_b32_e32 v177, v160
	v_pk_fma_f32 v[172:173], v[176:177], v[176:177], v[172:173]
	v_mov_b32_e32 v176, v105
	v_mov_b32_e32 v177, v161
	v_pk_fma_f32 v[172:173], v[176:177], v[176:177], v[172:173]
	v_mov_b32_e32 v176, v98
	v_mov_b32_e32 v177, v100
	v_mov_b32_e32 v100, v99
	v_pk_add_f32 v[98:99], v[176:177], v[100:101]
	v_mov_b32_e32 v100, v173
	v_mov_b32_e32 v101, v69
	v_pk_add_f32 v[98:99], v[100:101], v[98:99]
	v_mov_b32_e32 v173, v68
	v_pk_add_f32 v[100:101], v[172:173], v[98:99]
	v_mov_b32_e32 v173, v101
	s_nop 1
	v_permlane32_swap_b32_e32 v173, v101
	v_mov_b32_e32 v172, v100
	s_nop 1
	v_permlane32_swap_b32_e32 v172, v100
	v_cvt_pk_f16_f32 v68, v130, v131
	v_cvt_pk_f16_f32 v69, v164, v165
	global_store_dwordx4 v0, v[66:69], s[18:19] nt
	v_cvt_pk_f16_f32 v98, v126, v127
	s_waitcnt lgkmcnt(0)
	v_pk_add_f32 v[172:173], v[100:101], v[172:173]
	v_mov_b32_e32 v177, v173
	s_nop 1
	v_permlane16_swap_b32_e32 v177, v173
	v_mov_b32_e32 v176, v172
	s_nop 1
	v_permlane16_swap_b32_e32 v176, v172
	v_cvt_pk_f16_f32 v99, v128, v129
	v_cvt_pk_f16_f32 v100, v122, v123
	v_cvt_pk_f16_f32 v101, v124, v125
	global_store_dwordx4 v0, v[98:101], s[18:19] offset:1024 nt
	s_waitcnt lgkmcnt(0)
	v_pk_add_f32 v[68:69], v[172:173], v[176:177]
	s_nop 1
	v_mov_b32_dpp v173, v69 row_ror:8 row_mask:0xf bank_mask:0xf
	s_nop 1
	v_mov_b32_dpp v172, v68 row_ror:8 row_mask:0xf bank_mask:0xf
	v_pk_fma_f32 v[98:99], v[134:135], v[168:169], v[80:81]
	v_pk_fma_f32 v[66:67], v[82:83], v[170:171], v[78:79]
	s_waitcnt lgkmcnt(0)
	v_pk_add_f32 v[100:101], v[68:69], v[172:173]
	s_nop 1
	v_mov_b32_dpp v169, v101 row_ror:4 row_mask:0xf bank_mask:0xf
	s_nop 1
	v_mov_b32_dpp v168, v100 row_ror:4 row_mask:0xf bank_mask:0xf
	v_pk_fma_f32 v[68:69], v[96:97], v[130:131], v[74:75]
	v_cvt_pk_bf16_f32 v66, v66, v67
	v_cvt_pk_bf16_f32 v67, v98, v99
	v_pk_fma_f32 v[98:99], v[94:95], v[164:165], v[76:77]
	s_waitcnt lgkmcnt(0)
	v_pk_add_f32 v[100:101], v[100:101], v[168:169]
	s_nop 1
	v_mov_b32_dpp v131, v101 quad_perm:[2,3,0,1] row_mask:0xf bank_mask:0xf
	s_nop 1
	v_mov_b32_dpp v130, v100 quad_perm:[2,3,0,1] row_mask:0xf bank_mask:0xf
	v_cvt_pk_bf16_f32 v68, v68, v69
	v_cvt_pk_bf16_f32 v69, v98, v99
	v_pk_fma_f32 v[98:99], v[84:85], v[126:127], v[90:91]
	v_pk_fma_f32 v[126:127], v[140:141], v[128:129], v[92:93]
	s_waitcnt lgkmcnt(0)
	v_pk_add_f32 v[128:129], v[100:101], v[130:131]
	s_nop 1
	v_mov_b32_dpp v131, v129 quad_perm:[1,0,3,2] row_mask:0xf bank_mask:0xf
	s_nop 1
	v_mov_b32_dpp v130, v128 quad_perm:[1,0,3,2] row_mask:0xf bank_mask:0xf
	v_pk_fma_f32 v[100:101], v[138:139], v[122:123], v[86:87]
	v_pk_fma_f32 v[122:123], v[136:137], v[124:125], v[88:89]
	v_cvt_pk_bf16_f32 v100, v100, v101
	v_cvt_pk_bf16_f32 v98, v98, v99
	s_waitcnt lgkmcnt(0)
; DI unsigned pkh2(float lo, float hi) { f32x2 v = {lo, hi}; return __builtin_bit_cast(unsigned, __builtin_convertvector(v, h16x2)); }
; DI unsigned umod(float a, float b, float sca, float scb, float sha, float shb) { return pk2(a * (1.f + sca) + sha, b * (1.f + scb) + shb); }
; template <bool OUT16>
; DI void ln_finish(const LnRow& r, float* hout, unsigned short* hout16, bf16_t* yu, const LnVec& g, const LnVec& b, const LnVec& sc, const LnVec& sh, int c0, bool wr_u) {
;     ...
;   const float rstd = rsqrtf(wave_sum(sq) * (1.f / 1024.f) + 1e-5f);
;   const float4 o0 = ln_norm(r.z0, mean, rstd, g.a, b.a), o1 = ln_norm(r.z1, mean, rstd, g.b, b.b), o2 = ln_norm(r.z2, mean, rstd, g.c, b.c), o3 = ln_norm(r.z3, mean, rstd, g.d, b.d);
;   if (OUT16) {
;     u32x4 wa, wb;
;     wa[0] = pkh2(o0.x, o0.y); wa[1] = pkh2(o0.z, o0.w); wa[2] = pkh2(o1.x, o1.y); wa[3] = pkh2(o1.z, o1.w);
;     wb[0] = pkh2(o2.x, o2.y); wb[1] = pkh2(o2.z, o2.w); wb[2] = pkh2(o3.x, o3.y); wb[3] = pkh2(o3.z, o3.w);
;     __builtin_nontemporal_store(wa, (u32x4*)(hout16 + c0));
;     __builtin_nontemporal_store(wb, (u32x4*)(hout16 + 512 + c0));
;   } else {
;     f32x4 v;
;     v[0] = o0.x; v[1] = o0.y; v[2] = o0.z; v[3] = o0.w; __builtin_nontemporal_store(v, (f32x4*)(hout + c0));
;     v[0] = o1.x; v[1] = o1.y; v[2] = o1.z; v[3] = o1.w; __builtin_nontemporal_store(v, (f32x4*)(hout + c0 + 4));
;     v[0] = o2.x; v[1] = o2.y; v[2] = o2.z; v[3] = o2.w; __builtin_nontemporal_store(v, (f32x4*)(hout + 512 + c0));
;     v[0] = o3.x; v[1] = o3.y; v[2] = o3.z; v[3] = o3.w; __builtin_nontemporal_store(v, (f32x4*)(hout + 512 + c0 + 4));
;   }
;   if (wr_u) {
;     uint4 ua, ub;
;     ua.x = umod(o0.x, o0.y, sc.a.x, sc.a.y, sh.a.x, sh.a.y); ua.y = umod(o0.z, o0.w, sc.a.z, sc.a.w, sh.a.z, sh.a.w);
;     ua.z = umod(o1.x, o1.y, sc.b.x, sc.b.y, sh.b.x, sh.b.y); ua.w = umod(o1.z, o1.w, sc.b.z, sc.b.w, sh.b.z, sh.b.w);
;     ub.x = umod(o2.x, o2.y, sc.c.x, sc.c.y, sh.c.x, sh.c.y); ub.y = umod(o2.z, o2.w, sc.c.z, sc.c.w, sh.c.z, sh.c.w);
;     ub.z = umod(o3.x, o3.y, sc.d.x, sc.d.y, sh.d.x, sh.d.y); ub.w = umod(o3.z, o3.w, sc.d.z, sc.d.w, sh.d.z, sh.d.w);
;     *(uint4*)(yu + c0) = ua;
;     *(uint4*)(yu + 512 + c0) = ub;
;   }
	v_pk_add_f32 v[124:125], v[128:129], v[130:131]
	v_cvt_pk_bf16_f32 v99, v126, v127
	v_pk_fma_f32 v[124:125], v[124:125], s[20:21], v[148:149] op_sel_hi:[1,0,0]
	s_nop 0
	v_mul_f32_e32 v101, 0x4b800000, v125
	v_cmp_gt_f32_e32 vcc, s96, v125
	s_nop 1
	v_cndmask_b32_e32 v101, v125, v101, vcc
	v_rsq_f32_e32 v107, v101
	v_cvt_pk_bf16_f32 v101, v122, v123
	global_store_dwordx4 v0, v[66:69], s[14:15] offset:2048
	global_store_dwordx4 v0, v[98:101], s[14:15] offset:3072
	s_nop 0
	v_mul_f32_e32 v66, 0x45800000, v107
	v_cndmask_b32_e32 v66, v107, v66, vcc
	v_pk_mul_f32 v[68:69], v[120:121], v[66:67] op_sel_hi:[1,0]
	v_cmp_gt_f32_e32 vcc, s96, v124
	v_pk_fma_f32 v[98:99], v[58:59], v[68:69], v[62:63]
	v_pk_mul_f32 v[68:69], v[118:119], v[66:67] op_sel_hi:[1,0]
	s_nop 0
	v_pk_fma_f32 v[100:101], v[60:61], v[68:69], v[64:65]
	v_pk_mul_f32 v[68:69], v[72:73], v[66:67] op_sel_hi:[1,0]
	s_nop 0
	v_pk_fma_f32 v[118:119], v[50:51], v[68:69], v[54:55]
	v_pk_mul_f32 v[68:69], v[70:71], v[66:67] op_sel_hi:[1,0]
	s_nop 0
	v_pk_fma_f32 v[120:121], v[52:53], v[68:69], v[56:57]
	v_pk_mul_f32 v[68:69], v[154:155], v[66:67] op_sel_hi:[1,0]
	s_nop 0
	v_pk_fma_f32 v[122:123], v[42:43], v[68:69], v[46:47]
	v_pk_mul_f32 v[68:69], v[162:163], v[66:67] op_sel_hi:[1,0]
	v_cvt_pk_f16_f32 v70, v122, v123
	v_pk_fma_f32 v[126:127], v[44:45], v[68:69], v[48:49]
	v_pk_mul_f32 v[68:69], v[166:167], v[66:67] op_sel_hi:[1,0]
	v_pk_mul_f32 v[66:67], v[132:133], v[66:67] op_sel_hi:[1,0]
	v_pk_fma_f32 v[128:129], v[34:35], v[68:69], v[38:39]
	v_pk_fma_f32 v[130:131], v[36:37], v[66:67], v[40:41]
	v_cvt_pk_f16_f32 v66, v98, v99
	v_cvt_pk_f16_f32 v67, v100, v101
	v_cvt_pk_f16_f32 v68, v118, v119
	v_cvt_pk_f16_f32 v69, v120, v121
	v_cvt_pk_f16_f32 v71, v126, v127
	v_cvt_pk_f16_f32 v72, v128, v129
	v_cvt_pk_f16_f32 v73, v130, v131
	global_store_dwordx4 v0, v[66:69], s[16:17] nt
	global_store_dwordx4 v0, v[70:73], s[16:17] offset:1024 nt
	s_nop 0
	v_pk_fma_f32 v[66:67], v[82:83], v[98:99], v[78:79]
	v_pk_fma_f32 v[68:69], v[134:135], v[100:101], v[80:81]
	v_cvt_pk_bf16_f32 v66, v66, v67
	v_cvt_pk_bf16_f32 v67, v68, v69
	v_pk_fma_f32 v[68:69], v[96:97], v[118:119], v[74:75]
	v_pk_fma_f32 v[70:71], v[94:95], v[120:121], v[76:77]
	v_cvt_pk_bf16_f32 v68, v68, v69
	v_cvt_pk_bf16_f32 v69, v70, v71
	v_pk_fma_f32 v[70:71], v[84:85], v[122:123], v[90:91]
	v_pk_fma_f32 v[72:73], v[140:141], v[126:127], v[92:93]
	v_cvt_pk_bf16_f32 v70, v70, v71
	v_cvt_pk_bf16_f32 v71, v72, v73
	v_pk_fma_f32 v[72:73], v[138:139], v[128:129], v[86:87]
	v_pk_fma_f32 v[98:99], v[136:137], v[130:131], v[88:89]
	v_cvt_pk_bf16_f32 v72, v72, v73
	v_mul_f32_e32 v73, 0x4b800000, v124
	v_cndmask_b32_e32 v73, v124, v73, vcc
	v_rsq_f32_e32 v100, v73
	v_cvt_pk_bf16_f32 v73, v98, v99
	global_store_dwordx4 v[116:117], v[66:69], off
	global_store_dwordx4 v[116:117], v[70:73], off offset:1024
	s_nop 0
	v_mul_f32_e32 v66, 0x45800000, v100
	v_cndmask_b32_e32 v66, v100, v66, vcc
	v_pk_mul_f32 v[68:69], v[150:151], v[66:67] op_sel_hi:[1,0]
	s_nop 0
	v_pk_fma_f32 v[58:59], v[58:59], v[68:69], v[62:63]
	v_pk_mul_f32 v[62:63], v[152:153], v[66:67] op_sel_hi:[1,0]
	s_nop 0
	v_pk_fma_f32 v[60:61], v[60:61], v[62:63], v[64:65]
	v_pk_mul_f32 v[62:63], v[174:175], v[66:67] op_sel_hi:[1,0]
	s_nop 0
	v_pk_fma_f32 v[50:51], v[50:51], v[62:63], v[54:55]
	v_pk_mul_f32 v[54:55], v[156:157], v[66:67] op_sel_hi:[1,0]
	s_nop 0
	v_pk_fma_f32 v[52:53], v[52:53], v[54:55], v[56:57]
	v_pk_mul_f32 v[54:55], v[158:159], v[66:67] op_sel_hi:[1,0]
	s_nop 0
	v_pk_fma_f32 v[42:43], v[42:43], v[54:55], v[46:47]
	v_pk_mul_f32 v[46:47], v[160:161], v[66:67] op_sel_hi:[1,0]
	s_nop 0
	v_pk_fma_f32 v[44:45], v[44:45], v[46:47], v[48:49]
	v_pk_mul_f32 v[46:47], v[102:103], v[66:67] op_sel_hi:[1,0]
	s_nop 0
	v_pk_fma_f32 v[46:47], v[34:35], v[46:47], v[38:39]
	v_pk_mul_f32 v[34:35], v[104:105], v[66:67] op_sel_hi:[1,0]
	v_cvt_pk_f16_f32 v38, v42, v43
	v_pk_fma_f32 v[48:49], v[36:37], v[34:35], v[40:41]
	v_cvt_pk_f16_f32 v34, v58, v59
	v_cvt_pk_f16_f32 v35, v60, v61
	v_cvt_pk_f16_f32 v36, v50, v51
	v_cvt_pk_f16_f32 v37, v52, v53
	v_cvt_pk_f16_f32 v39, v44, v45
	v_cvt_pk_f16_f32 v40, v46, v47
	v_cvt_pk_f16_f32 v41, v48, v49
	global_store_dwordx4 v0, v[34:37], s[12:13] nt
	global_store_dwordx4 v0, v[38:41], s[12:13] offset:1024 nt
	s_mov_b64 s[12:13], 0
	v_pk_fma_f32 v[34:35], v[82:83], v[58:59], v[78:79]
	v_pk_fma_f32 v[36:37], v[134:135], v[60:61], v[80:81]
	v_cvt_pk_bf16_f32 v34, v34, v35
	v_cvt_pk_bf16_f32 v35, v36, v37
	v_pk_fma_f32 v[36:37], v[96:97], v[50:51], v[74:75]
	v_pk_fma_f32 v[38:39], v[94:95], v[52:53], v[76:77]
	v_cvt_pk_bf16_f32 v36, v36, v37
	v_cvt_pk_bf16_f32 v37, v38, v39
	v_pk_fma_f32 v[38:39], v[84:85], v[42:43], v[90:91]
	v_pk_fma_f32 v[40:41], v[140:141], v[44:45], v[92:93]
	v_cvt_pk_bf16_f32 v38, v38, v39
	v_cvt_pk_bf16_f32 v39, v40, v41
	v_pk_fma_f32 v[40:41], v[138:139], v[46:47], v[86:87]
	v_pk_fma_f32 v[42:43], v[136:137], v[48:49], v[88:89]
	v_cvt_pk_bf16_f32 v40, v40, v41
	v_cvt_pk_bf16_f32 v41, v42, v43
	global_store_dwordx4 v[116:117], v[34:37], off offset:2048
	global_store_dwordx4 v[116:117], v[38:41], off offset:3072

; DI unsigned pk2(float lo, float hi) { f32x2 v = {lo, hi}; return __builtin_bit_cast(unsigned, __builtin_convertvector(v, bf16x2v)); }
; DI float4 ld_nt4(const float* p) { const f32x4 v = __builtin_nontemporal_load((const f32x4*)p); return make_float4(v[0], v[1], v[2], v[3]); }
; DI float4 h4lo(const u32x4 v) { return make_float4(hlo(v[0]), hhi(v[0]), hlo(v[1]), hhi(v[1])); }
; DI float4 h4hi(const u32x4 v) { return make_float4(hlo(v[2]), hhi(v[2]), hlo(v[3]), hhi(v[3])); }
; DI float4 b4lo(const uint4 v) { return make_float4(bflo(v.x), bfhi(v.x), bflo(v.y), bfhi(v.y)); }
; DI float wave_sum(float v) {
; #pragma unroll
;   for (int o = 32; o > 0; o >>= 1) v += __shfl_xor(v, o);
;   return v;
; template <bool IN16>
; DI LnRow ln_load(const float* hin, const unsigned short* hin16, const bf16_t* yu, const LnVec& gate, int c0) {
;   LnRow r;
;   const uint4 ya = *(const uint4*)(yu + c0), yb = *(const uint4*)(yu + 512 + c0);
;   float4 h0, h1, h2, h3;
;   if (IN16) {
;     const u32x4 ha = __builtin_nontemporal_load((const u32x4*)(hin16 + c0)), hb = __builtin_nontemporal_load((const u32x4*)(hin16 + 512 + c0));
;     h0 = h4lo(ha); h1 = h4hi(ha); h2 = h4lo(hb); h3 = h4hi(hb);
;   } else {
;     h0 = ld_nt4(hin + c0); h1 = ld_nt4(hin + c0 + 4); h2 = ld_nt4(hin + 512 + c0); h3 = ld_nt4(hin + 512 + c0 + 4);
;   }
;   r.z0 = zmix(h0, gate.a, b4lo(ya)); r.z1 = zmix(h1, gate.b, b4hi(ya)); r.z2 = zmix(h2, gate.c, b4lo(yb)); r.z3 = zmix(h3, gate.d, b4hi(yb));
;   return r;
; }
; DI float4 ln_norm(const float4 z, float mean, float rstd, const float4 g, const float4 b) {
;   return make_float4((z.x - mean) * rstd * g.x + b.x, (z.y - mean) * rstd * g.y + b.y, (z.z - mean) * rstd * g.z + b.z, (z.w - mean) * rstd * g.w + b.w);
; }
; DI unsigned umod(float a, float b, float sca, float scb, float sha, float shb) { return pk2(a * (1.f + sca) + sha, b * (1.f + scb) + shb); }
; template <bool OUT16>
; DI void ln_finish(const LnRow& r, float* hout, unsigned short* hout16, bf16_t* yu, const LnVec& g, const LnVec& b, const LnVec& sc, const LnVec& sh, int c0, bool wr_u) {
;   const float sum = (r.z0.x + r.z0.y + r.z0.z + r.z0.w) + (r.z1.x + r.z1.y + r.z1.z + r.z1.w) + (r.z2.x + r.z2.y + r.z2.z + r.z2.w) + (r.z3.x + r.z3.y + r.z3.z + r.z3.w);
;   const float mean = wave_sum(sum) * (1.f / 1024.f);
.LBB0_172:
	global_load_dwordx4 v[18:21], v[54:55], off offset:-1024
	global_load_dwordx4 v[22:25], v[54:55], off
	global_load_dwordx4 v[50:53], v[56:57], off offset:-1024 nt
	global_load_dwordx4 v[34:37], v[56:57], off nt
	v_lshl_add_u64 v[62:63], s[0:1], 0, v[0:1]
	v_lshl_add_u64 v[60:61], v[62:63], 0, s[88:89]
	s_mov_b64 s[10:11], 0x1800
	v_lshl_add_u64 v[58:59], v[62:63], 0, s[10:11]
	s_add_i32 s7, s7, 1
	s_waitcnt vmcnt(3)
	v_lshlrev_b32_e32 v88, 16, v20
	v_and_b32_e32 v89, 0xffff0000, v20
	v_lshlrev_b32_e32 v38, 16, v21
	v_and_b32_e32 v39, 0xffff0000, v21
	s_waitcnt vmcnt(0)
	v_cvt_f32_f16_sdwa v21, v37 dst_sel:DWORD dst_unused:UNUSED_PAD src0_sel:WORD_1
	v_cvt_f32_f16_e32 v20, v37
	v_cvt_f32_f16_sdwa v37, v36 dst_sel:DWORD dst_unused:UNUSED_PAD src0_sel:WORD_1
	v_cvt_f32_f16_e32 v36, v36
	v_lshlrev_b32_e32 v44, 16, v24
	v_and_b32_e32 v45, 0xffff0000, v24
	v_lshlrev_b32_e32 v40, 16, v22
	v_pk_mul_f32 v[36:37], v[36:37], s[74:75] op_sel_hi:[1,0]
	v_and_b32_e32 v41, 0xffff0000, v22
	v_pk_fma_f32 v[66:67], v[14:15], v[44:45], v[36:37]
	v_cvt_f32_f16_sdwa v37, v35 dst_sel:DWORD dst_unused:UNUSED_PAD src0_sel:WORD_1
	v_cvt_f32_f16_e32 v36, v35
	v_cvt_f32_f16_sdwa v35, v34 dst_sel:DWORD dst_unused:UNUSED_PAD src0_sel:WORD_1
	v_cvt_f32_f16_e32 v34, v34
	v_lshlrev_b32_e32 v72, 16, v18
	v_and_b32_e32 v73, 0xffff0000, v18
	v_lshlrev_b32_e32 v86, 16, v19
	v_pk_mul_f32 v[34:35], v[34:35], s[74:75] op_sel_hi:[1,0]
	v_and_b32_e32 v87, 0xffff0000, v19
	v_lshlrev_b32_e32 v42, 16, v23
	v_and_b32_e32 v43, 0xffff0000, v23
	v_lshlrev_b32_e32 v18, 16, v25
	v_and_b32_e32 v19, 0xffff0000, v25
	v_pk_mul_f32 v[20:21], v[20:21], s[74:75] op_sel_hi:[1,0]
	v_pk_mul_f32 v[36:37], v[36:37], s[74:75] op_sel_hi:[1,0]
	v_pk_fma_f32 v[70:71], v[10:11], v[40:41], v[34:35]
	v_pk_fma_f32 v[64:65], v[16:17], v[18:19], v[20:21]
	v_pk_fma_f32 v[68:69], v[12:13], v[42:43], v[36:37]
	v_mov_b32_e32 v34, v66
	v_mov_b32_e32 v35, v70
	v_mov_b32_e32 v36, v67
	v_mov_b32_e32 v37, v71
	v_pk_add_f32 v[34:35], v[34:35], v[36:37]
	v_mov_b32_e32 v36, v64
	v_mov_b32_e32 v37, v68
	v_pk_add_f32 v[34:35], v[36:37], v[34:35]
	v_mov_b32_e32 v36, v65
	v_mov_b32_e32 v37, v69
	v_pk_add_f32 v[74:75], v[36:37], v[34:35]
	v_cvt_f32_f16_sdwa v35, v53 dst_sel:DWORD dst_unused:UNUSED_PAD src0_sel:WORD_1
	v_cvt_f32_f16_e32 v34, v53
	v_cvt_f32_f16_sdwa v53, v52 dst_sel:DWORD dst_unused:UNUSED_PAD src0_sel:WORD_1
	v_cvt_f32_f16_e32 v52, v52
	global_load_dwordx4 v[18:21], v[108:109], off offset:2064
	global_load_dwordx4 v[26:29], v[108:109], off offset:2048
	global_load_dwordx4 v[22:25], v[110:111], off offset:2064
	global_load_dwordx4 v[30:33], v[110:111], off offset:2048
	v_pk_mul_f32 v[34:35], v[34:35], s[74:75] op_sel_hi:[1,0]
	v_pk_mul_f32 v[52:53], v[52:53], s[74:75] op_sel_hi:[1,0]
	s_nop 0
	v_pk_fma_f32 v[52:53], v[6:7], v[88:89], v[52:53]
	v_cvt_f32_f16_sdwa v89, v51 dst_sel:DWORD dst_unused:UNUSED_PAD src0_sel:WORD_1
	v_cvt_f32_f16_e32 v88, v51
	v_cvt_f32_f16_sdwa v51, v50 dst_sel:DWORD dst_unused:UNUSED_PAD src0_sel:WORD_1
	v_cvt_f32_f16_e32 v50, v50
	v_pk_fma_f32 v[76:77], v[8:9], v[38:39], v[34:35]
	v_pk_mul_f32 v[88:89], v[88:89], s[74:75] op_sel_hi:[1,0]
	global_load_dwordx4 v[34:37], v[108:109], off offset:16
	global_load_dwordx4 v[42:45], v[108:109], off
	global_load_dwordx4 v[38:41], v[110:111], off offset:16
	global_load_dwordx4 v[46:49], v[110:111], off
	v_pk_mul_f32 v[50:51], v[50:51], s[74:75] op_sel_hi:[1,0]
	v_pk_fma_f32 v[86:87], v[4:5], v[86:87], v[88:89]
	v_pk_fma_f32 v[50:51], v[2:3], v[72:73], v[50:51]
	v_mov_b32_e32 v73, v52
	v_mov_b32_e32 v72, v50
	v_mov_b32_e32 v88, v51
	v_mov_b32_e32 v89, v53
	v_pk_add_f32 v[72:73], v[72:73], v[88:89]
	v_mov_b32_e32 v88, v86
	v_mov_b32_e32 v89, v76
	v_pk_add_f32 v[72:73], v[88:89], v[72:73]
	v_mov_b32_e32 v88, v87
	v_mov_b32_e32 v89, v77
	v_pk_add_f32 v[72:73], v[88:89], v[72:73]
	s_nop 0
	v_add_f32_e32 v72, v72, v73
	v_add_f32_e32 v72, v72, v75
	v_add_f32_e32 v72, v74, v72
	v_mov_b32_e32 v73, v72
	s_nop 1
	v_permlane32_swap_b32_e32 v73, v72
	s_waitcnt lgkmcnt(0)
	v_add_f32_e32 v72, v72, v73
	v_mov_b32_e32 v73, v72
	s_nop 1
	v_permlane16_swap_b32_e32 v73, v72
	s_waitcnt lgkmcnt(0)
	v_add_f32_e32 v72, v72, v73
	s_nop 1
	v_mov_b32_dpp v73, v72 row_ror:8 row_mask:0xf bank_mask:0xf
	s_waitcnt lgkmcnt(0)
	v_add_f32_e32 v72, v72, v73
	s_nop 1
	v_mov_b32_dpp v73, v72 row_ror:4 row_mask:0xf bank_mask:0xf
	s_waitcnt lgkmcnt(0)
	v_add_f32_e32 v72, v72, v73
	s_nop 1
	v_mov_b32_dpp v73, v72 quad_perm:[2,3,0,1] row_mask:0xf bank_mask:0xf
	s_waitcnt lgkmcnt(0)
	v_add_f32_e32 v72, v72, v73
	s_nop 1
	v_mov_b32_dpp v73, v72 quad_perm:[1,0,3,2] row_mask:0xf bank_mask:0xf
	s_waitcnt lgkmcnt(0)
; DI unsigned pkh2(float lo, float hi) { f32x2 v = {lo, hi}; return __builtin_bit_cast(unsigned, __builtin_convertvector(v, h16x2)); }
; DI float wave_sum(float v) {
; #pragma unroll
;   for (int o = 32; o > 0; o >>= 1) v += __shfl_xor(v, o);
;   return v;
; template <bool OUT16>
; DI void ln_finish(const LnRow& r, float* hout, unsigned short* hout16, bf16_t* yu, const LnVec& g, const LnVec& b, const LnVec& sc, const LnVec& sh, int c0, bool wr_u) {
;     ...
;   const float mean = wave_sum(sum) * (1.f / 1024.f);
;   const float sq = sq4(r.z0, mean) + sq4(r.z1, mean) + sq4(r.z2, mean) + sq4(r.z3, mean);
;   const float rstd = rsqrtf(wave_sum(sq) * (1.f / 1024.f) + 1e-5f);
;   const float4 o0 = ln_norm(r.z0, mean, rstd, g.a, b.a), o1 = ln_norm(r.z1, mean, rstd, g.b, b.b), o2 = ln_norm(r.z2, mean, rstd, g.c, b.c), o3 = ln_norm(r.z3, mean, rstd, g.d, b.d);
;   if (OUT16) {
;     u32x4 wa, wb;
;     wa[0] = pkh2(o0.x, o0.y); wa[1] = pkh2(o0.z, o0.w); wa[2] = pkh2(o1.x, o1.y); wa[3] = pkh2(o1.z, o1.w);
;     wb[0] = pkh2(o2.x, o2.y); wb[1] = pkh2(o2.z, o2.w); wb[2] = pkh2(o3.x, o3.y); wb[3] = pkh2(o3.z, o3.w);
;     __builtin_nontemporal_store(wa, (u32x4*)(hout16 + c0));
;     __builtin_nontemporal_store(wb, (u32x4*)(hout16 + 512 + c0));
;   } else {
;     f32x4 v;
;     v[0] = o0.x; v[1] = o0.y; v[2] = o0.z; v[3] = o0.w; __builtin_nontemporal_store(v, (f32x4*)(hout + c0));
;     v[0] = o1.x; v[1] = o1.y; v[2] = o1.z; v[3] = o1.w; __builtin_nontemporal_store(v, (f32x4*)(hout + c0 + 4));
;     v[0] = o2.x; v[1] = o2.y; v[2] = o2.z; v[3] = o2.w; __builtin_nontemporal_store(v, (f32x4*)(hout + 512 + c0));
;     v[0] = o3.x; v[1] = o3.y; v[2] = o3.z; v[3] = o3.w; __builtin_nontemporal_store(v, (f32x4*)(hout + 512 + c0 + 4));
;   }
;   if (wr_u) {
;     uint4 ua, ub;
;     ua.x = umod(o0.x, o0.y, sc.a.x, sc.a.y, sh.a.x, sh.a.y); ua.y = umod(o0.z, o0.w, sc.a.z, sc.a.w, sh.a.z, sh.a.w);
;     ua.z = umod(o1.x, o1.y, sc.b.x, sc.b.y, sh.b.x, sh.b.y); ua.w = umod(o1.z, o1.w, sc.b.z, sc.b.w, sh.b.z, sh.b.w);
;     ub.x = umod(o2.x, o2.y, sc.c.x, sc.c.y, sh.c.x, sh.c.y); ub.y = umod(o2.z, o2.w, sc.c.z, sc.c.w, sh.c.z, sh.c.w);
;     ub.z = umod(o3.x, o3.y, sc.d.x, sc.d.y, sh.d.x, sh.d.y); ub.w = umod(o3.z, o3.w, sc.d.z, sc.d.w, sh.d.z, sh.d.w);
;     *(uint4*)(yu + c0) = ua;
;     *(uint4*)(yu + 512 + c0) = ub;
;   }
	v_add_f32_e32 v72, v72, v73
	v_mul_f32_e32 v72, 0x3a800000, v72
	v_pk_add_f32 v[50:51], v[50:51], v[72:73] op_sel_hi:[1,0] neg_lo:[0,1] neg_hi:[0,1]
	v_pk_add_f32 v[74:75], v[86:87], v[72:73] op_sel_hi:[1,0] neg_lo:[0,1] neg_hi:[0,1]
	v_pk_add_f32 v[86:87], v[52:53], v[72:73] op_sel_hi:[1,0] neg_lo:[0,1] neg_hi:[0,1]
	v_mov_b32_e32 v88, v51
	v_mov_b32_e32 v89, v87
	v_pk_add_f32 v[76:77], v[76:77], v[72:73] op_sel_hi:[1,0] neg_lo:[0,1] neg_hi:[0,1]
	v_mov_b32_e32 v52, v50
	v_mov_b32_e32 v53, v86
	v_pk_mul_f32 v[88:89], v[88:89], v[88:89]
	v_pk_add_f32 v[70:71], v[70:71], v[72:73] op_sel_hi:[1,0] neg_lo:[0,1] neg_hi:[0,1]
	v_pk_fma_f32 v[52:53], v[52:53], v[52:53], v[88:89]
	v_mov_b32_e32 v88, v74
	v_mov_b32_e32 v89, v76
	v_pk_fma_f32 v[52:53], v[88:89], v[88:89], v[52:53]
	v_mov_b32_e32 v88, v75
	v_mov_b32_e32 v89, v77
	v_pk_add_f32 v[66:67], v[66:67], v[72:73] op_sel_hi:[1,0] neg_lo:[0,1] neg_hi:[0,1]
	v_pk_fma_f32 v[52:53], v[88:89], v[88:89], v[52:53]
	v_mov_b32_e32 v88, v67
	v_mov_b32_e32 v89, v71
	v_pk_add_f32 v[68:69], v[68:69], v[72:73] op_sel_hi:[1,0] neg_lo:[0,1] neg_hi:[0,1]
	v_pk_add_f32 v[64:65], v[64:65], v[72:73] op_sel_hi:[1,0] neg_lo:[0,1] neg_hi:[0,1]
	v_mov_b32_e32 v72, v66
	v_mov_b32_e32 v73, v70
	v_pk_mul_f32 v[88:89], v[88:89], v[88:89]
	v_add_f32_e32 v52, v52, v53
	v_pk_fma_f32 v[72:73], v[72:73], v[72:73], v[88:89]
	v_mov_b32_e32 v88, v64
	v_mov_b32_e32 v89, v68
	v_pk_fma_f32 v[72:73], v[88:89], v[88:89], v[72:73]
	v_mov_b32_e32 v88, v65
	v_mov_b32_e32 v89, v69
	v_pk_fma_f32 v[72:73], v[88:89], v[88:89], v[72:73]
	s_nop 0
	v_add_f32_e32 v52, v73, v52
	v_add_f32_e32 v52, v72, v52
	v_mov_b32_e32 v53, v52
	s_nop 1
	v_permlane32_swap_b32_e32 v53, v52
	s_waitcnt lgkmcnt(0)
	v_add_f32_e32 v52, v52, v53
	v_mov_b32_e32 v53, v52
	s_nop 1
	v_permlane16_swap_b32_e32 v53, v52
	s_waitcnt lgkmcnt(0)
	v_add_f32_e32 v52, v52, v53
	s_nop 1
	v_mov_b32_dpp v53, v52 row_ror:8 row_mask:0xf bank_mask:0xf
	s_waitcnt lgkmcnt(0)
	v_add_f32_e32 v52, v52, v53
	s_nop 1
	v_mov_b32_dpp v53, v52 row_ror:4 row_mask:0xf bank_mask:0xf
	s_waitcnt lgkmcnt(0)
	v_add_f32_e32 v52, v52, v53
	s_nop 1
	v_mov_b32_dpp v53, v52 quad_perm:[2,3,0,1] row_mask:0xf bank_mask:0xf
	s_waitcnt lgkmcnt(0)
	v_add_f32_e32 v52, v52, v53
	s_nop 1
	v_mov_b32_dpp v53, v52 quad_perm:[1,0,3,2] row_mask:0xf bank_mask:0xf
	s_waitcnt lgkmcnt(0)
	v_add_f32_e32 v52, v52, v53
	v_fmamk_f32 v52, v52, 0x3a800000, v209
	v_cmp_gt_f32_e32 vcc, s96, v52
	v_mul_f32_e32 v53, 0x4b800000, v52
	s_nop 0
	v_cndmask_b32_e32 v52, v52, v53, vcc
	v_rsq_f32_e32 v52, v52
	s_nop 0
	v_mul_f32_e32 v53, 0x45800000, v52
	v_cndmask_b32_e32 v72, v52, v53, vcc
	v_pk_mul_f32 v[50:51], v[50:51], v[72:73] op_sel_hi:[1,0]
	s_waitcnt vmcnt(0)
	v_pk_fma_f32 v[52:53], v[42:43], v[50:51], v[46:47]
	v_pk_mul_f32 v[42:43], v[74:75], v[72:73] op_sel_hi:[1,0]
	s_nop 0
	v_pk_fma_f32 v[50:51], v[44:45], v[42:43], v[48:49]
	v_pk_mul_f32 v[42:43], v[86:87], v[72:73] op_sel_hi:[1,0]
	s_nop 0
	v_pk_fma_f32 v[48:49], v[34:35], v[42:43], v[38:39]
	v_pk_mul_f32 v[34:35], v[76:77], v[72:73] op_sel_hi:[1,0]
	s_nop 0
	v_pk_fma_f32 v[46:47], v[36:37], v[34:35], v[40:41]
	v_pk_mul_f32 v[34:35], v[70:71], v[72:73] op_sel_hi:[1,0]
	v_add_co_u32_e32 v36, vcc, s91, v62
	v_pk_fma_f32 v[44:45], v[26:27], v[34:35], v[30:31]
	v_pk_mul_f32 v[26:27], v[68:69], v[72:73] op_sel_hi:[1,0]
	v_addc_co_u32_e32 v37, vcc, 0, v63, vcc
	v_pk_fma_f32 v[42:43], v[28:29], v[26:27], v[32:33]
	v_pk_mul_f32 v[26:27], v[66:67], v[72:73] op_sel_hi:[1,0]
	v_cmp_eq_u32_e32 vcc, s7, v78
	v_pk_fma_f32 v[40:41], v[18:19], v[26:27], v[22:23]
	v_pk_mul_f32 v[18:19], v[64:65], v[72:73] op_sel_hi:[1,0]
	global_load_dwordx4 v[32:35], v[36:37], off
	global_load_dwordx4 v[28:31], v[60:61], off offset:16
	s_nop 0
	global_load_dwordx4 v[60:63], v0, s[0:1] offset:16
	global_load_dwordx4 v[64:67], v0, s[0:1]
	v_pk_fma_f32 v[38:39], v[20:21], v[18:19], v[24:25]
	v_cvt_pk_f16_f32 v18, v52, v53
	v_cvt_pk_f16_f32 v19, v50, v51
	v_cvt_pk_f16_f32 v20, v48, v49
	v_cvt_pk_f16_f32 v21, v46, v47
	v_cvt_pk_f16_f32 v22, v44, v45
	v_cvt_pk_f16_f32 v23, v42, v43
	v_cvt_pk_f16_f32 v24, v40, v41
	v_cvt_pk_f16_f32 v25, v38, v39
	s_and_b64 vcc, exec, vcc
	s_waitcnt vmcnt(3)
	v_pk_add_f32 v[26:27], v[32:33], 1.0 op_sel_hi:[1,0]
	v_pk_add_f32 v[32:33], v[34:35], 1.0 op_sel_hi:[1,0]
	s_waitcnt vmcnt(2)
	v_pk_add_f32 v[28:29], v[28:29], 1.0 op_sel_hi:[1,0]
	v_pk_add_f32 v[30:31], v[30:31], 1.0 op_sel_hi:[1,0]
	s_waitcnt vmcnt(0)
	v_pk_fma_f32 v[26:27], v[26:27], v[52:53], v[64:65]
	v_pk_fma_f32 v[32:33], v[32:33], v[50:51], v[66:67]
	v_pk_fma_f32 v[28:29], v[28:29], v[48:49], v[60:61]
	v_pk_fma_f32 v[30:31], v[30:31], v[46:47], v[62:63]
	v_cvt_pk_bf16_f32 v26, v26, v27
	v_cvt_pk_bf16_f32 v27, v32, v33
	v_cvt_pk_bf16_f32 v28, v28, v29
	v_cvt_pk_bf16_f32 v29, v30, v31
	global_load_dwordx4 v[46:49], v[36:37], off offset:2048
	global_load_dwordx4 v[30:33], v[58:59], off offset:16
	s_nop 0
	global_load_dwordx4 v[34:37], v0, s[0:1] offset:2064
	global_load_dwordx4 v[50:53], v0, s[0:1] offset:2048
	s_nop 0
	global_store_dwordx4 v[56:57], v[18:21], off offset:-1024 nt
	global_store_dwordx4 v[56:57], v[22:25], off nt
	v_lshl_add_u64 v[56:57], v[56:57], 0, s[80:81]
	s_waitcnt vmcnt(5)
	v_pk_add_f32 v[46:47], v[46:47], 1.0 op_sel_hi:[1,0]
	s_waitcnt vmcnt(4)
	v_pk_add_f32 v[30:31], v[30:31], 1.0 op_sel_hi:[1,0]
	v_pk_add_f32 v[18:19], v[32:33], 1.0 op_sel_hi:[1,0]
	s_waitcnt vmcnt(2)
	v_pk_fma_f32 v[44:45], v[46:47], v[44:45], v[50:51]
	v_pk_add_f32 v[46:47], v[48:49], 1.0 op_sel_hi:[1,0]
	v_pk_fma_f32 v[30:31], v[30:31], v[40:41], v[34:35]
	v_pk_fma_f32 v[42:43], v[46:47], v[42:43], v[52:53]
	v_pk_fma_f32 v[18:19], v[18:19], v[38:39], v[36:37]
	v_cvt_pk_bf16_f32 v44, v44, v45
	v_cvt_pk_bf16_f32 v45, v42, v43
	v_cvt_pk_bf16_f32 v46, v30, v31
	v_cvt_pk_bf16_f32 v47, v18, v19
	global_store_dwordx4 v[54:55], v[26:29], off offset:-1024
	global_store_dwordx4 v[54:55], v[44:47], off
	v_lshl_add_u64 v[54:55], v[54:55], 0, s[80:81]
	s_cbranch_vccnz .LBB0_163

; DI float4 h4lo(const u32x4 v) { return make_float4(hlo(v[0]), hhi(v[0]), hlo(v[1]), hhi(v[1])); }
; template <bool IN16>
; DI LnRow ln_load(const float* hin, const unsigned short* hin16, const bf16_t* yu, const LnVec& gate, int c0) {
;   LnRow r;
;   const uint4 ya = *(const uint4*)(yu + c0), yb = *(const uint4*)(yu + 512 + c0);
;   float4 h0, h1, h2, h3;
;   if (IN16) {
;     const u32x4 ha = __builtin_nontemporal_load((const u32x4*)(hin16 + c0)), hb = __builtin_nontemporal_load((const u32x4*)(hin16 + 512 + c0));
;     h0 = h4lo(ha); h1 = h4hi(ha); h2 = h4lo(hb); h3 = h4hi(hb);
;   } else {
;     h0 = ld_nt4(hin + c0); h1 = ld_nt4(hin + c0 + 4); h2 = ld_nt4(hin + 512 + c0); h3 = ld_nt4(hin + 512 + c0 + 4);
;   }
;   r.z0 = zmix(h0, gate.a, b4lo(ya)); r.z1 = zmix(h1, gate.b, b4hi(ya)); r.z2 = zmix(h2, gate.c, b4lo(yb)); r.z3 = zmix(h3, gate.d, b4hi(yb));
;   return r;
; }
; DI float4 ln_norm(const float4 z, float mean, float rstd, const float4 g, const float4 b) {
;   return make_float4((z.x - mean) * rstd * g.x + b.x, (z.y - mean) * rstd * g.y + b.y, (z.z - mean) * rstd * g.z + b.z, (z.w - mean) * rstd * g.w + b.w);
; }
; DI unsigned umod(float a, float b, float sca, float scb, float sha, float shb) { return pk2(a * (1.f + sca) + sha, b * (1.f + scb) + shb); }
; template <bool OUT16>
; DI void ln_finish(const LnRow& r, float* hout, unsigned short* hout16, bf16_t* yu, const LnVec& g, const LnVec& b, const LnVec& sc, const LnVec& sh, int c0, bool wr_u) {
;   const float sum = (r.z0.x + r.z0.y + r.z0.z + r.z0.w) + (r.z1.x + r.z1.y + r.z1.z + r.z1.w) + (r.z2.x + r.z2.y + r.z2.z + r.z2.w) + (r.z3.x + r.z3.y + r.z3.z + r.z3.w);
;   const float mean = wave_sum(sum) * (1.f / 1024.f);
; template <bool IN16, bool OUT16>
; DI void ln_body(const Params& p, int layer) {
;     ...
;     const bool isctx = row >= TL;
;     const float* hin = isctx ? (p.ctx + (size_t)(row - TL) * 1024) : (p.x + (size_t)row * 1024);
;     const unsigned short* hin16 = in16 ? (p.h16 + (size_t)row * 1024) : nullptr;
;     float* hout = p.out + (size_t)(isctx ? 0 : row) * 1024;
;     unsigned short* hout16 = out16 ? (p.h16 + (size_t)row * 1024) : nullptr;
;     bf16_t* yu = p.u + (size_t)row * 1024;
;     const unsigned short* hb = hin16 ? hin16 + 1024 : nullptr; const unsigned short* hc_ = hin16 ? hin16 + 2048 : nullptr; const unsigned short* hd = hin16 ? hin16 + 3072 : nullptr;
.LBB0_194:
	s_lshl_b64 s[14:15], s[14:15], 11
	s_add_u32 s16, s40, s14
	s_addc_u32 s17, s41, s15
	s_add_u32 s14, s36, s14
	s_addc_u32 s15, s37, s15
	v_lshlrev_b32_e32 v0, 1, v122
	global_load_dwordx4 v[34:37], v0, s[14:15]
	global_load_dwordx4 v[38:41], v0, s[14:15] offset:1024
	global_load_dwordx4 v[42:45], v0, s[14:15] offset:2048
	global_load_dwordx4 v[46:49], v0, s[14:15] offset:3072
	v_lshl_add_u64 v[50:51], s[14:15], 0, v[0:1]
	v_add_co_u32_e32 v132, vcc, s91, v50
	v_lshlrev_b32_e32 v154, 2, v122
	s_nop 0
	v_addc_co_u32_e32 v133, vcc, 0, v51, vcc
	global_load_dwordx4 v[50:53], v[132:133], off
	global_load_dwordx4 v[54:57], v[132:133], off offset:1024
	global_load_dwordx4 v[58:61], v154, s[18:19] nt
	global_load_dwordx4 v[62:65], v154, s[18:19] offset:16 nt
	global_load_dwordx4 v[186:189], v154, s[18:19] offset:2048 nt
	global_load_dwordx4 v[182:185], v154, s[18:19] offset:2064 nt
	v_mov_b32_e32 v155, v1
	v_lshl_add_u64 v[74:75], s[18:19], 0, v[154:155]
	v_add_co_u32_e32 v68, vcc, s91, v74
	s_mov_b64 s[18:19], 0x2000
	s_nop 0
	v_addc_co_u32_e32 v69, vcc, 0, v75, vcc
	v_lshl_add_u64 v[66:67], v[74:75], 0, s[88:89]
	v_add_co_u32_e32 v70, vcc, s90, v74
	s_mov_b64 s[22:23], 0x1800
	v_lshl_add_u64 v[76:77], v[74:75], 0, s[18:19]
	s_mov_b64 s[18:19], 0x2800
	v_addc_co_u32_e32 v71, vcc, 0, v75, vcc
	v_lshl_add_u64 v[72:73], v[74:75], 0, s[22:23]
	v_lshl_add_u64 v[78:79], v[74:75], 0, s[18:19]
	global_load_dwordx4 v[86:89], v[66:67], off offset:16 nt
	global_load_dwordx4 v[102:105], v[68:69], off offset:2048 nt
	global_load_dwordx4 v[110:113], v[72:73], off offset:16 nt
	global_load_dwordx4 v[82:85], v[70:71], off offset:-4096 nt
	global_load_dwordx4 v[90:93], v[70:71], off nt
	global_load_dwordx4 v[98:101], v[70:71], off offset:2048 nt
	global_load_dwordx4 v[94:97], v[76:77], off offset:16 nt
	global_load_dwordx4 v[106:109], v[78:79], off offset:16 nt
	s_mov_b64 s[18:19], 0x3000
	global_load_dwordx4 v[118:121], v[132:133], off offset:2048
	global_load_dwordx4 v[114:117], v[132:133], off offset:3072
	v_lshl_add_u64 v[168:169], s[12:13], 0, v[154:155]
	v_lshl_add_u64 v[162:163], v[168:169], 0, s[88:89]
	v_lshl_add_u64 v[164:165], v[168:169], 0, s[22:23]
	s_waitcnt vmcnt(19)
	v_lshlrev_b32_e32 v192, 16, v36
	s_waitcnt vmcnt(18)
	v_lshlrev_b32_e32 v196, 16, v40
	s_waitcnt vmcnt(17)
	v_lshlrev_b32_e32 v166, 16, v44
	v_and_b32_e32 v167, 0xffff0000, v44
	v_add_co_u32_e32 v44, vcc, s3, v74
	v_lshlrev_b32_e32 v158, 16, v42
	v_and_b32_e32 v159, 0xffff0000, v42
	v_lshlrev_b32_e32 v160, 16, v43
	v_and_b32_e32 v161, 0xffff0000, v43
	v_lshlrev_b32_e32 v170, 16, v45
	v_and_b32_e32 v171, 0xffff0000, v45
	v_lshl_add_u64 v[42:43], v[74:75], 0, s[18:19]
	v_addc_co_u32_e32 v45, vcc, 0, v75, vcc
	s_mov_b64 s[18:19], 0x3800
	global_load_dwordx4 v[66:69], v[44:45], off nt
	global_load_dwordx4 v[70:73], v[42:43], off offset:16 nt
	v_lshl_add_u64 v[42:43], v[74:75], 0, s[18:19]
	global_load_dwordx4 v[74:77], v[44:45], off offset:2048 nt
	global_load_dwordx4 v[78:81], v[42:43], off offset:16 nt
	v_and_b32_e32 v42, 64, v214
	v_add_u32_e32 v44, 64, v42
	v_xor_b32_e32 v42, 32, v214
	v_cmp_lt_i32_e32 vcc, v42, v44
	v_and_b32_e32 v197, 0xffff0000, v40
	v_lshlrev_b32_e32 v40, 16, v41
	v_cndmask_b32_e32 v42, v214, v42, vcc
	v_lshlrev_b32_e32 v142, 2, v42
	v_xor_b32_e32 v42, 16, v214
	v_cmp_lt_i32_e32 vcc, v42, v44
	v_and_b32_e32 v41, 0xffff0000, v41
	v_lshlrev_b32_e32 v194, 16, v38
	v_cndmask_b32_e32 v42, v214, v42, vcc
	v_lshlrev_b32_e32 v123, 2, v42
	s_waitcnt vmcnt(14)
	v_pk_mul_f32 v[42:43], v[184:185], s[74:75] op_sel_hi:[1,0]
	v_and_b32_e32 v195, 0xffff0000, v38
	v_pk_fma_f32 v[180:181], v[32:33], v[40:41], v[42:43]
	v_pk_mul_f32 v[40:41], v[182:183], s[74:75] op_sel_hi:[1,0]
	v_lshlrev_b32_e32 v38, 16, v39
	v_and_b32_e32 v39, 0xffff0000, v39
	v_pk_fma_f32 v[182:183], v[30:31], v[196:197], v[40:41]
	v_pk_mul_f32 v[40:41], v[188:189], s[74:75] op_sel_hi:[1,0]
	v_and_b32_e32 v193, 0xffff0000, v36
	v_pk_fma_f32 v[184:185], v[28:29], v[38:39], v[40:41]
	v_pk_mul_f32 v[38:39], v[186:187], s[74:75] op_sel_hi:[1,0]
	v_mov_b32_e32 v41, v183
	v_pk_fma_f32 v[186:187], v[26:27], v[194:195], v[38:39]
	v_mov_b32_e32 v39, v182
	v_mov_b32_e32 v38, v186
	v_mov_b32_e32 v40, v187
	v_pk_add_f32 v[38:39], v[38:39], v[40:41]
	v_mov_b32_e32 v40, v184
	v_mov_b32_e32 v41, v180
	v_pk_add_f32 v[38:39], v[40:41], v[38:39]
	v_mov_b32_e32 v40, v185
	v_mov_b32_e32 v41, v181
	v_lshlrev_b32_e32 v36, 16, v37
	v_and_b32_e32 v37, 0xffff0000, v37
	v_pk_add_f32 v[38:39], v[40:41], v[38:39]
	v_pk_mul_f32 v[40:41], v[64:65], s[74:75] op_sel_hi:[1,0]
	v_lshlrev_b32_e32 v190, 16, v34
	v_pk_fma_f32 v[188:189], v[24:25], v[36:37], v[40:41]
	v_pk_mul_f32 v[36:37], v[62:63], s[74:75] op_sel_hi:[1,0]
	v_and_b32_e32 v191, 0xffff0000, v34
	v_lshlrev_b32_e32 v34, 16, v35
	v_and_b32_e32 v35, 0xffff0000, v35
	v_pk_fma_f32 v[192:193], v[22:23], v[192:193], v[36:37]
	v_pk_mul_f32 v[36:37], v[60:61], s[74:75] op_sel_hi:[1,0]
	v_lshlrev_b32_e32 v172, 16, v46
	v_pk_fma_f32 v[194:195], v[20:21], v[34:35], v[36:37]
	v_pk_mul_f32 v[34:35], v[58:59], s[74:75] op_sel_hi:[1,0]
	v_mov_b32_e32 v37, v193
	v_pk_fma_f32 v[190:191], v[18:19], v[190:191], v[34:35]
	v_mov_b32_e32 v35, v192
	v_mov_b32_e32 v34, v190
	v_mov_b32_e32 v36, v191
	v_pk_add_f32 v[34:35], v[34:35], v[36:37]
	v_mov_b32_e32 v36, v194
	v_mov_b32_e32 v37, v188
	v_pk_add_f32 v[34:35], v[36:37], v[34:35]
	v_mov_b32_e32 v36, v195
	v_mov_b32_e32 v37, v189
	v_pk_add_f32 v[34:35], v[36:37], v[34:35]
	v_and_b32_e32 v173, 0xffff0000, v46
	v_add_f32_e32 v34, v34, v35
	v_add_f32_e32 v34, v34, v38
	v_add_f32_e32 v34, v34, v39
	v_mov_b32_e32 v35, v34
	s_nop 1
	v_permlane32_swap_b32_e32 v35, v34
	v_lshlrev_b32_e32 v176, 16, v48
	v_and_b32_e32 v177, 0xffff0000, v48
	s_waitcnt vmcnt(11)
; DI float wave_sum(float v) {
; #pragma unroll
;   for (int o = 32; o > 0; o >>= 1) v += __shfl_xor(v, o);
;   return v;
; template <bool OUT16>
; DI void ln_finish(const LnRow& r, float* hout, unsigned short* hout16, bf16_t* yu, const LnVec& g, const LnVec& b, const LnVec& sc, const LnVec& sh, int c0, bool wr_u) {
;   const float sum = (r.z0.x + r.z0.y + r.z0.z + r.z0.w) + (r.z1.x + r.z1.y + r.z1.z + r.z1.w) + (r.z2.x + r.z2.y + r.z2.z + r.z2.w) + (r.z3.x + r.z3.y + r.z3.z + r.z3.w);
;   const float mean = wave_sum(sum) * (1.f / 1024.f);
;   const float sq = sq4(r.z0, mean) + sq4(r.z1, mean) + sq4(r.z2, mean) + sq4(r.z3, mean);
	v_pk_mul_f32 v[110:111], v[110:111], s[74:75] op_sel_hi:[1,0]
	v_pk_mul_f32 v[102:103], v[102:103], s[74:75] op_sel_hi:[1,0]
	v_lshlrev_b32_e32 v174, 16, v47
	v_and_b32_e32 v175, 0xffff0000, v47
	v_lshlrev_b32_e32 v178, 16, v49
	v_and_b32_e32 v179, 0xffff0000, v49
	v_pk_mul_f32 v[112:113], v[112:113], s[74:75] op_sel_hi:[1,0]
	v_pk_fma_f32 v[110:111], v[30:31], v[176:177], v[110:111]
	v_pk_mul_f32 v[104:105], v[104:105], s[74:75] op_sel_hi:[1,0]
	v_pk_fma_f32 v[102:103], v[26:27], v[172:173], v[102:103]
	v_pk_fma_f32 v[112:113], v[32:33], v[178:179], v[112:113]
	v_pk_fma_f32 v[104:105], v[28:29], v[174:175], v[104:105]
	v_mov_b32_e32 v172, v102
	v_mov_b32_e32 v173, v110
	v_mov_b32_e32 v174, v103
	v_mov_b32_e32 v175, v111
	v_pk_add_f32 v[172:173], v[172:173], v[174:175]
	v_mov_b32_e32 v174, v104
	v_mov_b32_e32 v175, v112
	v_pk_mul_f32 v[86:87], v[86:87], s[74:75] op_sel_hi:[1,0]
	s_waitcnt vmcnt(10)
	v_pk_mul_f32 v[82:83], v[82:83], s[74:75] op_sel_hi:[1,0]
	s_waitcnt lgkmcnt(0)
	v_add_f32_e32 v34, v34, v35
	v_pk_add_f32 v[172:173], v[174:175], v[172:173]
	v_mov_b32_e32 v174, v105
	v_mov_b32_e32 v175, v113
	v_pk_mul_f32 v[88:89], v[88:89], s[74:75] op_sel_hi:[1,0]
	v_pk_fma_f32 v[166:167], v[22:23], v[166:167], v[86:87]
	v_pk_mul_f32 v[84:85], v[84:85], s[74:75] op_sel_hi:[1,0]
	v_pk_fma_f32 v[176:177], v[18:19], v[158:159], v[82:83]
	v_mov_b32_e32 v35, v34
	s_nop 1
	v_permlane16_swap_b32_e32 v35, v34
	v_pk_add_f32 v[172:173], v[174:175], v[172:173]
	v_pk_fma_f32 v[170:171], v[24:25], v[170:171], v[88:89]
	v_pk_fma_f32 v[174:175], v[20:21], v[160:161], v[84:85]
	v_mov_b32_e32 v82, v176
	v_mov_b32_e32 v83, v166
	v_mov_b32_e32 v84, v177
	v_mov_b32_e32 v85, v167
	v_pk_add_f32 v[82:83], v[82:83], v[84:85]
	v_mov_b32_e32 v84, v174
	v_mov_b32_e32 v85, v170
	v_xor_b32_e32 v36, 8, v214
	v_pk_add_f32 v[82:83], v[84:85], v[82:83]
	v_mov_b32_e32 v84, v175
	v_mov_b32_e32 v85, v171
	v_cmp_lt_i32_e32 vcc, v36, v44
	v_pk_add_f32 v[82:83], v[84:85], v[82:83]
	s_waitcnt lgkmcnt(0)
	v_add_f32_e32 v34, v34, v35
	v_cndmask_b32_e32 v36, v214, v36, vcc
	v_add_f32_e32 v82, v82, v83
	v_lshlrev_b32_e32 v228, 2, v36
	v_add_f32_e32 v82, v82, v172
	s_nop 1
	v_mov_b32_dpp v35, v34 row_ror:8 row_mask:0xf bank_mask:0xf
	v_add_f32_e32 v82, v82, v173
	v_mov_b32_e32 v83, v82
	s_nop 1
	v_permlane32_swap_b32_e32 v83, v82
	v_xor_b32_e32 v36, 4, v214
	v_cmp_lt_i32_e32 vcc, v36, v44
	s_waitcnt lgkmcnt(1)
	v_add_f32_e32 v34, v34, v35
	v_lshlrev_b32_e32 v134, 16, v50
	v_cndmask_b32_e32 v36, v214, v36, vcc
	v_lshlrev_b32_e32 v227, 2, v36
	s_nop 1
	v_mov_b32_dpp v35, v34 row_ror:4 row_mask:0xf bank_mask:0xf
	s_waitcnt lgkmcnt(1)
	v_add_f32_e32 v86, v82, v83
	v_mov_b32_e32 v87, v86
	s_nop 1
	v_permlane16_swap_b32_e32 v87, v86
	v_xor_b32_e32 v36, 2, v214
	v_cmp_lt_i32_e32 vcc, v36, v44
	v_and_b32_e32 v135, 0xffff0000, v50
	s_waitcnt lgkmcnt(1)
	v_add_f32_e32 v50, v34, v35
	v_cndmask_b32_e32 v36, v214, v36, vcc
	v_lshlrev_b32_e32 v226, 2, v36
	v_lshlrev_b32_e32 v136, 16, v51
	v_and_b32_e32 v137, 0xffff0000, v51
	s_nop 1
	v_mov_b32_dpp v51, v50 quad_perm:[2,3,0,1] row_mask:0xf bank_mask:0xf
	s_waitcnt lgkmcnt(1)
	v_add_f32_e32 v86, v86, v87
	s_nop 1
	v_mov_b32_dpp v87, v86 row_ror:8 row_mask:0xf bank_mask:0xf
	v_xor_b32_e32 v36, 1, v214
	v_cmp_lt_i32_e32 vcc, v36, v44
	s_waitcnt lgkmcnt(1)
	v_add_f32_e32 v155, v50, v51
	v_lshlrev_b32_e32 v138, 16, v52
	v_cndmask_b32_e32 v36, v214, v36, vcc
	v_lshlrev_b32_e32 v225, 2, v36
	s_nop 1
	v_mov_b32_dpp v196, v155 quad_perm:[1,0,3,2] row_mask:0xf bank_mask:0xf
	s_waitcnt lgkmcnt(1)
	v_add_f32_e32 v86, v86, v87
	s_nop 1
	v_mov_b32_dpp v87, v86 row_ror:4 row_mask:0xf bank_mask:0xf
	v_add_co_u32_e32 v168, vcc, s91, v168
	s_waitcnt lgkmcnt(1)
	v_add_f32_e32 v155, v155, v196
	v_mul_f32_e32 v196, 0x3a800000, v155
	s_waitcnt lgkmcnt(0)
	v_add_f32_e32 v155, v86, v87
	v_pk_add_f32 v[212:213], v[186:187], v[196:197] op_sel_hi:[1,0] neg_lo:[0,1] neg_hi:[0,1]
	v_pk_add_f32 v[242:243], v[182:183], v[196:197] op_sel_hi:[1,0] neg_lo:[0,1] neg_hi:[0,1]
	s_nop 1
	v_mov_b32_dpp v158, v155 quad_perm:[2,3,0,1] row_mask:0xf bank_mask:0xf
	v_mov_b32_e32 v84, v243
	v_mov_b32_e32 v85, v213
	v_pk_add_f32 v[220:221], v[184:185], v[196:197] op_sel_hi:[1,0] neg_lo:[0,1] neg_hi:[0,1]
	v_pk_add_f32 v[244:245], v[180:181], v[196:197] op_sel_hi:[1,0] neg_lo:[0,1] neg_hi:[0,1]
	v_mov_b32_e32 v82, v242
	v_mov_b32_e32 v83, v212
	v_pk_mul_f32 v[84:85], v[84:85], v[84:85]
	v_addc_co_u32_e32 v169, vcc, 0, v169, vcc
	v_pk_fma_f32 v[82:83], v[82:83], v[82:83], v[84:85]
	v_mov_b32_e32 v84, v244
	v_mov_b32_e32 v85, v220
	v_pk_fma_f32 v[82:83], v[84:85], v[84:85], v[82:83]
	v_mov_b32_e32 v84, v245
	v_mov_b32_e32 v85, v221
	v_and_b32_e32 v139, 0xffff0000, v52
	v_lshlrev_b32_e32 v140, 16, v53
	v_and_b32_e32 v141, 0xffff0000, v53
	v_lshlrev_b32_e32 v148, 16, v54
	v_and_b32_e32 v149, 0xffff0000, v54
	v_lshlrev_b32_e32 v150, 16, v55
	v_and_b32_e32 v151, 0xffff0000, v55
	v_lshlrev_b32_e32 v152, 16, v56
	v_and_b32_e32 v153, 0xffff0000, v56
	v_lshlrev_b32_e32 v156, 16, v57
	v_and_b32_e32 v157, 0xffff0000, v57
	global_load_dwordx4 v[34:37], v[124:125], off offset:2064
	global_load_dwordx4 v[42:45], v[124:125], off offset:2048
	global_load_dwordx4 v[38:41], v[126:127], off offset:2064
	global_load_dwordx4 v[46:49], v[126:127], off offset:2048
	global_load_dwordx4 v[50:53], v[124:125], off offset:16
	global_load_dwordx4 v[58:61], v[124:125], off
	global_load_dwordx4 v[54:57], v[126:127], off offset:16
	global_load_dwordx4 v[62:65], v[126:127], off
	v_pk_fma_f32 v[172:173], v[84:85], v[84:85], v[82:83]
	global_load_dwordx4 v[82:85], v154, s[12:13] offset:16
	global_load_dwordx4 v[86:89], v154, s[12:13]
	s_waitcnt lgkmcnt(0)
; DI float wave_sum(float v) {
; #pragma unroll
;   for (int o = 32; o > 0; o >>= 1) v += __shfl_xor(v, o);
;   return v;
; template <bool OUT16>
; DI void ln_finish(const LnRow& r, float* hout, unsigned short* hout16, bf16_t* yu, const LnVec& g, const LnVec& b, const LnVec& sc, const LnVec& sh, int c0, bool wr_u) {
;     ...
;   const float mean = wave_sum(sum) * (1.f / 1024.f);
;   const float sq = sq4(r.z0, mean) + sq4(r.z1, mean) + sq4(r.z2, mean) + sq4(r.z3, mean);
;   const float rstd = rsqrtf(wave_sum(sq) * (1.f / 1024.f) + 1e-5f);
	v_add_f32_e32 v155, v155, v158
	global_load_dwordx4 v[158:161], v[168:169], off
	global_load_dwordx4 v[230:233], v[168:169], off offset:2048
	global_load_dwordx4 v[234:237], v[162:163], off offset:16
	global_load_dwordx4 v[238:241], v[164:165], off offset:16
	s_nop 1
	v_mov_b32_dpp v178, v155 quad_perm:[1,0,3,2] row_mask:0xf bank_mask:0xf
	v_pk_add_f32 v[206:207], v[190:191], v[196:197] op_sel_hi:[1,0] neg_lo:[0,1] neg_hi:[0,1]
	v_pk_add_f32 v[200:201], v[192:193], v[196:197] op_sel_hi:[1,0] neg_lo:[0,1] neg_hi:[0,1]
	v_mov_b32_e32 v190, v207
	v_mov_b32_e32 v191, v201
	v_pk_add_f32 v[202:203], v[194:195], v[196:197] op_sel_hi:[1,0] neg_lo:[0,1] neg_hi:[0,1]
	v_pk_add_f32 v[198:199], v[188:189], v[196:197] op_sel_hi:[1,0] neg_lo:[0,1] neg_hi:[0,1]
	v_mov_b32_e32 v188, v206
	v_mov_b32_e32 v189, v200
	v_pk_mul_f32 v[190:191], v[190:191], v[190:191]
	s_waitcnt lgkmcnt(0)
	v_add_f32_e32 v155, v155, v178
	v_pk_fma_f32 v[188:189], v[188:189], v[188:189], v[190:191]
	v_mov_b32_e32 v190, v202
	v_mov_b32_e32 v191, v198
	v_mul_f32_e32 v162, 0x3a800000, v155
	v_pk_fma_f32 v[188:189], v[190:191], v[190:191], v[188:189]
	v_mov_b32_e32 v190, v203
	v_mov_b32_e32 v191, v199
	v_pk_add_f32 v[184:185], v[176:177], v[162:163] op_sel_hi:[1,0] neg_lo:[0,1] neg_hi:[0,1]
	v_pk_add_f32 v[180:181], v[166:167], v[162:163] op_sel_hi:[1,0] neg_lo:[0,1] neg_hi:[0,1]
	v_pk_fma_f32 v[188:189], v[190:191], v[190:191], v[188:189]
	v_mov_b32_e32 v166, v185
	v_mov_b32_e32 v167, v181
	v_pk_add_f32 v[194:195], v[102:103], v[162:163] op_sel_hi:[1,0] neg_lo:[0,1] neg_hi:[0,1]
	v_pk_add_f32 v[190:191], v[110:111], v[162:163] op_sel_hi:[1,0] neg_lo:[0,1] neg_hi:[0,1]
	v_pk_add_f32 v[182:183], v[174:175], v[162:163] op_sel_hi:[1,0] neg_lo:[0,1] neg_hi:[0,1]
	v_pk_add_f32 v[178:179], v[170:171], v[162:163] op_sel_hi:[1,0] neg_lo:[0,1] neg_hi:[0,1]
	v_mov_b32_e32 v164, v184
	v_mov_b32_e32 v165, v180
	v_pk_mul_f32 v[166:167], v[166:167], v[166:167]
	v_pk_add_f32 v[192:193], v[104:105], v[162:163] op_sel_hi:[1,0] neg_lo:[0,1] neg_hi:[0,1]
	v_mov_b32_e32 v104, v191
	v_mov_b32_e32 v105, v195
	v_pk_fma_f32 v[164:165], v[164:165], v[164:165], v[166:167]
	v_mov_b32_e32 v166, v182
	v_mov_b32_e32 v167, v178
	v_pk_add_f32 v[186:187], v[112:113], v[162:163] op_sel_hi:[1,0] neg_lo:[0,1] neg_hi:[0,1]
	v_mov_b32_e32 v102, v190
	v_mov_b32_e32 v103, v194
	v_pk_mul_f32 v[104:105], v[104:105], v[104:105]
	v_pk_fma_f32 v[164:165], v[166:167], v[166:167], v[164:165]
	v_mov_b32_e32 v166, v183
	v_mov_b32_e32 v167, v179
	v_pk_fma_f32 v[102:103], v[102:103], v[102:103], v[104:105]
	v_mov_b32_e32 v104, v186
	v_mov_b32_e32 v105, v192
	v_pk_fma_f32 v[164:165], v[166:167], v[166:167], v[164:165]
	v_pk_fma_f32 v[102:103], v[104:105], v[104:105], v[102:103]
	v_mov_b32_e32 v104, v187
	v_mov_b32_e32 v105, v193
	v_pk_fma_f32 v[102:103], v[104:105], v[104:105], v[102:103]
	v_mov_b32_e32 v104, v164
	v_mov_b32_e32 v105, v188
	v_mov_b32_e32 v188, v165
	v_pk_add_f32 v[104:105], v[104:105], v[188:189]
	v_mov_b32_e32 v110, v103
	v_mov_b32_e32 v111, v173
	v_pk_add_f32 v[104:105], v[110:111], v[104:105]
	v_mov_b32_e32 v103, v172
	v_pk_add_f32 v[162:163], v[102:103], v[104:105]
	global_load_dwordx4 v[102:105], v154, s[12:13] offset:2064
	global_load_dwordx4 v[110:113], v154, s[12:13] offset:2048
	v_mov_b32_e32 v165, v163
	s_nop 1
	v_permlane32_swap_b32_e32 v165, v163
	v_mov_b32_e32 v164, v162
	s_nop 1
	v_permlane32_swap_b32_e32 v164, v162
	s_waitcnt vmcnt(21)
	v_lshlrev_b32_e32 v168, 16, v118
	v_and_b32_e32 v169, 0xffff0000, v118
	v_lshlrev_b32_e32 v170, 16, v119
	v_and_b32_e32 v171, 0xffff0000, v119
	s_waitcnt lgkmcnt(0)
	v_pk_add_f32 v[154:155], v[162:163], v[164:165]
	v_mov_b32_e32 v163, v155
	s_nop 1
	v_permlane16_swap_b32_e32 v163, v155
	v_mov_b32_e32 v162, v154
	s_nop 1
	v_permlane16_swap_b32_e32 v162, v154
	v_lshlrev_b32_e32 v172, 16, v120
	v_and_b32_e32 v173, 0xffff0000, v120
	v_lshlrev_b32_e32 v174, 16, v121
	v_and_b32_e32 v175, 0xffff0000, v121
	s_waitcnt lgkmcnt(0)
	v_pk_add_f32 v[118:119], v[154:155], v[162:163]
	s_nop 1
	v_mov_b32_dpp v155, v119 row_ror:8 row_mask:0xf bank_mask:0xf
	s_nop 1
	v_mov_b32_dpp v154, v118 row_ror:8 row_mask:0xf bank_mask:0xf
	s_waitcnt vmcnt(20)
	v_lshlrev_b32_e32 v176, 16, v114
	v_and_b32_e32 v177, 0xffff0000, v114
	v_lshlrev_b32_e32 v188, 16, v115
	v_and_b32_e32 v189, 0xffff0000, v115
	s_waitcnt lgkmcnt(0)
	v_pk_add_f32 v[118:119], v[118:119], v[154:155]
	s_nop 1
	v_mov_b32_dpp v121, v119 row_ror:4 row_mask:0xf bank_mask:0xf
	s_nop 1
	v_mov_b32_dpp v120, v118 row_ror:4 row_mask:0xf bank_mask:0xf
	s_waitcnt vmcnt(5)
	v_pk_add_f32 v[114:115], v[158:159], 1.0 op_sel_hi:[1,0]
	s_mov_b32 s18, 0x3727c5ac
	v_mov_b64_e32 v[166:167], s[18:19]
	s_mov_b32 s18, 0x3a800000
	s_waitcnt lgkmcnt(0)
	v_pk_add_f32 v[118:119], v[118:119], v[120:121]
	s_nop 1
	v_mov_b32_dpp v121, v119 quad_perm:[2,3,0,1] row_mask:0xf bank_mask:0xf
	s_nop 1
	v_mov_b32_dpp v120, v118 quad_perm:[2,3,0,1] row_mask:0xf bank_mask:0xf
	v_lshlrev_b32_e32 v196, 16, v116
	v_and_b32_e32 v197, 0xffff0000, v116
	v_lshlrev_b32_e32 v204, 16, v117
	v_and_b32_e32 v205, 0xffff0000, v117
	s_waitcnt lgkmcnt(0)
	v_pk_add_f32 v[158:159], v[118:119], v[120:121]
	s_nop 1
	v_mov_b32_dpp v163, v159 quad_perm:[1,0,3,2] row_mask:0xf bank_mask:0xf
	s_nop 1
	v_mov_b32_dpp v162, v158 quad_perm:[1,0,3,2] row_mask:0xf bank_mask:0xf
	s_waitcnt vmcnt(4)
	v_pk_add_f32 v[116:117], v[230:231], 1.0 op_sel_hi:[1,0]
	v_pk_add_f32 v[154:155], v[160:161], 1.0 op_sel_hi:[1,0]
	s_waitcnt vmcnt(2)
	v_pk_add_f32 v[160:161], v[238:239], 1.0 op_sel_hi:[1,0]
	v_pk_add_f32 v[120:121], v[234:235], 1.0 op_sel_hi:[1,0]
	s_waitcnt lgkmcnt(0)
; DI unsigned pkh2(float lo, float hi) { f32x2 v = {lo, hi}; return __builtin_bit_cast(unsigned, __builtin_convertvector(v, h16x2)); }
; template <bool OUT16>
; DI void ln_finish(const LnRow& r, float* hout, unsigned short* hout16, bf16_t* yu, const LnVec& g, const LnVec& b, const LnVec& sc, const LnVec& sh, int c0, bool wr_u) {
;   const float sum = (r.z0.x + r.z0.y + r.z0.z + r.z0.w) + (r.z1.x + r.z1.y + r.z1.z + r.z1.w) + (r.z2.x + r.z2.y + r.z2.z + r.z2.w) + (r.z3.x + r.z3.y + r.z3.z + r.z3.w);
;   const float mean = wave_sum(sum) * (1.f / 1024.f);
;   const float sq = sq4(r.z0, mean) + sq4(r.z1, mean) + sq4(r.z2, mean) + sq4(r.z3, mean);
;   const float rstd = rsqrtf(wave_sum(sq) * (1.f / 1024.f) + 1e-5f);
;   const float4 o0 = ln_norm(r.z0, mean, rstd, g.a, b.a), o1 = ln_norm(r.z1, mean, rstd, g.b, b.b), o2 = ln_norm(r.z2, mean, rstd, g.c, b.c), o3 = ln_norm(r.z3, mean, rstd, g.d, b.d);
;   if (OUT16) {
;     u32x4 wa, wb;
;     wa[0] = pkh2(o0.x, o0.y); wa[1] = pkh2(o0.z, o0.w); wa[2] = pkh2(o1.x, o1.y); wa[3] = pkh2(o1.z, o1.w);
;     wb[0] = pkh2(o2.x, o2.y); wb[1] = pkh2(o2.z, o2.w); wb[2] = pkh2(o3.x, o3.y); wb[3] = pkh2(o3.z, o3.w);
;     __builtin_nontemporal_store(wa, (u32x4*)(hout16 + c0));
;     __builtin_nontemporal_store(wb, (u32x4*)(hout16 + 512 + c0));
;   } else {
;     f32x4 v;
;     v[0] = o0.x; v[1] = o0.y; v[2] = o0.z; v[3] = o0.w; __builtin_nontemporal_store(v, (f32x4*)(hout + c0));
;     v[0] = o1.x; v[1] = o1.y; v[2] = o1.z; v[3] = o1.w; __builtin_nontemporal_store(v, (f32x4*)(hout + c0 + 4));
;     v[0] = o2.x; v[1] = o2.y; v[2] = o2.z; v[3] = o2.w; __builtin_nontemporal_store(v, (f32x4*)(hout + 512 + c0));
;     v[0] = o3.x; v[1] = o3.y; v[2] = o3.z; v[3] = o3.w; __builtin_nontemporal_store(v, (f32x4*)(hout + 512 + c0 + 4));
;   }
;   if (wr_u) {
;     uint4 ua, ub;
;     ua.x = umod(o0.x, o0.y, sc.a.x, sc.a.y, sh.a.x, sh.a.y); ua.y = umod(o0.z, o0.w, sc.a.z, sc.a.w, sh.a.z, sh.a.w);
;     ua.z = umod(o1.x, o1.y, sc.b.x, sc.b.y, sh.b.x, sh.b.y); ua.w = umod(o1.z, o1.w, sc.b.z, sc.b.w, sh.b.z, sh.b.w);
;     ub.x = umod(o2.x, o2.y, sc.c.x, sc.c.y, sh.c.x, sh.c.y); ub.y = umod(o2.z, o2.w, sc.c.z, sc.c.w, sh.c.z, sh.c.w);
;     ub.z = umod(o3.x, o3.y, sc.d.x, sc.d.y, sh.d.x, sh.d.y); ub.w = umod(o3.z, o3.w, sc.d.z, sc.d.w, sh.d.z, sh.d.w);
;     *(uint4*)(yu + c0) = ua;
;     *(uint4*)(yu + 512 + c0) = ub;
;   }
	v_pk_add_f32 v[158:159], v[158:159], v[162:163]
	v_pk_add_f32 v[118:119], v[236:237], 1.0 op_sel_hi:[1,0]
	v_pk_fma_f32 v[246:247], v[158:159], s[18:19], v[166:167] op_sel_hi:[1,0,0]
	v_pk_add_f32 v[162:163], v[232:233], 1.0 op_sel_hi:[1,0]
	v_mul_f32_e32 v158, 0x4b800000, v247
	v_cmp_gt_f32_e32 vcc, s96, v247
	v_pk_mul_f32 v[94:95], v[94:95], s[74:75] op_sel_hi:[1,0]
	v_pk_mul_f32 v[90:91], v[90:91], s[74:75] op_sel_hi:[1,0]
	v_cndmask_b32_e32 v158, v247, v158, vcc
	v_rsq_f32_e32 v215, v158
	v_pk_add_f32 v[158:159], v[240:241], 1.0 op_sel_hi:[1,0]
	v_pk_mul_f32 v[106:107], v[106:107], s[74:75] op_sel_hi:[1,0]
	v_pk_mul_f32 v[98:99], v[98:99], s[74:75] op_sel_hi:[1,0]
	v_mul_f32_e32 v219, 0x45800000, v215
	v_cndmask_b32_e32 v230, v215, v219, vcc
	v_pk_mul_f32 v[198:199], v[198:199], v[230:231] op_sel_hi:[1,0]
	v_pk_mul_f32 v[202:203], v[202:203], v[230:231] op_sel_hi:[1,0]
	v_pk_fma_f32 v[238:239], v[52:53], v[198:199], v[56:57]
	v_pk_mul_f32 v[198:199], v[212:213], v[230:231] op_sel_hi:[1,0]
	v_pk_fma_f32 v[202:203], v[60:61], v[202:203], v[64:65]
	v_pk_fma_f32 v[212:213], v[42:43], v[198:199], v[46:47]
	v_pk_mul_f32 v[198:199], v[220:221], v[230:231] op_sel_hi:[1,0]
	v_pk_mul_f32 v[200:201], v[200:201], v[230:231] op_sel_hi:[1,0]
	v_pk_fma_f32 v[220:221], v[44:45], v[198:199], v[48:49]
	v_pk_mul_f32 v[198:199], v[242:243], v[230:231] op_sel_hi:[1,0]
	v_pk_fma_f32 v[236:237], v[50:51], v[200:201], v[54:55]
	v_pk_fma_f32 v[240:241], v[34:35], v[198:199], v[38:39]
	v_pk_mul_f32 v[198:199], v[244:245], v[230:231] op_sel_hi:[1,0]
	v_pk_mul_f32 v[206:207], v[206:207], v[230:231] op_sel_hi:[1,0]
	v_pk_fma_f32 v[242:243], v[36:37], v[198:199], v[40:41]
	v_cvt_pk_f16_f32 v199, v202, v203
	v_pk_fma_f32 v[202:203], v[154:155], v[202:203], v[88:89]
	v_pk_fma_f32 v[206:207], v[58:59], v[206:207], v[62:63]
	v_cvt_pk_bf16_f32 v235, v202, v203
	v_pk_fma_f32 v[202:203], v[120:121], v[236:237], v[82:83]
	v_cvt_pk_f16_f32 v200, v236, v237
	v_cvt_pk_bf16_f32 v236, v202, v203
	v_pk_fma_f32 v[202:203], v[118:119], v[238:239], v[84:85]
	v_cvt_pk_f16_f32 v198, v206, v207
	v_cvt_pk_f16_f32 v201, v238, v239
	v_cvt_pk_bf16_f32 v237, v202, v203
	s_waitcnt vmcnt(0)
	v_pk_fma_f32 v[202:203], v[116:117], v[212:213], v[110:111]
	v_cvt_pk_f16_f32 v230, v212, v213
	v_cvt_pk_f16_f32 v231, v220, v221
	v_cvt_pk_f16_f32 v232, v240, v241
	v_cvt_pk_f16_f32 v233, v242, v243
	v_cvt_pk_bf16_f32 v238, v202, v203
	v_pk_fma_f32 v[202:203], v[162:163], v[220:221], v[112:113]
	global_store_dwordx4 v0, v[198:201], s[16:17] nt
	global_store_dwordx4 v0, v[230:233], s[16:17] offset:1024 nt
	v_cvt_pk_bf16_f32 v239, v202, v203
	v_pk_fma_f32 v[198:199], v[158:159], v[242:243], v[104:105]
	v_pk_fma_f32 v[202:203], v[160:161], v[240:241], v[102:103]
	v_cvt_pk_bf16_f32 v241, v198, v199
	v_pk_mul_f32 v[96:97], v[96:97], s[74:75] op_sel_hi:[1,0]
	v_pk_fma_f32 v[198:199], v[22:23], v[138:139], v[94:95]
	v_pk_mul_f32 v[92:93], v[92:93], s[74:75] op_sel_hi:[1,0]
	v_pk_fma_f32 v[90:91], v[18:19], v[134:135], v[90:91]
	v_pk_mul_f32 v[108:109], v[108:109], s[74:75] op_sel_hi:[1,0]
	v_pk_fma_f32 v[152:153], v[30:31], v[152:153], v[106:107]
	v_pk_mul_f32 v[100:101], v[100:101], s[74:75] op_sel_hi:[1,0]
	v_pk_fma_f32 v[148:149], v[26:27], v[148:149], v[98:99]
	v_pk_fma_f32 v[140:141], v[24:25], v[140:141], v[96:97]
	v_pk_fma_f32 v[92:93], v[20:21], v[136:137], v[92:93]
	v_mov_b32_e32 v94, v90
	v_mov_b32_e32 v95, v198
	v_mov_b32_e32 v96, v91
	v_mov_b32_e32 v97, v199
	v_pk_fma_f32 v[156:157], v[32:33], v[156:157], v[108:109]
	v_pk_fma_f32 v[150:151], v[28:29], v[150:151], v[100:101]
	v_mov_b32_e32 v98, v148
	v_mov_b32_e32 v99, v152
	v_mov_b32_e32 v100, v149
	v_mov_b32_e32 v101, v153
	v_pk_add_f32 v[94:95], v[94:95], v[96:97]
	v_mov_b32_e32 v96, v92
	v_mov_b32_e32 v97, v140
	v_pk_add_f32 v[98:99], v[98:99], v[100:101]
	v_mov_b32_e32 v100, v150
	v_mov_b32_e32 v101, v156
	v_pk_add_f32 v[94:95], v[96:97], v[94:95]
	v_mov_b32_e32 v96, v93
	v_mov_b32_e32 v97, v141
	v_pk_add_f32 v[98:99], v[100:101], v[98:99]
	v_mov_b32_e32 v100, v151
	v_mov_b32_e32 v101, v157
	v_pk_add_f32 v[94:95], v[96:97], v[94:95]
	v_pk_add_f32 v[98:99], v[100:101], v[98:99]
	v_add_f32_e32 v94, v94, v95
	v_add_f32_e32 v94, v94, v98
	v_add_f32_e32 v94, v94, v99
	v_mov_b32_e32 v95, v94
	s_nop 1
	v_permlane32_swap_b32_e32 v95, v94
	v_mul_f32_e32 v96, 0x4b800000, v246
	v_cmp_gt_f32_e32 vcc, s96, v246
	v_pk_mul_f32 v[70:71], v[70:71], s[74:75] op_sel_hi:[1,0]
	v_pk_mul_f32 v[66:67], v[66:67], s[74:75] op_sel_hi:[1,0]
	v_cndmask_b32_e32 v96, v246, v96, vcc
	v_rsq_f32_e32 v96, v96
	s_waitcnt lgkmcnt(0)
	v_add_f32_e32 v95, v94, v95
	v_mov_b32_e32 v98, v95
	s_nop 1
	v_permlane16_swap_b32_e32 v98, v95
	v_pk_mul_f32 v[78:79], v[78:79], s[74:75] op_sel_hi:[1,0]
	v_mul_f32_e32 v94, 0x45800000, v96
	v_cndmask_b32_e32 v94, v96, v94, vcc
	v_pk_mul_f32 v[96:97], v[184:185], v[94:95] op_sel_hi:[1,0]
	s_waitcnt lgkmcnt(0)
	v_add_f32_e32 v95, v95, v98
	s_nop 1
	v_mov_b32_dpp v98, v95 row_ror:8 row_mask:0xf bank_mask:0xf
	v_pk_fma_f32 v[184:185], v[58:59], v[96:97], v[62:63]
	v_pk_mul_f32 v[96:97], v[182:183], v[94:95] op_sel_hi:[1,0]
	v_pk_mul_f32 v[74:75], v[74:75], s[74:75] op_sel_hi:[1,0]
	v_pk_fma_f32 v[182:183], v[60:61], v[96:97], v[64:65]
	v_pk_mul_f32 v[96:97], v[180:181], v[94:95] op_sel_hi:[1,0]
	s_waitcnt lgkmcnt(0)
	v_add_f32_e32 v95, v95, v98
	s_nop 1
	v_mov_b32_dpp v98, v95 row_ror:4 row_mask:0xf bank_mask:0xf
	v_pk_fma_f32 v[134:135], v[50:51], v[96:97], v[54:55]
	v_pk_mul_f32 v[96:97], v[178:179], v[94:95] op_sel_hi:[1,0]
	v_pk_mul_f32 v[72:73], v[72:73], s[74:75] op_sel_hi:[1,0]
	v_pk_fma_f32 v[136:137], v[52:53], v[96:97], v[56:57]
	v_pk_mul_f32 v[96:97], v[194:195], v[94:95] op_sel_hi:[1,0]
	s_waitcnt lgkmcnt(0)
; DI float wave_sum(float v) {
; #pragma unroll
;   for (int o = 32; o > 0; o >>= 1) v += __shfl_xor(v, o);
;   return v;
; template <bool OUT16>
; DI void ln_finish(const LnRow& r, float* hout, unsigned short* hout16, bf16_t* yu, const LnVec& g, const LnVec& b, const LnVec& sc, const LnVec& sh, int c0, bool wr_u) {
;   const float sum = (r.z0.x + r.z0.y + r.z0.z + r.z0.w) + (r.z1.x + r.z1.y + r.z1.z + r.z1.w) + (r.z2.x + r.z2.y + r.z2.z + r.z2.w) + (r.z3.x + r.z3.y + r.z3.z + r.z3.w);
;   const float mean = wave_sum(sum) * (1.f / 1024.f);
;   const float sq = sq4(r.z0, mean) + sq4(r.z1, mean) + sq4(r.z2, mean) + sq4(r.z3, mean);
;   const float rstd = rsqrtf(wave_sum(sq) * (1.f / 1024.f) + 1e-5f);
	v_add_f32_e32 v95, v95, v98
	s_nop 1
	v_mov_b32_dpp v98, v95 quad_perm:[2,3,0,1] row_mask:0xf bank_mask:0xf
	v_pk_fma_f32 v[70:71], v[22:23], v[172:173], v[70:71]
	v_pk_mul_f32 v[68:69], v[68:69], s[74:75] op_sel_hi:[1,0]
	v_pk_fma_f32 v[66:67], v[18:19], v[168:169], v[66:67]
	v_pk_fma_f32 v[106:107], v[42:43], v[96:97], v[46:47]
	s_waitcnt lgkmcnt(0)
	v_add_f32_e32 v139, v95, v98
	s_nop 1
	v_mov_b32_dpp v178, v139 quad_perm:[1,0,3,2] row_mask:0xf bank_mask:0xf
	v_pk_mul_f32 v[96:97], v[192:193], v[94:95] op_sel_hi:[1,0]
	v_pk_mul_f32 v[80:81], v[80:81], s[74:75] op_sel_hi:[1,0]
	v_pk_fma_f32 v[78:79], v[30:31], v[196:197], v[78:79]
	v_pk_mul_f32 v[76:77], v[76:77], s[74:75] op_sel_hi:[1,0]
	v_pk_fma_f32 v[74:75], v[26:27], v[176:177], v[74:75]
	v_pk_fma_f32 v[72:73], v[24:25], v[174:175], v[72:73]
	v_pk_fma_f32 v[68:69], v[20:21], v[170:171], v[68:69]
	v_mov_b32_e32 v168, v66
	v_mov_b32_e32 v169, v70
	v_mov_b32_e32 v170, v67
	v_mov_b32_e32 v171, v71
	v_pk_fma_f32 v[108:109], v[44:45], v[96:97], v[48:49]
	v_pk_mul_f32 v[96:97], v[190:191], v[94:95] op_sel_hi:[1,0]
	v_pk_mul_f32 v[94:95], v[186:187], v[94:95] op_sel_hi:[1,0]
	v_pk_fma_f32 v[80:81], v[32:33], v[204:205], v[80:81]
	v_pk_fma_f32 v[76:77], v[28:29], v[188:189], v[76:77]
	v_mov_b32_e32 v176, v74
	v_mov_b32_e32 v177, v78
	v_mov_b32_e32 v186, v75
	v_mov_b32_e32 v187, v79
	v_pk_add_f32 v[168:169], v[168:169], v[170:171]
	v_mov_b32_e32 v170, v68
	v_mov_b32_e32 v171, v72
	v_pk_add_f32 v[176:177], v[176:177], v[186:187]
	v_mov_b32_e32 v186, v76
	v_mov_b32_e32 v187, v80
	v_pk_add_f32 v[168:169], v[170:171], v[168:169]
	v_mov_b32_e32 v170, v69
	v_mov_b32_e32 v171, v73
	v_pk_add_f32 v[176:177], v[186:187], v[176:177]
	v_mov_b32_e32 v186, v77
	v_mov_b32_e32 v187, v81
	v_pk_add_f32 v[168:169], v[170:171], v[168:169]
	v_pk_fma_f32 v[100:101], v[36:37], v[94:95], v[40:41]
	s_waitcnt lgkmcnt(0)
	v_add_f32_e32 v94, v139, v178
	v_pk_add_f32 v[176:177], v[186:187], v[176:177]
	v_add_f32_e32 v139, v168, v169
	v_add_f32_e32 v139, v139, v176
	v_add_f32_e32 v139, v139, v177
	v_mov_b32_e32 v170, v139
	s_nop 1
	v_permlane32_swap_b32_e32 v170, v139
	v_mul_f32_e32 v178, 0x3a800000, v94
	v_pk_fma_f32 v[98:99], v[34:35], v[96:97], v[38:39]
	v_pk_add_f32 v[96:97], v[90:91], v[178:179] op_sel_hi:[1,0] neg_lo:[0,1] neg_hi:[0,1]
	v_pk_add_f32 v[94:95], v[92:93], v[178:179] op_sel_hi:[1,0] neg_lo:[0,1] neg_hi:[0,1]
	s_waitcnt lgkmcnt(0)
	v_add_f32_e32 v139, v139, v170
	v_mov_b32_e32 v170, v139
	s_nop 1
	v_permlane16_swap_b32_e32 v170, v139
	v_pk_add_f32 v[92:93], v[198:199], v[178:179] op_sel_hi:[1,0] neg_lo:[0,1] neg_hi:[0,1]
	v_mov_b32_e32 v180, v97
	v_mov_b32_e32 v181, v93
	v_pk_add_f32 v[90:91], v[140:141], v[178:179] op_sel_hi:[1,0] neg_lo:[0,1] neg_hi:[0,1]
	v_mov_b32_e32 v140, v96
	v_mov_b32_e32 v141, v92
	v_pk_mul_f32 v[168:169], v[180:181], v[180:181]
	s_waitcnt lgkmcnt(0)
	v_add_f32_e32 v139, v139, v170
	v_pk_fma_f32 v[140:141], v[140:141], v[140:141], v[168:169]
	v_mov_b32_e32 v168, v94
	v_mov_b32_e32 v169, v90
	v_pk_fma_f32 v[140:141], v[168:169], v[168:169], v[140:141]
	v_mov_b32_e32 v168, v95
	v_mov_b32_e32 v169, v91
	v_pk_fma_f32 v[140:141], v[168:169], v[168:169], v[140:141]
	s_nop 1
	v_mov_b32_dpp v168, v139 row_ror:8 row_mask:0xf bank_mask:0xf
	v_pk_add_f32 v[148:149], v[148:149], v[178:179] op_sel_hi:[1,0] neg_lo:[0,1] neg_hi:[0,1]
	v_pk_add_f32 v[152:153], v[152:153], v[178:179] op_sel_hi:[1,0] neg_lo:[0,1] neg_hi:[0,1]
	v_mov_b32_e32 v171, v149
	v_mov_b32_e32 v170, v153
	s_waitcnt lgkmcnt(0)
	v_add_f32_e32 v139, v139, v168
	s_nop 1
	v_mov_b32_dpp v172, v139 row_ror:4 row_mask:0xf bank_mask:0xf
	v_pk_add_f32 v[150:151], v[150:151], v[178:179] op_sel_hi:[1,0] neg_lo:[0,1] neg_hi:[0,1]
	v_pk_add_f32 v[156:157], v[156:157], v[178:179] op_sel_hi:[1,0] neg_lo:[0,1] neg_hi:[0,1]
	v_mov_b32_e32 v168, v152
	v_mov_b32_e32 v169, v148
	s_waitcnt lgkmcnt(0)
	v_add_f32_e32 v139, v139, v172
	s_nop 1
	v_mov_b32_dpp v172, v139 quad_perm:[2,3,0,1] row_mask:0xf bank_mask:0xf
	v_pk_mul_f32 v[170:171], v[170:171], v[170:171]
	v_pk_fma_f32 v[206:207], v[114:115], v[206:207], v[86:87]
	v_pk_fma_f32 v[168:169], v[168:169], v[168:169], v[170:171]
	v_mov_b32_e32 v170, v156
	s_waitcnt lgkmcnt(0)
	v_add_f32_e32 v139, v139, v172
	s_nop 1
	v_mov_b32_dpp v172, v139 quad_perm:[1,0,3,2] row_mask:0xf bank_mask:0xf
	v_mov_b32_e32 v171, v150
	v_pk_fma_f32 v[168:169], v[170:171], v[170:171], v[168:169]
	v_mov_b32_e32 v170, v157
	v_mov_b32_e32 v171, v151
	s_waitcnt lgkmcnt(0)
	v_add_f32_e32 v139, v139, v172
	v_pk_fma_f32 v[168:169], v[170:171], v[170:171], v[168:169]
	v_mul_f32_e32 v170, 0x3a800000, v139
	v_pk_add_f32 v[172:173], v[66:67], v[170:171] op_sel_hi:[1,0] neg_lo:[0,1] neg_hi:[0,1]
	v_pk_add_f32 v[176:177], v[70:71], v[170:171] op_sel_hi:[1,0] neg_lo:[0,1] neg_hi:[0,1]
	v_pk_add_f32 v[174:175], v[68:69], v[170:171] op_sel_hi:[1,0] neg_lo:[0,1] neg_hi:[0,1]
	v_mov_b32_e32 v68, v173
	v_mov_b32_e32 v69, v177
	v_pk_add_f32 v[178:179], v[72:73], v[170:171] op_sel_hi:[1,0] neg_lo:[0,1] neg_hi:[0,1]
	v_mov_b32_e32 v66, v172
	v_mov_b32_e32 v67, v176
	v_pk_mul_f32 v[68:69], v[68:69], v[68:69]
	v_pk_add_f32 v[74:75], v[74:75], v[170:171] op_sel_hi:[1,0] neg_lo:[0,1] neg_hi:[0,1]
	v_pk_fma_f32 v[66:67], v[66:67], v[66:67], v[68:69]
	v_mov_b32_e32 v68, v174
	v_mov_b32_e32 v69, v178
	v_pk_add_f32 v[78:79], v[78:79], v[170:171] op_sel_hi:[1,0] neg_lo:[0,1] neg_hi:[0,1]
	v_pk_fma_f32 v[66:67], v[68:69], v[68:69], v[66:67]
	v_mov_b32_e32 v68, v175
	v_mov_b32_e32 v69, v179
	v_mov_b32_e32 v70, v79
	v_mov_b32_e32 v71, v75
	v_pk_fma_f32 v[66:67], v[68:69], v[68:69], v[66:67]
	v_pk_add_f32 v[76:77], v[76:77], v[170:171] op_sel_hi:[1,0] neg_lo:[0,1] neg_hi:[0,1]
	v_pk_add_f32 v[80:81], v[80:81], v[170:171] op_sel_hi:[1,0] neg_lo:[0,1] neg_hi:[0,1]
	v_mov_b32_e32 v68, v78
	v_mov_b32_e32 v69, v74
	v_pk_mul_f32 v[70:71], v[70:71], v[70:71]
	v_cvt_pk_bf16_f32 v234, v206, v207
	v_pk_fma_f32 v[68:69], v[68:69], v[68:69], v[70:71]
	v_mov_b32_e32 v70, v80
	v_mov_b32_e32 v71, v76
	v_pk_fma_f32 v[68:69], v[70:71], v[70:71], v[68:69]
	v_mov_b32_e32 v70, v81
	v_mov_b32_e32 v71, v77
	v_pk_fma_f32 v[68:69], v[70:71], v[70:71], v[68:69]
	v_mov_b32_e32 v70, v66
	v_mov_b32_e32 v71, v140
	v_mov_b32_e32 v140, v67
	v_pk_add_f32 v[66:67], v[70:71], v[140:141]
	v_mov_b32_e32 v70, v69
	v_mov_b32_e32 v71, v169
	v_pk_add_f32 v[66:67], v[70:71], v[66:67]
	v_mov_b32_e32 v69, v168
	v_pk_add_f32 v[68:69], v[68:69], v[66:67]
	v_mov_b32_e32 v71, v69
	s_nop 1
	v_permlane32_swap_b32_e32 v71, v69
	v_mov_b32_e32 v70, v68
	s_nop 1
	v_permlane32_swap_b32_e32 v70, v68
	v_cvt_pk_bf16_f32 v240, v202, v203
	v_cvt_pk_f16_f32 v66, v106, v107
	v_cvt_pk_f16_f32 v67, v108, v109
	global_store_dwordx4 v0, v[234:237], s[14:15]
	s_waitcnt lgkmcnt(0)
; DI unsigned pkh2(float lo, float hi) { f32x2 v = {lo, hi}; return __builtin_bit_cast(unsigned, __builtin_convertvector(v, h16x2)); }
; DI unsigned umod(float a, float b, float sca, float scb, float sha, float shb) { return pk2(a * (1.f + sca) + sha, b * (1.f + scb) + shb); }
; template <bool OUT16>
; DI void ln_finish(const LnRow& r, float* hout, unsigned short* hout16, bf16_t* yu, const LnVec& g, const LnVec& b, const LnVec& sc, const LnVec& sh, int c0, bool wr_u) {
;     ...
;   const float sq = sq4(r.z0, mean) + sq4(r.z1, mean) + sq4(r.z2, mean) + sq4(r.z3, mean);
;   const float rstd = rsqrtf(wave_sum(sq) * (1.f / 1024.f) + 1e-5f);
;   const float4 o0 = ln_norm(r.z0, mean, rstd, g.a, b.a), o1 = ln_norm(r.z1, mean, rstd, g.b, b.b), o2 = ln_norm(r.z2, mean, rstd, g.c, b.c), o3 = ln_norm(r.z3, mean, rstd, g.d, b.d);
;   if (OUT16) {
;     u32x4 wa, wb;
;     wa[0] = pkh2(o0.x, o0.y); wa[1] = pkh2(o0.z, o0.w); wa[2] = pkh2(o1.x, o1.y); wa[3] = pkh2(o1.z, o1.w);
;     wb[0] = pkh2(o2.x, o2.y); wb[1] = pkh2(o2.z, o2.w); wb[2] = pkh2(o3.x, o3.y); wb[3] = pkh2(o3.z, o3.w);
;     __builtin_nontemporal_store(wa, (u32x4*)(hout16 + c0));
;     __builtin_nontemporal_store(wb, (u32x4*)(hout16 + 512 + c0));
;   } else {
;     f32x4 v;
;     v[0] = o0.x; v[1] = o0.y; v[2] = o0.z; v[3] = o0.w; __builtin_nontemporal_store(v, (f32x4*)(hout + c0));
;     v[0] = o1.x; v[1] = o1.y; v[2] = o1.z; v[3] = o1.w; __builtin_nontemporal_store(v, (f32x4*)(hout + c0 + 4));
;     v[0] = o2.x; v[1] = o2.y; v[2] = o2.z; v[3] = o2.w; __builtin_nontemporal_store(v, (f32x4*)(hout + 512 + c0));
;     v[0] = o3.x; v[1] = o3.y; v[2] = o3.z; v[3] = o3.w; __builtin_nontemporal_store(v, (f32x4*)(hout + 512 + c0 + 4));
;   }
;   if (wr_u) {
;     uint4 ua, ub;
;     ua.x = umod(o0.x, o0.y, sc.a.x, sc.a.y, sh.a.x, sh.a.y); ua.y = umod(o0.z, o0.w, sc.a.z, sc.a.w, sh.a.z, sh.a.w);
;     ua.z = umod(o1.x, o1.y, sc.b.x, sc.b.y, sh.b.x, sh.b.y); ua.w = umod(o1.z, o1.w, sc.b.z, sc.b.w, sh.b.z, sh.b.w);
;     ub.x = umod(o2.x, o2.y, sc.c.x, sc.c.y, sh.c.x, sh.c.y); ub.y = umod(o2.z, o2.w, sc.c.z, sc.c.w, sh.c.z, sh.c.w);
;     ub.z = umod(o3.x, o3.y, sc.d.x, sc.d.y, sh.d.x, sh.d.y); ub.w = umod(o3.z, o3.w, sc.d.z, sc.d.w, sh.d.z, sh.d.w);
;     *(uint4*)(yu + c0) = ua;
;     *(uint4*)(yu + 512 + c0) = ub;
;   }
	v_pk_add_f32 v[70:71], v[68:69], v[70:71]
	v_mov_b32_e32 v73, v71
	s_nop 1
	v_permlane16_swap_b32_e32 v73, v71
	v_mov_b32_e32 v72, v70
	s_nop 1
	v_permlane16_swap_b32_e32 v72, v70
	v_cvt_pk_f16_f32 v68, v98, v99
	v_cvt_pk_f16_f32 v69, v100, v101
	global_store_dwordx4 v0, v[238:241], s[14:15] offset:1024
	global_store_dwordx4 v0, v[66:69], s[16:17] offset:3072 nt
	s_waitcnt lgkmcnt(0)
	v_pk_add_f32 v[70:71], v[70:71], v[72:73]
	s_nop 1
	v_mov_b32_dpp v73, v71 row_ror:8 row_mask:0xf bank_mask:0xf
	s_nop 1
	v_mov_b32_dpp v72, v70 row_ror:8 row_mask:0xf bank_mask:0xf
	v_pk_fma_f32 v[66:67], v[114:115], v[184:185], v[86:87]
	v_pk_fma_f32 v[68:69], v[154:155], v[182:183], v[88:89]
	v_cvt_pk_f16_f32 v140, v134, v135
	v_cvt_pk_f16_f32 v141, v136, v137
	s_waitcnt lgkmcnt(0)
	v_pk_add_f32 v[70:71], v[70:71], v[72:73]
	s_nop 1
	v_mov_b32_dpp v73, v71 row_ror:4 row_mask:0xf bank_mask:0xf
	s_nop 1
	v_mov_b32_dpp v72, v70 row_ror:4 row_mask:0xf bank_mask:0xf
	v_cvt_pk_bf16_f32 v66, v66, v67
	v_cvt_pk_bf16_f32 v67, v68, v69
	v_pk_fma_f32 v[68:69], v[120:121], v[134:135], v[82:83]
	v_pk_fma_f32 v[134:135], v[118:119], v[136:137], v[84:85]
	s_waitcnt lgkmcnt(0)
	v_pk_add_f32 v[72:73], v[70:71], v[72:73]
	s_nop 1
	v_mov_b32_dpp v137, v73 quad_perm:[2,3,0,1] row_mask:0xf bank_mask:0xf
	s_nop 1
	v_mov_b32_dpp v136, v72 quad_perm:[2,3,0,1] row_mask:0xf bank_mask:0xf
	v_pk_fma_f32 v[70:71], v[116:117], v[106:107], v[110:111]
	v_pk_fma_f32 v[106:107], v[162:163], v[108:109], v[112:113]
	v_cvt_pk_bf16_f32 v68, v68, v69
	v_cvt_pk_bf16_f32 v69, v134, v135
	s_waitcnt lgkmcnt(0)
	v_pk_add_f32 v[108:109], v[72:73], v[136:137]
	s_nop 1
	v_mov_b32_dpp v135, v109 quad_perm:[1,0,3,2] row_mask:0xf bank_mask:0xf
	s_nop 1
	v_mov_b32_dpp v134, v108 quad_perm:[1,0,3,2] row_mask:0xf bank_mask:0xf
	v_pk_fma_f32 v[72:73], v[160:161], v[98:99], v[102:103]
	v_pk_fma_f32 v[98:99], v[158:159], v[100:101], v[104:105]
	v_cvt_pk_bf16_f32 v72, v72, v73
	v_cvt_pk_f16_f32 v138, v184, v185
	s_waitcnt lgkmcnt(0)
; DI unsigned pkh2(float lo, float hi) { f32x2 v = {lo, hi}; return __builtin_bit_cast(unsigned, __builtin_convertvector(v, h16x2)); }
; DI unsigned umod(float a, float b, float sca, float scb, float sha, float shb) { return pk2(a * (1.f + sca) + sha, b * (1.f + scb) + shb); }
; template <bool OUT16>
; DI void ln_finish(const LnRow& r, float* hout, unsigned short* hout16, bf16_t* yu, const LnVec& g, const LnVec& b, const LnVec& sc, const LnVec& sh, int c0, bool wr_u) {
;     ...
;   const float rstd = rsqrtf(wave_sum(sq) * (1.f / 1024.f) + 1e-5f);
;   const float4 o0 = ln_norm(r.z0, mean, rstd, g.a, b.a), o1 = ln_norm(r.z1, mean, rstd, g.b, b.b), o2 = ln_norm(r.z2, mean, rstd, g.c, b.c), o3 = ln_norm(r.z3, mean, rstd, g.d, b.d);
;   if (OUT16) {
;     u32x4 wa, wb;
;     wa[0] = pkh2(o0.x, o0.y); wa[1] = pkh2(o0.z, o0.w); wa[2] = pkh2(o1.x, o1.y); wa[3] = pkh2(o1.z, o1.w);
;     wb[0] = pkh2(o2.x, o2.y); wb[1] = pkh2(o2.z, o2.w); wb[2] = pkh2(o3.x, o3.y); wb[3] = pkh2(o3.z, o3.w);
;     __builtin_nontemporal_store(wa, (u32x4*)(hout16 + c0));
;     __builtin_nontemporal_store(wb, (u32x4*)(hout16 + 512 + c0));
;   } else {
;     f32x4 v;
;     v[0] = o0.x; v[1] = o0.y; v[2] = o0.z; v[3] = o0.w; __builtin_nontemporal_store(v, (f32x4*)(hout + c0));
;     v[0] = o1.x; v[1] = o1.y; v[2] = o1.z; v[3] = o1.w; __builtin_nontemporal_store(v, (f32x4*)(hout + c0 + 4));
;     v[0] = o2.x; v[1] = o2.y; v[2] = o2.z; v[3] = o2.w; __builtin_nontemporal_store(v, (f32x4*)(hout + 512 + c0));
;     v[0] = o3.x; v[1] = o3.y; v[2] = o3.z; v[3] = o3.w; __builtin_nontemporal_store(v, (f32x4*)(hout + 512 + c0 + 4));
;   }
;   if (wr_u) {
;     uint4 ua, ub;
;     ua.x = umod(o0.x, o0.y, sc.a.x, sc.a.y, sh.a.x, sh.a.y); ua.y = umod(o0.z, o0.w, sc.a.z, sc.a.w, sh.a.z, sh.a.w);
;     ua.z = umod(o1.x, o1.y, sc.b.x, sc.b.y, sh.b.x, sh.b.y); ua.w = umod(o1.z, o1.w, sc.b.z, sc.b.w, sh.b.z, sh.b.w);
;     ub.x = umod(o2.x, o2.y, sc.c.x, sc.c.y, sh.c.x, sh.c.y); ub.y = umod(o2.z, o2.w, sc.c.z, sc.c.w, sh.c.z, sh.c.w);
;     ub.z = umod(o3.x, o3.y, sc.d.x, sc.d.y, sh.d.x, sh.d.y); ub.w = umod(o3.z, o3.w, sc.d.z, sc.d.w, sh.d.z, sh.d.w);
;     *(uint4*)(yu + c0) = ua;
;     *(uint4*)(yu + 512 + c0) = ub;
;   }
	v_pk_add_f32 v[100:101], v[108:109], v[134:135]
	v_cvt_pk_f16_f32 v139, v182, v183
	v_pk_fma_f32 v[100:101], v[100:101], s[18:19], v[166:167] op_sel_hi:[1,0,0]
	v_lshl_add_u64 v[164:165], s[16:17], 0, v[0:1]
	v_mul_f32_e32 v73, 0x4b800000, v101
	v_cmp_gt_f32_e32 vcc, s96, v101
	global_store_dwordx4 v0, v[138:141], s[16:17] offset:2048 nt
	v_cvt_pk_bf16_f32 v70, v70, v71
	v_cndmask_b32_e32 v73, v101, v73, vcc
	v_rsq_f32_e32 v101, v73
	v_cvt_pk_bf16_f32 v71, v106, v107
	v_cvt_pk_bf16_f32 v73, v98, v99
	global_store_dwordx4 v0, v[66:69], s[14:15] offset:2048
	global_store_dwordx4 v0, v[70:73], s[14:15] offset:3072
	v_mul_f32_e32 v0, 0x45800000, v101
	v_cndmask_b32_e32 v0, v101, v0, vcc
	v_pk_mul_f32 v[66:67], v[96:97], v[0:1] op_sel_hi:[1,0]
	v_add_co_u32_e32 v136, vcc, s91, v164
	v_pk_fma_f32 v[96:97], v[58:59], v[66:67], v[62:63]
	v_pk_mul_f32 v[66:67], v[94:95], v[0:1] op_sel_hi:[1,0]
	v_addc_co_u32_e32 v137, vcc, 0, v165, vcc
	v_pk_fma_f32 v[94:95], v[60:61], v[66:67], v[64:65]
	v_pk_mul_f32 v[66:67], v[92:93], v[0:1] op_sel_hi:[1,0]
	v_cmp_gt_f32_e32 vcc, s96, v100
	v_pk_fma_f32 v[92:93], v[50:51], v[66:67], v[54:55]
	v_pk_mul_f32 v[66:67], v[90:91], v[0:1] op_sel_hi:[1,0]
	v_cvt_pk_f16_f32 v68, v92, v93
	v_pk_fma_f32 v[90:91], v[52:53], v[66:67], v[56:57]
	v_pk_mul_f32 v[66:67], v[148:149], v[0:1] op_sel_hi:[1,0]
	v_cvt_pk_f16_f32 v69, v90, v91
	v_pk_fma_f32 v[98:99], v[42:43], v[66:67], v[46:47]
	v_pk_mul_f32 v[66:67], v[150:151], v[0:1] op_sel_hi:[1,0]
	v_cvt_pk_f16_f32 v70, v98, v99
	v_pk_fma_f32 v[106:107], v[44:45], v[66:67], v[48:49]
	v_pk_mul_f32 v[66:67], v[152:153], v[0:1] op_sel_hi:[1,0]
	v_cvt_pk_f16_f32 v71, v106, v107
	v_pk_fma_f32 v[108:109], v[34:35], v[66:67], v[38:39]
	v_pk_mul_f32 v[66:67], v[156:157], v[0:1] op_sel_hi:[1,0]
	v_mul_f32_e32 v0, 0x4b800000, v100
	v_pk_fma_f32 v[134:135], v[36:37], v[66:67], v[40:41]
	v_cvt_pk_f16_f32 v66, v96, v97
	v_cvt_pk_f16_f32 v67, v94, v95
	v_cndmask_b32_e32 v0, v100, v0, vcc
	v_cvt_pk_f16_f32 v72, v108, v109
	v_cvt_pk_f16_f32 v73, v134, v135
	global_store_dwordx4 v[136:137], v[66:69], off nt
	global_store_dwordx4 v[136:137], v[70:73], off offset:1024 nt
	v_rsq_f32_e32 v0, v0
	v_pk_fma_f32 v[66:67], v[114:115], v[96:97], v[86:87]
	v_pk_fma_f32 v[68:69], v[154:155], v[94:95], v[88:89]
	v_cvt_pk_bf16_f32 v66, v66, v67
	v_cvt_pk_bf16_f32 v67, v68, v69
	v_pk_fma_f32 v[68:69], v[120:121], v[92:93], v[82:83]
	v_pk_fma_f32 v[70:71], v[118:119], v[90:91], v[84:85]
	v_cvt_pk_bf16_f32 v68, v68, v69
	v_cvt_pk_bf16_f32 v69, v70, v71
	v_pk_fma_f32 v[70:71], v[116:117], v[98:99], v[110:111]
	v_pk_fma_f32 v[72:73], v[162:163], v[106:107], v[112:113]
	v_cvt_pk_bf16_f32 v70, v70, v71
	v_cvt_pk_bf16_f32 v71, v72, v73
	v_pk_fma_f32 v[72:73], v[160:161], v[108:109], v[102:103]
	v_pk_fma_f32 v[90:91], v[158:159], v[134:135], v[104:105]
	v_cvt_pk_bf16_f32 v72, v72, v73
	v_cvt_pk_bf16_f32 v73, v90, v91
	global_store_dwordx4 v[132:133], v[66:69], off
	global_store_dwordx4 v[132:133], v[70:73], off offset:1024
	s_mov_b64 s[14:15], 0
	v_mul_f32_e32 v66, 0x45800000, v0
	v_cndmask_b32_e32 v0, v0, v66, vcc
	v_pk_mul_f32 v[66:67], v[172:173], v[0:1] op_sel_hi:[1,0]
	s_nop 0
	v_pk_fma_f32 v[58:59], v[58:59], v[66:67], v[62:63]
	v_pk_mul_f32 v[62:63], v[174:175], v[0:1] op_sel_hi:[1,0]
	s_nop 0
	v_pk_fma_f32 v[60:61], v[60:61], v[62:63], v[64:65]
	v_pk_mul_f32 v[62:63], v[176:177], v[0:1] op_sel_hi:[1,0]
	s_nop 0
	v_pk_fma_f32 v[50:51], v[50:51], v[62:63], v[54:55]
	v_pk_mul_f32 v[54:55], v[178:179], v[0:1] op_sel_hi:[1,0]
	s_nop 0
	v_pk_fma_f32 v[52:53], v[52:53], v[54:55], v[56:57]
	v_pk_mul_f32 v[54:55], v[74:75], v[0:1] op_sel_hi:[1,0]
	s_nop 0
	v_pk_fma_f32 v[42:43], v[42:43], v[54:55], v[46:47]
	v_pk_mul_f32 v[46:47], v[76:77], v[0:1] op_sel_hi:[1,0]
	s_nop 0
	v_pk_fma_f32 v[44:45], v[44:45], v[46:47], v[48:49]
	v_pk_mul_f32 v[46:47], v[78:79], v[0:1] op_sel_hi:[1,0]
	s_nop 0
	v_pk_fma_f32 v[46:47], v[34:35], v[46:47], v[38:39]
	v_pk_mul_f32 v[34:35], v[80:81], v[0:1] op_sel_hi:[1,0]
	v_cvt_pk_f16_f32 v38, v42, v43
	v_pk_fma_f32 v[48:49], v[36:37], v[34:35], v[40:41]
	v_cvt_pk_f16_f32 v34, v58, v59
	v_cvt_pk_f16_f32 v35, v60, v61
	v_cvt_pk_f16_f32 v36, v50, v51
	v_cvt_pk_f16_f32 v37, v52, v53
	v_cvt_pk_f16_f32 v39, v44, v45
	v_cvt_pk_f16_f32 v40, v46, v47
	v_cvt_pk_f16_f32 v41, v48, v49
	global_store_dwordx4 v[136:137], v[34:37], off offset:2048 nt
	global_store_dwordx4 v[136:137], v[38:41], off offset:3072 nt
	s_nop 0
	v_pk_fma_f32 v[34:35], v[114:115], v[58:59], v[86:87]
	v_pk_fma_f32 v[36:37], v[154:155], v[60:61], v[88:89]
	v_cvt_pk_bf16_f32 v34, v34, v35
	v_cvt_pk_bf16_f32 v35, v36, v37
	v_pk_fma_f32 v[36:37], v[120:121], v[50:51], v[82:83]
	v_pk_fma_f32 v[38:39], v[118:119], v[52:53], v[84:85]
	v_cvt_pk_bf16_f32 v36, v36, v37
	v_cvt_pk_bf16_f32 v37, v38, v39
	v_pk_fma_f32 v[38:39], v[116:117], v[42:43], v[110:111]
	v_pk_fma_f32 v[40:41], v[162:163], v[44:45], v[112:113]
	v_cvt_pk_bf16_f32 v38, v38, v39
	v_cvt_pk_bf16_f32 v39, v40, v41
	v_pk_fma_f32 v[40:41], v[160:161], v[46:47], v[102:103]
	v_pk_fma_f32 v[42:43], v[158:159], v[48:49], v[104:105]
	v_cvt_pk_bf16_f32 v40, v40, v41
	v_cvt_pk_bf16_f32 v41, v42, v43
	global_store_dwordx4 v[132:133], v[34:37], off offset:2048
	global_store_dwordx4 v[132:133], v[38:41], off offset:3072

; DI unsigned pk2(float lo, float hi) { f32x2 v = {lo, hi}; return __builtin_bit_cast(unsigned, __builtin_convertvector(v, bf16x2v)); }
; DI float4 ld_nt4(const float* p) { const f32x4 v = __builtin_nontemporal_load((const f32x4*)p); return make_float4(v[0], v[1], v[2], v[3]); }
; DI float4 h4lo(const u32x4 v) { return make_float4(hlo(v[0]), hhi(v[0]), hlo(v[1]), hhi(v[1])); }
; DI float4 h4hi(const u32x4 v) { return make_float4(hlo(v[2]), hhi(v[2]), hlo(v[3]), hhi(v[3])); }
; DI float wave_sum(float v) {
; #pragma unroll
;   for (int o = 32; o > 0; o >>= 1) v += __shfl_xor(v, o);
;   return v;
; template <bool IN16>
; DI LnRow ln_load(const float* hin, const unsigned short* hin16, const bf16_t* yu, const LnVec& gate, int c0) {
;   LnRow r;
;   const uint4 ya = *(const uint4*)(yu + c0), yb = *(const uint4*)(yu + 512 + c0);
;   float4 h0, h1, h2, h3;
;   if (IN16) {
;     const u32x4 ha = __builtin_nontemporal_load((const u32x4*)(hin16 + c0)), hb = __builtin_nontemporal_load((const u32x4*)(hin16 + 512 + c0));
;     h0 = h4lo(ha); h1 = h4hi(ha); h2 = h4lo(hb); h3 = h4hi(hb);
;   } else {
;     h0 = ld_nt4(hin + c0); h1 = ld_nt4(hin + c0 + 4); h2 = ld_nt4(hin + 512 + c0); h3 = ld_nt4(hin + 512 + c0 + 4);
;   }
;   r.z0 = zmix(h0, gate.a, b4lo(ya)); r.z1 = zmix(h1, gate.b, b4hi(ya)); r.z2 = zmix(h2, gate.c, b4lo(yb)); r.z3 = zmix(h3, gate.d, b4hi(yb));
;   return r;
; }
; DI float4 ln_norm(const float4 z, float mean, float rstd, const float4 g, const float4 b) {
;   return make_float4((z.x - mean) * rstd * g.x + b.x, (z.y - mean) * rstd * g.y + b.y, (z.z - mean) * rstd * g.z + b.z, (z.w - mean) * rstd * g.w + b.w);
; }
; DI unsigned umod(float a, float b, float sca, float scb, float sha, float shb) { return pk2(a * (1.f + sca) + sha, b * (1.f + scb) + shb); }
; template <bool OUT16>
; DI void ln_finish(const LnRow& r, float* hout, unsigned short* hout16, bf16_t* yu, const LnVec& g, const LnVec& b, const LnVec& sc, const LnVec& sh, int c0, bool wr_u) {
;   const float sum = (r.z0.x + r.z0.y + r.z0.z + r.z0.w) + (r.z1.x + r.z1.y + r.z1.z + r.z1.w) + (r.z2.x + r.z2.y + r.z2.z + r.z2.w) + (r.z3.x + r.z3.y + r.z3.z + r.z3.w);
;   const float mean = wave_sum(sum) * (1.f / 1024.f);
;   const float sq = sq4(r.z0, mean) + sq4(r.z1, mean) + sq4(r.z2, mean) + sq4(r.z3, mean);
.LBB0_198:
	s_lshl_b64 s[16:17], s[16:17], 11
	v_lshl_add_u64 v[56:57], v[128:129], 0, s[16:17]
	global_load_dwordx4 v[18:21], v[56:57], off
	global_load_dwordx4 v[22:25], v[56:57], off offset:1024
	global_load_dwordx4 v[34:37], v0, s[18:19] nt
	global_load_dwordx4 v[38:41], v0, s[18:19] offset:16 nt
	global_load_dwordx4 v[42:45], v0, s[18:19] offset:2048 nt
	global_load_dwordx4 v[46:49], v0, s[18:19] offset:2064 nt
	v_lshl_add_u64 v[62:63], s[10:11], 0, v[0:1]
	v_lshl_add_u64 v[60:61], v[62:63], 0, s[88:89]
	s_mov_b64 s[18:19], 0x1800
	v_lshl_add_u64 v[58:59], v[62:63], 0, s[18:19]
	s_add_u32 s14, s14, 1
	v_add_u32_e32 v82, -1, v82
	s_addc_u32 s15, s15, 0
	s_add_u32 s12, s12, 0x1000
	s_addc_u32 s13, s13, 0
	s_waitcnt vmcnt(5)
	v_lshlrev_b32_e32 v66, 16, v18
	v_and_b32_e32 v67, 0xffff0000, v18
	v_lshlrev_b32_e32 v76, 16, v20
	v_and_b32_e32 v77, 0xffff0000, v20
	s_waitcnt vmcnt(2)
	v_pk_mul_f32 v[38:39], v[38:39], s[74:75] op_sel_hi:[1,0]
	v_pk_mul_f32 v[34:35], v[34:35], s[74:75] op_sel_hi:[1,0]
	v_lshlrev_b32_e32 v74, 16, v19
	v_and_b32_e32 v75, 0xffff0000, v19
	v_lshlrev_b32_e32 v50, 16, v21
	v_and_b32_e32 v51, 0xffff0000, v21
	v_lshlrev_b32_e32 v52, 16, v22
	v_and_b32_e32 v53, 0xffff0000, v22
	v_lshlrev_b32_e32 v68, 16, v24
	v_and_b32_e32 v69, 0xffff0000, v24
	s_waitcnt vmcnt(0)
	v_pk_mul_f32 v[46:47], v[46:47], s[74:75] op_sel_hi:[1,0]
	v_pk_mul_f32 v[42:43], v[42:43], s[74:75] op_sel_hi:[1,0]
	v_pk_mul_f32 v[40:41], v[40:41], s[74:75] op_sel_hi:[1,0]
	v_pk_fma_f32 v[38:39], v[6:7], v[76:77], v[38:39]
	v_pk_mul_f32 v[36:37], v[36:37], s[74:75] op_sel_hi:[1,0]
	v_pk_fma_f32 v[34:35], v[2:3], v[66:67], v[34:35]
	v_lshlrev_b32_e32 v54, 16, v23
	v_and_b32_e32 v55, 0xffff0000, v23
	v_lshlrev_b32_e32 v18, 16, v25
	v_and_b32_e32 v19, 0xffff0000, v25
	v_pk_mul_f32 v[20:21], v[48:49], s[74:75] op_sel_hi:[1,0]
	v_pk_fma_f32 v[68:69], v[14:15], v[68:69], v[46:47]
	v_pk_mul_f32 v[44:45], v[44:45], s[74:75] op_sel_hi:[1,0]
	v_pk_fma_f32 v[72:73], v[10:11], v[52:53], v[42:43]
	v_pk_fma_f32 v[80:81], v[8:9], v[50:51], v[40:41]
	v_pk_fma_f32 v[36:37], v[4:5], v[74:75], v[36:37]
	v_mov_b32_e32 v66, v34
	v_mov_b32_e32 v67, v38
	v_mov_b32_e32 v74, v35
	v_mov_b32_e32 v75, v39
	v_pk_fma_f32 v[64:65], v[16:17], v[18:19], v[20:21]
	v_pk_fma_f32 v[70:71], v[12:13], v[54:55], v[44:45]
	v_mov_b32_e32 v42, v72
	v_mov_b32_e32 v43, v68
	v_mov_b32_e32 v44, v73
	v_mov_b32_e32 v45, v69
	v_pk_add_f32 v[66:67], v[66:67], v[74:75]
	v_mov_b32_e32 v74, v36
	v_mov_b32_e32 v75, v80
	v_pk_add_f32 v[42:43], v[42:43], v[44:45]
	v_mov_b32_e32 v44, v70
	v_mov_b32_e32 v45, v64
	v_pk_add_f32 v[66:67], v[74:75], v[66:67]
	v_mov_b32_e32 v74, v37
	v_mov_b32_e32 v75, v81
	v_pk_add_f32 v[42:43], v[44:45], v[42:43]
	v_mov_b32_e32 v44, v71
	v_mov_b32_e32 v45, v65
	v_pk_add_f32 v[66:67], v[74:75], v[66:67]
	v_pk_add_f32 v[78:79], v[44:45], v[42:43]
	v_add_f32_e32 v66, v66, v67
	v_add_f32_e32 v66, v66, v78
	v_add_f32_e32 v66, v66, v79
	v_mov_b32_e32 v67, v66
	s_nop 1
	v_permlane32_swap_b32_e32 v67, v66
	global_load_dwordx4 v[18:21], v[124:125], off offset:2064
	global_load_dwordx4 v[26:29], v[124:125], off offset:2048
	global_load_dwordx4 v[22:25], v[126:127], off offset:2064
	global_load_dwordx4 v[30:33], v[126:127], off offset:2048
	global_load_dwordx4 v[40:43], v[124:125], off offset:16
	global_load_dwordx4 v[48:51], v[124:125], off
	global_load_dwordx4 v[44:47], v[126:127], off offset:16
	global_load_dwordx4 v[52:55], v[126:127], off
	s_waitcnt lgkmcnt(0)
	v_add_f32_e32 v66, v66, v67
	v_mov_b32_e32 v67, v66
	s_nop 1
	v_permlane16_swap_b32_e32 v67, v66
	s_waitcnt lgkmcnt(0)
	v_add_f32_e32 v66, v66, v67
	s_nop 1
	v_mov_b32_dpp v67, v66 row_ror:8 row_mask:0xf bank_mask:0xf
	s_waitcnt lgkmcnt(0)
	v_add_f32_e32 v66, v66, v67
	s_nop 1
	v_mov_b32_dpp v67, v66 row_ror:4 row_mask:0xf bank_mask:0xf
	s_waitcnt lgkmcnt(0)
	v_add_f32_e32 v66, v66, v67
	s_nop 1
	v_mov_b32_dpp v67, v66 quad_perm:[2,3,0,1] row_mask:0xf bank_mask:0xf
	s_waitcnt lgkmcnt(0)
	v_add_f32_e32 v66, v66, v67
	s_nop 1
	v_mov_b32_dpp v67, v66 quad_perm:[1,0,3,2] row_mask:0xf bank_mask:0xf
	s_waitcnt lgkmcnt(0)
	v_add_f32_e32 v66, v66, v67
	v_mul_f32_e32 v66, 0x3a800000, v66
	v_pk_add_f32 v[34:35], v[34:35], v[66:67] op_sel_hi:[1,0] neg_lo:[0,1] neg_hi:[0,1]
	v_pk_add_f32 v[38:39], v[38:39], v[66:67] op_sel_hi:[1,0] neg_lo:[0,1] neg_hi:[0,1]
	v_mov_b32_e32 v78, v35
	v_mov_b32_e32 v79, v39
	v_pk_add_f32 v[36:37], v[36:37], v[66:67] op_sel_hi:[1,0] neg_lo:[0,1] neg_hi:[0,1]
	v_pk_add_f32 v[74:75], v[80:81], v[66:67] op_sel_hi:[1,0] neg_lo:[0,1] neg_hi:[0,1]
	v_mov_b32_e32 v76, v34
	v_mov_b32_e32 v77, v38
	v_pk_mul_f32 v[78:79], v[78:79], v[78:79]
	v_pk_add_f32 v[72:73], v[72:73], v[66:67] op_sel_hi:[1,0] neg_lo:[0,1] neg_hi:[0,1]
	v_pk_fma_f32 v[76:77], v[76:77], v[76:77], v[78:79]
	v_mov_b32_e32 v78, v36
	v_mov_b32_e32 v79, v74
	v_pk_fma_f32 v[76:77], v[78:79], v[78:79], v[76:77]
	v_mov_b32_e32 v78, v37
	v_mov_b32_e32 v79, v75
	v_pk_add_f32 v[68:69], v[68:69], v[66:67] op_sel_hi:[1,0] neg_lo:[0,1] neg_hi:[0,1]
	v_pk_fma_f32 v[76:77], v[78:79], v[78:79], v[76:77]
	v_mov_b32_e32 v78, v69
	v_mov_b32_e32 v79, v73
	v_pk_add_f32 v[70:71], v[70:71], v[66:67] op_sel_hi:[1,0] neg_lo:[0,1] neg_hi:[0,1]
	v_pk_add_f32 v[66:67], v[64:65], v[66:67] op_sel_hi:[1,0] neg_lo:[0,1] neg_hi:[0,1]
	v_mov_b32_e32 v64, v68
	v_mov_b32_e32 v65, v72
	v_pk_mul_f32 v[78:79], v[78:79], v[78:79]
	v_add_f32_e32 v76, v76, v77
	v_pk_fma_f32 v[64:65], v[64:65], v[64:65], v[78:79]
	v_mov_b32_e32 v78, v66
	v_mov_b32_e32 v79, v70
	v_pk_fma_f32 v[64:65], v[78:79], v[78:79], v[64:65]
	v_mov_b32_e32 v78, v67
	v_mov_b32_e32 v79, v71
	v_pk_fma_f32 v[64:65], v[78:79], v[78:79], v[64:65]
	s_nop 0
	v_add_f32_e32 v65, v65, v76
	v_add_f32_e32 v64, v64, v65
	v_mov_b32_e32 v65, v64
	s_nop 1
	v_permlane32_swap_b32_e32 v65, v64
	s_waitcnt lgkmcnt(0)
; DI unsigned pkh2(float lo, float hi) { f32x2 v = {lo, hi}; return __builtin_bit_cast(unsigned, __builtin_convertvector(v, h16x2)); }
; DI unsigned umod(float a, float b, float sca, float scb, float sha, float shb) { return pk2(a * (1.f + sca) + sha, b * (1.f + scb) + shb); }
; template <bool OUT16>
; DI void ln_finish(const LnRow& r, float* hout, unsigned short* hout16, bf16_t* yu, const LnVec& g, const LnVec& b, const LnVec& sc, const LnVec& sh, int c0, bool wr_u) {
;     ...
;   const float sq = sq4(r.z0, mean) + sq4(r.z1, mean) + sq4(r.z2, mean) + sq4(r.z3, mean);
;   const float rstd = rsqrtf(wave_sum(sq) * (1.f / 1024.f) + 1e-5f);
;   const float4 o0 = ln_norm(r.z0, mean, rstd, g.a, b.a), o1 = ln_norm(r.z1, mean, rstd, g.b, b.b), o2 = ln_norm(r.z2, mean, rstd, g.c, b.c), o3 = ln_norm(r.z3, mean, rstd, g.d, b.d);
;   if (OUT16) {
;     u32x4 wa, wb;
;     wa[0] = pkh2(o0.x, o0.y); wa[1] = pkh2(o0.z, o0.w); wa[2] = pkh2(o1.x, o1.y); wa[3] = pkh2(o1.z, o1.w);
;     wb[0] = pkh2(o2.x, o2.y); wb[1] = pkh2(o2.z, o2.w); wb[2] = pkh2(o3.x, o3.y); wb[3] = pkh2(o3.z, o3.w);
;     __builtin_nontemporal_store(wa, (u32x4*)(hout16 + c0));
;     __builtin_nontemporal_store(wb, (u32x4*)(hout16 + 512 + c0));
;   } else {
;     f32x4 v;
;     v[0] = o0.x; v[1] = o0.y; v[2] = o0.z; v[3] = o0.w; __builtin_nontemporal_store(v, (f32x4*)(hout + c0));
;     v[0] = o1.x; v[1] = o1.y; v[2] = o1.z; v[3] = o1.w; __builtin_nontemporal_store(v, (f32x4*)(hout + c0 + 4));
;     v[0] = o2.x; v[1] = o2.y; v[2] = o2.z; v[3] = o2.w; __builtin_nontemporal_store(v, (f32x4*)(hout + 512 + c0));
;     v[0] = o3.x; v[1] = o3.y; v[2] = o3.z; v[3] = o3.w; __builtin_nontemporal_store(v, (f32x4*)(hout + 512 + c0 + 4));
;   }
;   if (wr_u) {
;     uint4 ua, ub;
;     ua.x = umod(o0.x, o0.y, sc.a.x, sc.a.y, sh.a.x, sh.a.y); ua.y = umod(o0.z, o0.w, sc.a.z, sc.a.w, sh.a.z, sh.a.w);
;     ua.z = umod(o1.x, o1.y, sc.b.x, sc.b.y, sh.b.x, sh.b.y); ua.w = umod(o1.z, o1.w, sc.b.z, sc.b.w, sh.b.z, sh.b.w);
;     ub.x = umod(o2.x, o2.y, sc.c.x, sc.c.y, sh.c.x, sh.c.y); ub.y = umod(o2.z, o2.w, sc.c.z, sc.c.w, sh.c.z, sh.c.w);
;     ub.z = umod(o3.x, o3.y, sc.d.x, sc.d.y, sh.d.x, sh.d.y); ub.w = umod(o3.z, o3.w, sc.d.z, sc.d.w, sh.d.z, sh.d.w);
;     *(uint4*)(yu + c0) = ua;
;     *(uint4*)(yu + 512 + c0) = ub;
;   }
	v_add_f32_e32 v64, v64, v65
	v_mov_b32_e32 v65, v64
	s_nop 1
	v_permlane16_swap_b32_e32 v65, v64
	s_waitcnt lgkmcnt(0)
	v_add_f32_e32 v64, v64, v65
	s_nop 1
	v_mov_b32_dpp v65, v64 row_ror:8 row_mask:0xf bank_mask:0xf
	s_waitcnt lgkmcnt(0)
	v_add_f32_e32 v64, v64, v65
	s_nop 1
	v_mov_b32_dpp v65, v64 row_ror:4 row_mask:0xf bank_mask:0xf
	s_waitcnt lgkmcnt(0)
	v_add_f32_e32 v64, v64, v65
	s_nop 1
	v_mov_b32_dpp v65, v64 quad_perm:[2,3,0,1] row_mask:0xf bank_mask:0xf
	s_waitcnt lgkmcnt(0)
	v_add_f32_e32 v64, v64, v65
	s_nop 1
	v_mov_b32_dpp v65, v64 quad_perm:[1,0,3,2] row_mask:0xf bank_mask:0xf
	s_waitcnt lgkmcnt(0)
	v_add_f32_e32 v64, v64, v65
	v_fmamk_f32 v64, v64, 0x3a800000, v209
	v_cmp_gt_f32_e32 vcc, s96, v64
	v_mul_f32_e32 v65, 0x4b800000, v64
	s_nop 0
	v_cndmask_b32_e32 v64, v64, v65, vcc
	v_rsq_f32_e32 v64, v64
	s_nop 0
	v_mul_f32_e32 v65, 0x45800000, v64
	v_cndmask_b32_e32 v76, v64, v65, vcc
	v_pk_mul_f32 v[34:35], v[34:35], v[76:77] op_sel_hi:[1,0]
	s_waitcnt vmcnt(0)
	v_pk_fma_f32 v[64:65], v[48:49], v[34:35], v[52:53]
	v_pk_mul_f32 v[34:35], v[36:37], v[76:77] op_sel_hi:[1,0]
	v_add_co_u32_e32 v36, vcc, s91, v62
	v_pk_fma_f32 v[52:53], v[50:51], v[34:35], v[54:55]
	v_pk_mul_f32 v[34:35], v[38:39], v[76:77] op_sel_hi:[1,0]
	v_addc_co_u32_e32 v37, vcc, 0, v63, vcc
	v_pk_fma_f32 v[40:41], v[40:41], v[34:35], v[44:45]
	v_pk_mul_f32 v[34:35], v[74:75], v[76:77] op_sel_hi:[1,0]
	v_lshl_add_u64 v[50:51], v[130:131], 0, s[16:17]
	v_pk_fma_f32 v[38:39], v[42:43], v[34:35], v[46:47]
	v_pk_mul_f32 v[34:35], v[72:73], v[76:77] op_sel_hi:[1,0]
	v_cmp_eq_u32_e32 vcc, 0, v82
	v_pk_fma_f32 v[48:49], v[26:27], v[34:35], v[30:31]
	v_pk_mul_f32 v[26:27], v[70:71], v[76:77] op_sel_hi:[1,0]
	s_and_b64 vcc, exec, vcc
	v_pk_fma_f32 v[46:47], v[28:29], v[26:27], v[32:33]
	v_pk_mul_f32 v[26:27], v[68:69], v[76:77] op_sel_hi:[1,0]
	s_nop 0
	v_pk_fma_f32 v[44:45], v[18:19], v[26:27], v[22:23]
	v_pk_mul_f32 v[18:19], v[66:67], v[76:77] op_sel_hi:[1,0]
	global_load_dwordx4 v[32:35], v[36:37], off
	global_load_dwordx4 v[28:31], v[60:61], off offset:16
	s_nop 0
	global_load_dwordx4 v[60:63], v0, s[10:11] offset:16
	global_load_dwordx4 v[66:69], v0, s[10:11]
	v_pk_fma_f32 v[42:43], v[20:21], v[18:19], v[24:25]
	v_cvt_pk_f16_f32 v19, v52, v53
	v_cvt_pk_f16_f32 v20, v40, v41
	v_cvt_pk_f16_f32 v21, v38, v39
	v_cvt_pk_f16_f32 v18, v64, v65
	v_cvt_pk_f16_f32 v22, v48, v49
	v_cvt_pk_f16_f32 v23, v46, v47
	v_cvt_pk_f16_f32 v24, v44, v45
	v_cvt_pk_f16_f32 v25, v42, v43
	s_waitcnt vmcnt(3)
	v_pk_add_f32 v[26:27], v[32:33], 1.0 op_sel_hi:[1,0]
	v_pk_add_f32 v[32:33], v[34:35], 1.0 op_sel_hi:[1,0]
	s_waitcnt vmcnt(2)
	v_pk_add_f32 v[28:29], v[28:29], 1.0 op_sel_hi:[1,0]
	v_pk_add_f32 v[30:31], v[30:31], 1.0 op_sel_hi:[1,0]
	s_waitcnt vmcnt(0)
	v_pk_fma_f32 v[26:27], v[26:27], v[64:65], v[66:67]
	v_pk_fma_f32 v[32:33], v[32:33], v[52:53], v[68:69]
	v_pk_fma_f32 v[28:29], v[28:29], v[40:41], v[60:61]
	v_pk_fma_f32 v[30:31], v[30:31], v[38:39], v[62:63]
	v_cvt_pk_bf16_f32 v26, v26, v27
	v_cvt_pk_bf16_f32 v27, v32, v33
	v_cvt_pk_bf16_f32 v28, v28, v29
	v_cvt_pk_bf16_f32 v29, v30, v31
	global_load_dwordx4 v[38:41], v[36:37], off offset:2048
	global_load_dwordx4 v[30:33], v[58:59], off offset:16
	s_nop 0
	global_load_dwordx4 v[34:37], v0, s[10:11] offset:2064
	global_load_dwordx4 v[52:55], v0, s[10:11] offset:2048
	s_nop 0
	global_store_dwordx4 v[50:51], v[18:21], off nt
	global_store_dwordx4 v[50:51], v[22:25], off offset:1024 nt
	s_waitcnt vmcnt(5)
	v_pk_add_f32 v[38:39], v[38:39], 1.0 op_sel_hi:[1,0]
	v_pk_add_f32 v[40:41], v[40:41], 1.0 op_sel_hi:[1,0]
	s_waitcnt vmcnt(4)
	v_pk_add_f32 v[30:31], v[30:31], 1.0 op_sel_hi:[1,0]
	v_pk_add_f32 v[18:19], v[32:33], 1.0 op_sel_hi:[1,0]
	s_waitcnt vmcnt(2)
	v_pk_fma_f32 v[38:39], v[38:39], v[48:49], v[52:53]
	v_pk_fma_f32 v[40:41], v[40:41], v[46:47], v[54:55]
	v_pk_fma_f32 v[30:31], v[30:31], v[44:45], v[34:35]
	v_pk_fma_f32 v[18:19], v[18:19], v[42:43], v[36:37]
	v_cvt_pk_bf16_f32 v38, v38, v39
	v_cvt_pk_bf16_f32 v39, v40, v41
	v_cvt_pk_bf16_f32 v40, v30, v31
	v_cvt_pk_bf16_f32 v41, v18, v19
	global_store_dwordx4 v[56:57], v[26:29], off
	global_store_dwordx4 v[56:57], v[38:41], off offset:1024
	s_cbranch_vccnz .LBB0_185
